# EpiRes GEMMs: tile-header vmcnt(0) removed; peeled phase-1 LDS reads hoisted to the top of the tile header in all 8 GEMM loops (on v43)
# speedup vs baseline: 1.0042x; 1.0042x over previous
; #define PG8_STAGE(bufoff, gbase, voff) do { _Pragma("unroll") for (int _i = 0; _i < 2; ++_i) \
;         __builtin_amdgcn_global_load_lds((const unsigned*)((const char*)(gbase) + (voff)[_i]), (LAS unsigned*)(lds + (bufoff) + ldsw + _i * 8192), 16, 0, 0); } while (0)
; #define PG8_LDA(dst, b, h) do { _Pragma("unroll") for (int m = 0; m < 4; ++m) _Pragma("unroll") for (int k = 0; k < 2; ++k) dst[m][k] = *(const LAS bf16x8*)(lds + PG8_SA(b, h) + aoff + m * 2048 + k * 1024); } while (0)
; #define PG8_WAIT_V(n) asm volatile("s_waitcnt vmcnt(" #n ")" ::: "memory")
; #define PG8_BAR __builtin_amdgcn_s_barrier()
;     __device__ bool next(int i, Unit& u) const {
;         const long L = (long)i * G + c; if (L >= nwg) return false;
;         int wgid = (int)L; { const int q = nwg / NXCD, r = nwg % NXCD, xcd = wgid % NXCD, off = wgid / NXCD; wgid = (xcd < r ? xcd * (q + 1) : r * (q + 1) + (xcd - r) * q) + off; }
;         const int nig = WGM * nN, gid = wgid / nig, fm = gid * WGM, gsz = (nM - fm) < WGM ? (nM - fm) : WGM;
;         u.pm = fm + ((wgid % nig) % gsz); u.pn = (wgid % nig) / gsz; return true;
;     }
; template <class Epi, bool ALIGN_EPI, int K, int LDA, int LDB>
; __device__ __forceinline__ void gemm_phase(LAS unsigned char* lds, const int wid, const Gemm g, const StaticOrder& S, const Epi& E) {
;     ...
;         const bool has_next = S.next(ui + 1, nxt);
;         const char* nA = has_next ? (const char*)g.A + (size_t)nxt.pm * tA : cA; const char* nB = has_next ? (const char*)g.Bt + (size_t)nxt.pn * tB : cB;
;         for (int t = 0; t < nt; t += 2) {
;             const bool last = (t == nt - 2);
;             const char* a1 = cA + (size_t)(t + 1) * kstep;
;             const char* a2 = last ? nA : cA + (size_t)(t + 2) * kstep; const char* b2 = last ? nB : cB + (size_t)(t + 2) * kstep;
;             const char* a3 = a2 + kstep; const char* b3 = b2 + kstep;
;             PG8_LDB(B0, 0, 0); PG8_LDB(B1, 0, 1); PG8_SCHED; PG8_LDA(At, 0, 0); PG8_STAGE(PG8_SA(1, 1), a1 + hA, voffA);
;             PG8_WAIT_V(8); PG8_WAIT_L(0); PG8_BAR; PG8_MMA(0, 0, At, B0); PG8_MMA(0, 1, At, B1); PG8_BAR; PG8_SCHED;
;             PG8_LDA(At, 0, 1); PG8_STAGE(PG8_SB(0, 0), b2, voffB); PG8_STAGE(PG8_SB(0, 1), b2 + hB, voffB); PG8_STAGE(PG8_SA(0, 0), a2, voffA);
;             PG8_WAIT_V(8); PG8_WAIT_L(0); PG8_BAR; PG8_MMA(1, 0, At, B0); PG8_MMA(1, 1, At, B1); PG8_BAR; PG8_SCHED;
.LBB0_229:
	ds_read_b128 v[148:151], v145
	ds_read_b128 v[152:155], v145 offset:1024
	ds_read_b128 v[156:159], v145 offset:2048
	ds_read_b128 v[160:163], v145 offset:3072
	ds_read_b128 v[164:167], v146
	ds_read_b128 v[168:171], v146 offset:1024
	ds_read_b128 v[172:175], v146 offset:2048
	ds_read_b128 v[176:179], v146 offset:3072
	ds_read_b128 v[180:183], v147
	ds_read_b128 v[184:187], v147 offset:1024
	ds_read_b128 v[188:191], v147 offset:2048
	ds_read_b128 v[192:195], v147 offset:3072
	ds_read_b128 v[196:199], v147 offset:4096
	ds_read_b128 v[200:203], v147 offset:5120
	ds_read_b128 v[204:207], v147 offset:6144
	ds_read_b128 v[208:211], v147 offset:7168
	s_add_i32 s34, s34, 1
	s_mul_i32 s4, s34, s37
	s_mul_hi_u32 s5, s34, s90
	s_add_i32 s5, s5, s4
	s_mul_i32 s4, s34, s90
	s_add_u32 s18, s4, s2
	s_addc_u32 s19, s5, s28
	v_cmp_gt_i64_e32 vcc, s[18:19], v[142:143]
	v_cmp_lt_i64_e64 s[4:5], s[18:19], v[140:141]
	s_cbranch_vccnz .LBB0_231
	s_ashr_i32 s14, s18, 31
	s_lshr_b32 s14, s14, 29
	s_add_i32 s14, s18, s14
	s_ashr_i32 s15, s14, 3
	s_and_b32 s14, s14, -8
	s_sub_i32 s14, s18, s14
	s_cmp_lt_i32 s14, 0
	s_cselect_b32 s16, s29, 0x140
	s_mul_i32 s14, s14, s16
	s_add_i32 s14, s14, s15
	s_mul_hi_i32 s15, s14, 0x66666667
	s_lshr_b32 s16, s15, 31
	s_ashr_i32 s15, s15, 5
	s_add_i32 s15, s15, s16
	s_lshl_b32 s16, s15, 3
	s_mulk_i32 s15, 0x50
	s_sub_i32 s15, s14, s15
	s_lshr_b32 s14, s15, 3
	s_and_b32 s15, s15, 7
	s_add_i32 s16, s16, s15
.LBB0_231:
	s_ashr_i32 s17, s16, 31
	s_lshl_b64 s[18:19], s[16:17], 19
	v_readlane_b32 s15, v254, 0
	s_add_u32 s18, s15, s18
	v_readlane_b32 s15, v254, 1
	s_addc_u32 s19, s15, s19
	s_and_b64 s[20:21], s[4:5], exec
	s_cselect_b32 s17, s19, s23
	s_cselect_b32 s48, s18, s22
	s_ashr_i32 s15, s14, 31
	s_lshl_b64 s[20:21], s[14:15], 19
	s_add_u32 s20, s0, s20
	s_addc_u32 s21, s1, s21
	s_and_b64 s[26:27], s[4:5], exec
	s_cselect_b32 s15, s21, s25
	s_cselect_b32 s49, s20, s24
	s_add_u32 s22, s22, 0x40080
	s_addc_u32 s23, s23, 0
	s_add_u32 s51, s24, 0x100
	s_addc_u32 s54, s25, 0
	s_mov_b32 s55, -2
	s_add_u32 s24, s22, 0xfffc0080
	s_addc_u32 s25, s23, -1
	s_cmp_eq_u32 s55, 12
	s_cselect_b32 s27, s17, s25
	s_cselect_b32 s26, s48, s24
	s_cselect_b32 s25, s15, s54
	s_cselect_b32 s24, s49, s51
	s_add_i32 m0, s13, 0xc000
	global_load_lds_dwordx4 v136, s[22:23]
	s_add_i32 m0, s13, 0xe000
	s_nop 0
	global_load_lds_dwordx4 v138, s[22:23]
	s_waitcnt vmcnt(8)
	s_waitcnt lgkmcnt(0)
	s_barrier
	s_setprio 1
	s_waitcnt lgkmcnt(0)
	v_mfma_f32_16x16x32_bf16 v[124:127], v[148:151], v[180:183], 0
	v_mfma_f32_16x16x32_bf16 v[120:123], v[156:159], v[180:183], 0
	v_mfma_f32_16x16x32_bf16 v[116:119], v[148:151], v[188:191], 0
	v_mfma_f32_16x16x32_bf16 v[112:115], v[156:159], v[188:191], 0
	v_mfma_f32_16x16x32_bf16 v[100:103], v[148:151], v[196:199], 0
	v_mfma_f32_16x16x32_bf16 v[96:99], v[156:159], v[196:199], 0
	v_mfma_f32_16x16x32_bf16 v[84:87], v[148:151], v[204:207], 0
	v_mfma_f32_16x16x32_bf16 v[80:83], v[156:159], v[204:207], 0
	v_mfma_f32_16x16x32_bf16 v[124:127], v[152:155], v[184:187], v[124:127]
	v_mfma_f32_16x16x32_bf16 v[120:123], v[160:163], v[184:187], v[120:123]
	v_mfma_f32_16x16x32_bf16 v[116:119], v[152:155], v[192:195], v[116:119]
	v_mfma_f32_16x16x32_bf16 v[112:115], v[160:163], v[192:195], v[112:115]
	v_mfma_f32_16x16x32_bf16 v[100:103], v[152:155], v[200:203], v[100:103]
	v_mfma_f32_16x16x32_bf16 v[96:99], v[160:163], v[200:203], v[96:99]
	v_mfma_f32_16x16x32_bf16 v[84:87], v[152:155], v[208:211], v[84:87]
	v_mfma_f32_16x16x32_bf16 v[80:83], v[160:163], v[208:211], v[80:83]
	v_mfma_f32_16x16x32_bf16 v[108:111], v[164:167], v[180:183], 0
	v_mfma_f32_16x16x32_bf16 v[104:107], v[172:175], v[180:183], 0
	v_mfma_f32_16x16x32_bf16 v[92:95], v[164:167], v[188:191], 0
	v_mfma_f32_16x16x32_bf16 v[88:91], v[172:175], v[188:191], 0
	v_mfma_f32_16x16x32_bf16 v[76:79], v[164:167], v[196:199], 0
	v_mfma_f32_16x16x32_bf16 v[72:75], v[172:175], v[196:199], 0
	v_mfma_f32_16x16x32_bf16 v[68:71], v[164:167], v[204:207], 0
	v_mfma_f32_16x16x32_bf16 v[64:67], v[172:175], v[204:207], 0
	v_mfma_f32_16x16x32_bf16 v[108:111], v[168:171], v[184:187], v[108:111]
	v_mfma_f32_16x16x32_bf16 v[104:107], v[176:179], v[184:187], v[104:107]
	v_mfma_f32_16x16x32_bf16 v[92:95], v[168:171], v[192:195], v[92:95]
	v_mfma_f32_16x16x32_bf16 v[88:91], v[176:179], v[192:195], v[88:91]
	v_mfma_f32_16x16x32_bf16 v[76:79], v[168:171], v[200:203], v[76:79]
	v_mfma_f32_16x16x32_bf16 v[72:75], v[176:179], v[200:203], v[72:75]
	v_mfma_f32_16x16x32_bf16 v[68:71], v[168:171], v[208:211], v[68:71]
	v_mfma_f32_16x16x32_bf16 v[64:67], v[176:179], v[208:211], v[64:67]
	s_setprio 0
	s_barrier
	s_add_u32 s98, s24, s10
	s_addc_u32 s99, s25, s11
	s_add_u32 s100, s26, s10
	s_addc_u32 s101, s27, s11
	s_add_i32 s56, s40, s3
	s_mov_b32 m0, s56
	ds_read_b128 v[180:183], v147 offset:16384
	ds_read_b128 v[184:187], v147 offset:17408
	ds_read_b128 v[188:191], v147 offset:18432
	ds_read_b128 v[192:195], v147 offset:19456
	ds_read_b128 v[196:199], v147 offset:20480
	ds_read_b128 v[200:203], v147 offset:21504
	ds_read_b128 v[204:207], v147 offset:22528
	ds_read_b128 v[208:211], v147 offset:23552
	global_load_lds_dwordx4 v132, s[24:25]
	s_add_i32 m0, s56, 0x2000
	s_add_u32 s56, s24, 0x40000
	s_addc_u32 s57, s25, 0
	s_add_i32 s58, s41, s3
	global_load_lds_dwordx4 v128, s[24:25]
	s_mov_b32 m0, s58
	s_nop 0
	global_load_lds_dwordx4 v132, s[56:57]
	s_add_i32 m0, s58, 0x2000
	s_nop 0
	global_load_lds_dwordx4 v128, s[56:57]
	s_mov_b32 m0, s13
	s_nop 0
	global_load_lds_dwordx4 v134, s[26:27]
	s_mov_b32 m0, s30
	s_nop 0
	global_load_lds_dwordx4 v130, s[26:27]
	s_waitcnt vmcnt(8)
	s_waitcnt lgkmcnt(0)
	s_barrier
; #define PG8_STAGE(bufoff, gbase, voff) do { _Pragma("unroll") for (int _i = 0; _i < 2; ++_i) \
;         __builtin_amdgcn_global_load_lds((const unsigned*)((const char*)(gbase) + (voff)[_i]), (LAS unsigned*)(lds + (bufoff) + ldsw + _i * 8192), 16, 0, 0); } while (0)
; #define PG8_LDA(dst, b, h) do { _Pragma("unroll") for (int m = 0; m < 4; ++m) _Pragma("unroll") for (int k = 0; k < 2; ++k) dst[m][k] = *(const LAS bf16x8*)(lds + PG8_SA(b, h) + aoff + m * 2048 + k * 1024); } while (0)
; #define PG8_LDB(dst, b, h) do { _Pragma("unroll") for (int n = 0; n < 2; ++n) _Pragma("unroll") for (int k = 0; k < 2; ++k) dst[n][k] = *(const LAS bf16x8*)(lds + PG8_SB(b, h) + boff + n * 2048 + k * 1024); } while (0)
; #define PG8_MMA(ai, bj, At, Bt) do { __builtin_amdgcn_s_setprio(1); _Pragma("unroll") for (int m = 0; m < 4; ++m) _Pragma("unroll") for (int n = 0; n < 2; ++n) _Pragma("unroll") for (int k = 0; k < 2; ++k) \
;         acc[ai][bj][m][n] = __builtin_amdgcn_mfma_f32_16x16x32_bf16(Bt[n][k], At[m][k], acc[ai][bj][m][n], 0, 0, 0); __builtin_amdgcn_s_setprio(0); } while (0)
; #define PG8_WAIT_V(n) asm volatile("s_waitcnt vmcnt(" #n ")" ::: "memory")
; #define PG8_WAIT_L(n) asm volatile("s_waitcnt lgkmcnt(" #n ")" ::: "memory")
; #define PG8_BAR __builtin_amdgcn_s_barrier()
; #define PG8_SCHED __builtin_amdgcn_sched_barrier(0)
; template <class Epi, bool ALIGN_EPI, int K, int LDA, int LDB>
; __device__ __forceinline__ void gemm_phase(LAS unsigned char* lds, const int wid, const Gemm g, const StaticOrder& S, const Epi& E) {
;     ...
;             PG8_WAIT_V(8); PG8_WAIT_L(0); PG8_BAR; PG8_MMA(1, 0, At, B0); PG8_MMA(1, 1, At, B1); PG8_BAR; PG8_SCHED;
;             PG8_LDB(B0, 1, 0); PG8_LDB(B1, 1, 1); PG8_SCHED; PG8_LDA(At, 1, 0); PG8_STAGE(PG8_SA(0, 1), a2 + hA, voffA);
;             PG8_WAIT_V(8); PG8_WAIT_L(0); PG8_BAR; PG8_MMA(0, 0, At, B0); PG8_MMA(0, 1, At, B1); PG8_BAR; PG8_SCHED;
	s_setprio 1
	s_waitcnt lgkmcnt(0)
	v_mfma_f32_16x16x32_bf16 v[60:63], v[148:151], v[180:183], 0
	v_mfma_f32_16x16x32_bf16 v[56:59], v[156:159], v[180:183], 0
	v_mfma_f32_16x16x32_bf16 v[52:55], v[148:151], v[188:191], 0
	v_mfma_f32_16x16x32_bf16 v[48:51], v[156:159], v[188:191], 0
	v_mfma_f32_16x16x32_bf16 v[36:39], v[148:151], v[196:199], 0
	v_mfma_f32_16x16x32_bf16 v[32:35], v[156:159], v[196:199], 0
	v_mfma_f32_16x16x32_bf16 v[20:23], v[148:151], v[204:207], 0
	v_mfma_f32_16x16x32_bf16 v[16:19], v[156:159], v[204:207], 0
	v_mfma_f32_16x16x32_bf16 v[60:63], v[152:155], v[184:187], v[60:63]
	v_mfma_f32_16x16x32_bf16 v[56:59], v[160:163], v[184:187], v[56:59]
	v_mfma_f32_16x16x32_bf16 v[52:55], v[152:155], v[192:195], v[52:55]
	v_mfma_f32_16x16x32_bf16 v[48:51], v[160:163], v[192:195], v[48:51]
	v_mfma_f32_16x16x32_bf16 v[36:39], v[152:155], v[200:203], v[36:39]
	v_mfma_f32_16x16x32_bf16 v[32:35], v[160:163], v[200:203], v[32:35]
	v_mfma_f32_16x16x32_bf16 v[20:23], v[152:155], v[208:211], v[20:23]
	v_mfma_f32_16x16x32_bf16 v[16:19], v[160:163], v[208:211], v[16:19]
	v_mfma_f32_16x16x32_bf16 v[44:47], v[164:167], v[180:183], 0
	v_mfma_f32_16x16x32_bf16 v[40:43], v[172:175], v[180:183], 0
	v_mfma_f32_16x16x32_bf16 v[28:31], v[164:167], v[188:191], 0
	v_mfma_f32_16x16x32_bf16 v[24:27], v[172:175], v[188:191], 0
	v_mfma_f32_16x16x32_bf16 v[12:15], v[164:167], v[196:199], 0
	v_mfma_f32_16x16x32_bf16 v[8:11], v[172:175], v[196:199], 0
	v_mfma_f32_16x16x32_bf16 v[4:7], v[164:167], v[204:207], 0
	v_mfma_f32_16x16x32_bf16 v[0:3], v[172:175], v[204:207], 0
	v_mfma_f32_16x16x32_bf16 v[44:47], v[168:171], v[184:187], v[44:47]
	v_mfma_f32_16x16x32_bf16 v[40:43], v[176:179], v[184:187], v[40:43]
	v_mfma_f32_16x16x32_bf16 v[28:31], v[168:171], v[192:195], v[28:31]
	v_mfma_f32_16x16x32_bf16 v[24:27], v[176:179], v[192:195], v[24:27]
	v_mfma_f32_16x16x32_bf16 v[12:15], v[168:171], v[200:203], v[12:15]
	v_mfma_f32_16x16x32_bf16 v[8:11], v[176:179], v[200:203], v[8:11]
	v_mfma_f32_16x16x32_bf16 v[4:7], v[168:171], v[208:211], v[4:7]
	v_mfma_f32_16x16x32_bf16 v[0:3], v[176:179], v[208:211], v[0:3]
	s_setprio 0
	s_barrier
	s_add_i32 s56, 0, 0x18000
	s_add_i32 s57, 0, 0x1c000
	v_add_u32_e32 v160, s56, v144
	v_add_u32_e32 v176, s57, v144
	ds_read_b128 v[148:151], v160
	ds_read_b128 v[152:155], v160 offset:1024
	ds_read_b128 v[156:159], v160 offset:2048
	ds_read_b128 v[160:163], v160 offset:3072
	ds_read_b128 v[164:167], v176
	ds_read_b128 v[168:171], v176 offset:1024
	ds_read_b128 v[172:175], v176 offset:2048
	ds_read_b128 v[176:179], v176 offset:3072
	s_add_u32 s26, s26, 0x40000
	s_addc_u32 s27, s27, 0
	s_mov_b32 m0, s31
	ds_read_b128 v[180:183], v147 offset:32768
	ds_read_b128 v[184:187], v147 offset:33792
	ds_read_b128 v[188:191], v147 offset:34816
	ds_read_b128 v[192:195], v147 offset:35840
	ds_read_b128 v[196:199], v147 offset:36864
	ds_read_b128 v[200:203], v147 offset:37888
	ds_read_b128 v[204:207], v147 offset:38912
	ds_read_b128 v[208:211], v147 offset:39936
	global_load_lds_dwordx4 v134, s[26:27]
	s_mov_b32 m0, s33
	s_nop 0
	global_load_lds_dwordx4 v130, s[26:27]
	s_waitcnt vmcnt(8)
	s_waitcnt lgkmcnt(0)
	s_barrier
	s_setprio 1
	s_waitcnt lgkmcnt(0)
	v_mfma_f32_16x16x32_bf16 v[124:127], v[148:151], v[180:183], v[124:127]
	v_mfma_f32_16x16x32_bf16 v[120:123], v[156:159], v[180:183], v[120:123]
	v_mfma_f32_16x16x32_bf16 v[116:119], v[148:151], v[188:191], v[116:119]
	v_mfma_f32_16x16x32_bf16 v[112:115], v[156:159], v[188:191], v[112:115]
	v_mfma_f32_16x16x32_bf16 v[100:103], v[148:151], v[196:199], v[100:103]
	v_mfma_f32_16x16x32_bf16 v[96:99], v[156:159], v[196:199], v[96:99]
	v_mfma_f32_16x16x32_bf16 v[84:87], v[148:151], v[204:207], v[84:87]
	v_mfma_f32_16x16x32_bf16 v[80:83], v[156:159], v[204:207], v[80:83]
	v_mfma_f32_16x16x32_bf16 v[124:127], v[152:155], v[184:187], v[124:127]
	v_mfma_f32_16x16x32_bf16 v[120:123], v[160:163], v[184:187], v[120:123]
	v_mfma_f32_16x16x32_bf16 v[116:119], v[152:155], v[192:195], v[116:119]
	v_mfma_f32_16x16x32_bf16 v[112:115], v[160:163], v[192:195], v[112:115]
	v_mfma_f32_16x16x32_bf16 v[100:103], v[152:155], v[200:203], v[100:103]
	v_mfma_f32_16x16x32_bf16 v[96:99], v[160:163], v[200:203], v[96:99]
	v_mfma_f32_16x16x32_bf16 v[84:87], v[152:155], v[208:211], v[84:87]
	v_mfma_f32_16x16x32_bf16 v[80:83], v[160:163], v[208:211], v[80:83]
	v_mfma_f32_16x16x32_bf16 v[108:111], v[164:167], v[180:183], v[108:111]
	v_mfma_f32_16x16x32_bf16 v[104:107], v[172:175], v[180:183], v[104:107]
	v_mfma_f32_16x16x32_bf16 v[92:95], v[164:167], v[188:191], v[92:95]
	v_mfma_f32_16x16x32_bf16 v[88:91], v[172:175], v[188:191], v[88:91]
	v_mfma_f32_16x16x32_bf16 v[76:79], v[164:167], v[196:199], v[76:79]
	v_mfma_f32_16x16x32_bf16 v[72:75], v[172:175], v[196:199], v[72:75]
	v_mfma_f32_16x16x32_bf16 v[68:71], v[164:167], v[204:207], v[68:71]
	v_mfma_f32_16x16x32_bf16 v[64:67], v[172:175], v[204:207], v[64:67]
	v_mfma_f32_16x16x32_bf16 v[108:111], v[168:171], v[184:187], v[108:111]
	v_mfma_f32_16x16x32_bf16 v[104:107], v[176:179], v[184:187], v[104:107]
	v_mfma_f32_16x16x32_bf16 v[92:95], v[168:171], v[192:195], v[92:95]
	v_mfma_f32_16x16x32_bf16 v[88:91], v[176:179], v[192:195], v[88:91]
	v_mfma_f32_16x16x32_bf16 v[76:79], v[168:171], v[200:203], v[76:79]
	v_mfma_f32_16x16x32_bf16 v[72:75], v[176:179], v[200:203], v[72:75]
	v_mfma_f32_16x16x32_bf16 v[68:71], v[168:171], v[208:211], v[68:71]
	v_mfma_f32_16x16x32_bf16 v[64:67], v[176:179], v[208:211], v[64:67]
	s_setprio 0
	s_barrier
; #define PG8_STAGE(bufoff, gbase, voff) do { _Pragma("unroll") for (int _i = 0; _i < 2; ++_i) \
;         __builtin_amdgcn_global_load_lds((const unsigned*)((const char*)(gbase) + (voff)[_i]), (LAS unsigned*)(lds + (bufoff) + ldsw + _i * 8192), 16, 0, 0); } while (0)
; #define PG8_LDA(dst, b, h) do { _Pragma("unroll") for (int m = 0; m < 4; ++m) _Pragma("unroll") for (int k = 0; k < 2; ++k) dst[m][k] = *(const LAS bf16x8*)(lds + PG8_SA(b, h) + aoff + m * 2048 + k * 1024); } while (0)
; #define PG8_MMA(ai, bj, At, Bt) do { __builtin_amdgcn_s_setprio(1); _Pragma("unroll") for (int m = 0; m < 4; ++m) _Pragma("unroll") for (int n = 0; n < 2; ++n) _Pragma("unroll") for (int k = 0; k < 2; ++k) \
;         acc[ai][bj][m][n] = __builtin_amdgcn_mfma_f32_16x16x32_bf16(Bt[n][k], At[m][k], acc[ai][bj][m][n], 0, 0, 0); __builtin_amdgcn_s_setprio(0); } while (0)
; #define PG8_WAIT_V(n) asm volatile("s_waitcnt vmcnt(" #n ")" ::: "memory")
; #define PG8_WAIT_L(n) asm volatile("s_waitcnt lgkmcnt(" #n ")" ::: "memory")
; #define PG8_BAR __builtin_amdgcn_s_barrier()
; #define PG8_SCHED __builtin_amdgcn_sched_barrier(0)
; template <class Epi, bool ALIGN_EPI, int K, int LDA, int LDB>
; __device__ __forceinline__ void gemm_phase(LAS unsigned char* lds, const int wid, const Gemm g, const StaticOrder& S, const Epi& E) {
;     ...
;             PG8_LDA(At, 1, 1); PG8_STAGE(PG8_SB(1, 0), b3, voffB); PG8_STAGE(PG8_SB(1, 1), b3 + hB, voffB); PG8_STAGE(PG8_SA(1, 0), a3, voffA);
;             PG8_WAIT_V(8); PG8_WAIT_L(0); PG8_BAR; PG8_MMA(1, 0, At, B0); PG8_MMA(1, 1, At, B1); PG8_BAR; PG8_SCHED;
;         }
	s_add_i32 s26, s56, s3
	s_mov_b32 m0, s26
	ds_read_b128 v[180:183], v147 offset:49152
	ds_read_b128 v[184:187], v147 offset:50176
	ds_read_b128 v[188:191], v147 offset:51200
	ds_read_b128 v[192:195], v147 offset:52224
	ds_read_b128 v[196:199], v147 offset:53248
	ds_read_b128 v[200:203], v147 offset:54272
	ds_read_b128 v[204:207], v147 offset:55296
	ds_read_b128 v[208:211], v147 offset:56320
	global_load_lds_dwordx4 v132, s[98:99]
	s_add_i32 m0, s26, 0x2000
	s_add_u32 s24, s24, 0x40080
	s_addc_u32 s25, s25, 0
	s_add_i32 s26, s57, s3
	global_load_lds_dwordx4 v128, s[98:99]
	s_mov_b32 m0, s26
	s_nop 0
	global_load_lds_dwordx4 v132, s[24:25]
	s_add_i32 m0, s26, 0x2000
	s_nop 0
	global_load_lds_dwordx4 v128, s[24:25]
	s_mov_b32 m0, s38
	s_nop 0
	global_load_lds_dwordx4 v134, s[100:101]
	s_mov_b32 m0, s39
	s_nop 0
	global_load_lds_dwordx4 v130, s[100:101]
	s_waitcnt vmcnt(8)
	s_waitcnt lgkmcnt(0)
	s_barrier
	s_setprio 1
	s_waitcnt lgkmcnt(0)
	v_mfma_f32_16x16x32_bf16 v[60:63], v[148:151], v[180:183], v[60:63]
	v_mfma_f32_16x16x32_bf16 v[56:59], v[156:159], v[180:183], v[56:59]
	v_mfma_f32_16x16x32_bf16 v[52:55], v[148:151], v[188:191], v[52:55]
	v_mfma_f32_16x16x32_bf16 v[48:51], v[156:159], v[188:191], v[48:51]
	v_mfma_f32_16x16x32_bf16 v[36:39], v[148:151], v[196:199], v[36:39]
	v_mfma_f32_16x16x32_bf16 v[32:35], v[156:159], v[196:199], v[32:35]
	v_mfma_f32_16x16x32_bf16 v[20:23], v[148:151], v[204:207], v[20:23]
	v_mfma_f32_16x16x32_bf16 v[16:19], v[156:159], v[204:207], v[16:19]
	v_mfma_f32_16x16x32_bf16 v[60:63], v[152:155], v[184:187], v[60:63]
	v_mfma_f32_16x16x32_bf16 v[56:59], v[160:163], v[184:187], v[56:59]
	v_mfma_f32_16x16x32_bf16 v[52:55], v[152:155], v[192:195], v[52:55]
	v_mfma_f32_16x16x32_bf16 v[48:51], v[160:163], v[192:195], v[48:51]
	v_mfma_f32_16x16x32_bf16 v[36:39], v[152:155], v[200:203], v[36:39]
	v_mfma_f32_16x16x32_bf16 v[32:35], v[160:163], v[200:203], v[32:35]
	v_mfma_f32_16x16x32_bf16 v[20:23], v[152:155], v[208:211], v[20:23]
	v_mfma_f32_16x16x32_bf16 v[16:19], v[160:163], v[208:211], v[16:19]
	v_mfma_f32_16x16x32_bf16 v[44:47], v[164:167], v[180:183], v[44:47]
	v_mfma_f32_16x16x32_bf16 v[40:43], v[172:175], v[180:183], v[40:43]
	v_mfma_f32_16x16x32_bf16 v[28:31], v[164:167], v[188:191], v[28:31]
	v_mfma_f32_16x16x32_bf16 v[24:27], v[172:175], v[188:191], v[24:27]
	v_mfma_f32_16x16x32_bf16 v[12:15], v[164:167], v[196:199], v[12:15]
	v_mfma_f32_16x16x32_bf16 v[8:11], v[172:175], v[196:199], v[8:11]
	v_mfma_f32_16x16x32_bf16 v[4:7], v[164:167], v[204:207], v[4:7]
	v_mfma_f32_16x16x32_bf16 v[0:3], v[172:175], v[204:207], v[0:3]
	v_mfma_f32_16x16x32_bf16 v[44:47], v[168:171], v[184:187], v[44:47]
	v_mfma_f32_16x16x32_bf16 v[40:43], v[176:179], v[184:187], v[40:43]
	v_mfma_f32_16x16x32_bf16 v[28:31], v[168:171], v[192:195], v[28:31]
	v_mfma_f32_16x16x32_bf16 v[24:27], v[176:179], v[192:195], v[24:27]
	v_mfma_f32_16x16x32_bf16 v[12:15], v[168:171], v[200:203], v[12:15]
	v_mfma_f32_16x16x32_bf16 v[8:11], v[176:179], v[200:203], v[8:11]
	v_mfma_f32_16x16x32_bf16 v[4:7], v[168:171], v[208:211], v[4:7]
	v_mfma_f32_16x16x32_bf16 v[0:3], v[176:179], v[208:211], v[0:3]
	s_setprio 0
	s_barrier
	s_add_i32 s55, s55, 2
	s_add_u32 s22, s22, 0x100
	s_addc_u32 s23, s23, 0
	s_add_u32 s51, s51, 0x100
	s_addc_u32 s54, s54, 0

; #define PG8_STAGE(bufoff, gbase, voff) do { _Pragma("unroll") for (int _i = 0; _i < 2; ++_i) \
;         __builtin_amdgcn_global_load_lds((const unsigned*)((const char*)(gbase) + (voff)[_i]), (LAS unsigned*)(lds + (bufoff) + ldsw + _i * 8192), 16, 0, 0); } while (0)
; #define PG8_LDA(dst, b, h) do { _Pragma("unroll") for (int m = 0; m < 4; ++m) _Pragma("unroll") for (int k = 0; k < 2; ++k) dst[m][k] = *(const LAS bf16x8*)(lds + PG8_SA(b, h) + aoff + m * 2048 + k * 1024); } while (0)
; #define PG8_LDB(dst, b, h) do { _Pragma("unroll") for (int n = 0; n < 2; ++n) _Pragma("unroll") for (int k = 0; k < 2; ++k) dst[n][k] = *(const LAS bf16x8*)(lds + PG8_SB(b, h) + boff + n * 2048 + k * 1024); } while (0)
; #define PG8_SCHED __builtin_amdgcn_sched_barrier(0)
;     __device__ bool next(int i, Unit& u) const {
;         const long L = (long)i * G + c; if (L >= nwg) return false;
;         int wgid = (int)L; { const int q = nwg / NXCD, r = nwg % NXCD, xcd = wgid % NXCD, off = wgid / NXCD; wgid = (xcd < r ? xcd * (q + 1) : r * (q + 1) + (xcd - r) * q) + off; }
;         const int nig = WGM * nN, gid = wgid / nig, fm = gid * WGM, gsz = (nM - fm) < WGM ? (nM - fm) : WGM;
;         u.pm = fm + ((wgid % nig) % gsz); u.pn = (wgid % nig) / gsz; return true;
; template <class Epi, bool ALIGN_EPI, int K, int LDA, int LDB>
; __device__ __forceinline__ void gemm_phase(LAS unsigned char* lds, const int wid, const Gemm g, const StaticOrder& S, const Epi& E) {
;     ...
;             PG8_LDB(B0, 0, 0); PG8_LDB(B1, 0, 1); PG8_SCHED; PG8_LDA(At, 0, 0); PG8_STAGE(PG8_SA(1, 1), a1 + hA, voffA);
.LBB0_910:
	ds_read_b128 v[128:131], v163
	ds_read_b128 v[132:135], v163 offset:1024
	ds_read_b128 v[136:139], v163 offset:2048
	ds_read_b128 v[140:143], v163 offset:3072
	ds_read_b128 v[166:169], v164
	ds_read_b128 v[170:173], v164 offset:1024
	ds_read_b128 v[174:177], v164 offset:2048
	ds_read_b128 v[178:181], v164 offset:3072
	ds_read_b128 v[182:185], v165
	ds_read_b128 v[186:189], v165 offset:1024
	ds_read_b128 v[190:193], v165 offset:2048
	ds_read_b128 v[194:197], v165 offset:3072
	ds_read_b128 v[198:201], v165 offset:4096
	ds_read_b128 v[202:205], v165 offset:5120
	ds_read_b128 v[206:209], v165 offset:6144
	ds_read_b128 v[210:213], v165 offset:7168
	s_add_i32 s61, s61, 1
	s_mul_i32 s4, s61, s57
	s_mul_hi_u32 s5, s61, s90
	s_add_i32 s5, s5, s4
	s_mul_i32 s4, s61, s90
	s_add_u32 s28, s4, s2
	s_addc_u32 s29, s5, s0
	v_cmp_gt_i64_e32 vcc, s[28:29], v[158:159]
	v_cmp_lt_i64_e64 s[4:5], s[28:29], v[156:157]
	s_cbranch_vccnz .LBB0_916
	s_ashr_i32 s24, s28, 31
	s_lshr_b32 s24, s24, 29
	s_add_i32 s26, s28, s24
	s_and_b32 s24, s26, -8
	s_sub_i32 s27, s28, s24
	s_cmp_gt_i32 s27, -1
	s_mov_b64 s[24:25], -1
	s_cbranch_scc0 .LBB0_913
	s_lshl_b32 s28, s27, 7
	s_mov_b64 s[24:25], 0

; #define PG8_STAGE(bufoff, gbase, voff) do { _Pragma("unroll") for (int _i = 0; _i < 2; ++_i) \
;         __builtin_amdgcn_global_load_lds((const unsigned*)((const char*)(gbase) + (voff)[_i]), (LAS unsigned*)(lds + (bufoff) + ldsw + _i * 8192), 16, 0, 0); } while (0)
; #define PG8_LDA(dst, b, h) do { _Pragma("unroll") for (int m = 0; m < 4; ++m) _Pragma("unroll") for (int k = 0; k < 2; ++k) dst[m][k] = *(const LAS bf16x8*)(lds + PG8_SA(b, h) + aoff + m * 2048 + k * 1024); } while (0)
; #define PG8_LDB(dst, b, h) do { _Pragma("unroll") for (int n = 0; n < 2; ++n) _Pragma("unroll") for (int k = 0; k < 2; ++k) dst[n][k] = *(const LAS bf16x8*)(lds + PG8_SB(b, h) + boff + n * 2048 + k * 1024); } while (0)
; #define PG8_MMA(ai, bj, At, Bt) do { __builtin_amdgcn_s_setprio(1); _Pragma("unroll") for (int m = 0; m < 4; ++m) _Pragma("unroll") for (int n = 0; n < 2; ++n) _Pragma("unroll") for (int k = 0; k < 2; ++k) \
;         acc[ai][bj][m][n] = __builtin_amdgcn_mfma_f32_16x16x32_bf16(Bt[n][k], At[m][k], acc[ai][bj][m][n], 0, 0, 0); __builtin_amdgcn_s_setprio(0); } while (0)
; template <class Epi, bool ALIGN_EPI, int K, int LDA, int LDB>
; __device__ __forceinline__ void gemm_phase(LAS unsigned char* lds, const int wid, const Gemm g, const StaticOrder& S, const Epi& E) {
;     ...
;         const bool has_next = S.next(ui + 1, nxt);
;         const char* nA = has_next ? (const char*)g.A + (size_t)nxt.pm * tA : cA; const char* nB = has_next ? (const char*)g.Bt + (size_t)nxt.pn * tB : cB;
;         for (int t = 0; t < nt; t += 2) {
;             const bool last = (t == nt - 2);
;             const char* a1 = cA + (size_t)(t + 1) * kstep;
;             const char* a2 = last ? nA : cA + (size_t)(t + 2) * kstep; const char* b2 = last ? nB : cB + (size_t)(t + 2) * kstep;
;             const char* a3 = a2 + kstep; const char* b3 = b2 + kstep;
;             PG8_LDB(B0, 0, 0); PG8_LDB(B1, 0, 1); PG8_SCHED; PG8_LDA(At, 0, 0); PG8_STAGE(PG8_SA(1, 1), a1 + hA, voffA);
;             PG8_WAIT_V(8); PG8_WAIT_L(0); PG8_BAR; PG8_MMA(0, 0, At, B0); PG8_MMA(0, 1, At, B1); PG8_BAR; PG8_SCHED;
;             PG8_LDA(At, 0, 1); PG8_STAGE(PG8_SB(0, 0), b2, voffB); PG8_STAGE(PG8_SB(0, 1), b2 + hB, voffB); PG8_STAGE(PG8_SA(0, 0), a2, voffA);
;             PG8_WAIT_V(8); PG8_WAIT_L(0); PG8_BAR; PG8_MMA(1, 0, At, B0); PG8_MMA(1, 1, At, B1); PG8_BAR; PG8_SCHED;
.LBB0_916:
	s_ashr_i32 s27, s26, 31
	s_lshl_b64 s[28:29], s[26:27], 19
	v_readlane_b32 s25, v254, 0
	s_add_u32 s28, s25, s28
	v_readlane_b32 s25, v254, 1
	s_addc_u32 s29, s25, s29
	s_and_b64 s[30:31], s[4:5], exec
	s_cselect_b32 s27, s29, s37
	s_cselect_b32 s63, s28, s36
	s_ashr_i32 s25, s24, 31
	s_lshl_b64 s[30:31], s[24:25], 19
	s_add_u32 s30, s1, s30
	s_addc_u32 s31, s3, s31
	s_and_b64 s[40:41], s[4:5], exec
	s_cselect_b32 s25, s31, s39
	s_cselect_b32 s64, s30, s38
	s_add_u32 s36, s36, 0x40080
	s_addc_u32 s37, s37, 0
	s_add_u32 s65, s38, 0x100
	s_addc_u32 s66, s39, 0
	s_mov_b32 s67, -2
	s_add_u32 s38, s36, 0xfffc0080
	s_addc_u32 s39, s37, -1
	s_cmp_eq_u32 s67, 12
	s_cselect_b32 s41, s27, s39
	s_cselect_b32 s40, s63, s38
	s_cselect_b32 s39, s25, s66
	s_cselect_b32 s38, s64, s65
	s_add_i32 m0, s35, 0xc000
	global_load_lds_dwordx4 v152, s[36:37]
	s_add_i32 m0, s35, 0xe000
	s_nop 0
	global_load_lds_dwordx4 v154, s[36:37]
	s_waitcnt vmcnt(8)
	s_waitcnt lgkmcnt(0)
	s_barrier
	s_setprio 1
	s_waitcnt lgkmcnt(0)
	v_mfma_f32_16x16x32_bf16 v[124:127], v[128:131], v[182:185], 0
	v_mfma_f32_16x16x32_bf16 v[120:123], v[136:139], v[182:185], 0
	v_mfma_f32_16x16x32_bf16 v[108:111], v[128:131], v[190:193], 0
	v_mfma_f32_16x16x32_bf16 v[104:107], v[136:139], v[190:193], 0
	v_mfma_f32_16x16x32_bf16 v[92:95], v[128:131], v[198:201], 0
	v_mfma_f32_16x16x32_bf16 v[88:91], v[136:139], v[198:201], 0
	v_mfma_f32_16x16x32_bf16 v[76:79], v[128:131], v[206:209], 0
	v_mfma_f32_16x16x32_bf16 v[72:75], v[136:139], v[206:209], 0
	v_mfma_f32_16x16x32_bf16 v[124:127], v[132:135], v[186:189], v[124:127]
	v_mfma_f32_16x16x32_bf16 v[120:123], v[140:143], v[186:189], v[120:123]
	v_mfma_f32_16x16x32_bf16 v[108:111], v[132:135], v[194:197], v[108:111]
	v_mfma_f32_16x16x32_bf16 v[104:107], v[140:143], v[194:197], v[104:107]
	v_mfma_f32_16x16x32_bf16 v[92:95], v[132:135], v[202:205], v[92:95]
	v_mfma_f32_16x16x32_bf16 v[88:91], v[140:143], v[202:205], v[88:91]
	v_mfma_f32_16x16x32_bf16 v[76:79], v[132:135], v[210:213], v[76:79]
	v_mfma_f32_16x16x32_bf16 v[72:75], v[140:143], v[210:213], v[72:75]
	v_mfma_f32_16x16x32_bf16 v[116:119], v[166:169], v[182:185], 0
	v_mfma_f32_16x16x32_bf16 v[112:115], v[174:177], v[182:185], 0
	v_mfma_f32_16x16x32_bf16 v[100:103], v[166:169], v[190:193], 0
	v_mfma_f32_16x16x32_bf16 v[96:99], v[174:177], v[190:193], 0
	v_mfma_f32_16x16x32_bf16 v[84:87], v[166:169], v[198:201], 0
	v_mfma_f32_16x16x32_bf16 v[80:83], v[174:177], v[198:201], 0
	v_mfma_f32_16x16x32_bf16 v[68:71], v[166:169], v[206:209], 0
	v_mfma_f32_16x16x32_bf16 v[64:67], v[174:177], v[206:209], 0
	v_mfma_f32_16x16x32_bf16 v[116:119], v[170:173], v[186:189], v[116:119]
	v_mfma_f32_16x16x32_bf16 v[112:115], v[178:181], v[186:189], v[112:115]
	v_mfma_f32_16x16x32_bf16 v[100:103], v[170:173], v[194:197], v[100:103]
	v_mfma_f32_16x16x32_bf16 v[96:99], v[178:181], v[194:197], v[96:99]
	v_mfma_f32_16x16x32_bf16 v[84:87], v[170:173], v[202:205], v[84:87]
	v_mfma_f32_16x16x32_bf16 v[80:83], v[178:181], v[202:205], v[80:83]
	v_mfma_f32_16x16x32_bf16 v[68:71], v[170:173], v[210:213], v[68:71]
	v_mfma_f32_16x16x32_bf16 v[64:67], v[178:181], v[210:213], v[64:67]
	s_setprio 0
	s_barrier
	s_add_u32 s98, s38, s12
	s_addc_u32 s99, s39, s13
	s_add_u32 s100, s40, s12
	s_addc_u32 s101, s41, s13
	s_add_i32 s52, s58, s33
	s_mov_b32 m0, s52
	ds_read_b128 v[182:185], v165 offset:16384
	ds_read_b128 v[186:189], v165 offset:17408
	ds_read_b128 v[190:193], v165 offset:18432
	ds_read_b128 v[194:197], v165 offset:19456
	ds_read_b128 v[198:201], v165 offset:20480
	ds_read_b128 v[202:205], v165 offset:21504
	ds_read_b128 v[206:209], v165 offset:22528
	ds_read_b128 v[210:213], v165 offset:23552
	global_load_lds_dwordx4 v146, s[38:39]
	s_add_i32 m0, s52, 0x2000
	s_add_u32 s68, s38, 0x40000
	s_addc_u32 s69, s39, 0
	s_add_i32 s52, s59, s33
	global_load_lds_dwordx4 v150, s[38:39]
	s_mov_b32 m0, s52
	s_nop 0
	global_load_lds_dwordx4 v146, s[68:69]
	s_add_i32 m0, s52, 0x2000
	s_nop 0
	global_load_lds_dwordx4 v150, s[68:69]
	s_mov_b32 m0, s35
	s_nop 0
	global_load_lds_dwordx4 v144, s[40:41]
	s_mov_b32 m0, s42
	s_nop 0
	global_load_lds_dwordx4 v148, s[40:41]
	s_waitcnt vmcnt(8)
	s_waitcnt lgkmcnt(0)
	s_barrier
	s_setprio 1
	s_waitcnt lgkmcnt(0)
	v_mfma_f32_16x16x32_bf16 v[60:63], v[128:131], v[182:185], 0
	v_mfma_f32_16x16x32_bf16 v[56:59], v[136:139], v[182:185], 0
	v_mfma_f32_16x16x32_bf16 v[44:47], v[128:131], v[190:193], 0
	v_mfma_f32_16x16x32_bf16 v[40:43], v[136:139], v[190:193], 0
	v_mfma_f32_16x16x32_bf16 v[28:31], v[128:131], v[198:201], 0
	v_mfma_f32_16x16x32_bf16 v[24:27], v[136:139], v[198:201], 0
	v_mfma_f32_16x16x32_bf16 v[12:15], v[128:131], v[206:209], 0
	v_mfma_f32_16x16x32_bf16 v[8:11], v[136:139], v[206:209], 0
	v_mfma_f32_16x16x32_bf16 v[60:63], v[132:135], v[186:189], v[60:63]
	v_mfma_f32_16x16x32_bf16 v[56:59], v[140:143], v[186:189], v[56:59]
	v_mfma_f32_16x16x32_bf16 v[44:47], v[132:135], v[194:197], v[44:47]
	v_mfma_f32_16x16x32_bf16 v[40:43], v[140:143], v[194:197], v[40:43]
	v_mfma_f32_16x16x32_bf16 v[28:31], v[132:135], v[202:205], v[28:31]
	v_mfma_f32_16x16x32_bf16 v[24:27], v[140:143], v[202:205], v[24:27]
	v_mfma_f32_16x16x32_bf16 v[12:15], v[132:135], v[210:213], v[12:15]
	v_mfma_f32_16x16x32_bf16 v[8:11], v[140:143], v[210:213], v[8:11]
	v_mfma_f32_16x16x32_bf16 v[52:55], v[166:169], v[182:185], 0
	v_mfma_f32_16x16x32_bf16 v[48:51], v[174:177], v[182:185], 0
	v_mfma_f32_16x16x32_bf16 v[36:39], v[166:169], v[190:193], 0
	v_mfma_f32_16x16x32_bf16 v[32:35], v[174:177], v[190:193], 0
	v_mfma_f32_16x16x32_bf16 v[20:23], v[166:169], v[198:201], 0
	v_mfma_f32_16x16x32_bf16 v[16:19], v[174:177], v[198:201], 0
	v_mfma_f32_16x16x32_bf16 v[4:7], v[166:169], v[206:209], 0
	v_mfma_f32_16x16x32_bf16 v[0:3], v[174:177], v[206:209], 0
	v_mfma_f32_16x16x32_bf16 v[52:55], v[170:173], v[186:189], v[52:55]
	v_mfma_f32_16x16x32_bf16 v[48:51], v[178:181], v[186:189], v[48:51]
	v_mfma_f32_16x16x32_bf16 v[36:39], v[170:173], v[194:197], v[36:39]
	v_mfma_f32_16x16x32_bf16 v[32:35], v[178:181], v[194:197], v[32:35]
	v_mfma_f32_16x16x32_bf16 v[20:23], v[170:173], v[202:205], v[20:23]
	v_mfma_f32_16x16x32_bf16 v[16:19], v[178:181], v[202:205], v[16:19]
	v_mfma_f32_16x16x32_bf16 v[4:7], v[170:173], v[210:213], v[4:7]
	v_mfma_f32_16x16x32_bf16 v[0:3], v[178:181], v[210:213], v[0:3]
	s_setprio 0
	s_barrier
; #define PG8_STAGE(bufoff, gbase, voff) do { _Pragma("unroll") for (int _i = 0; _i < 2; ++_i) \
;         __builtin_amdgcn_global_load_lds((const unsigned*)((const char*)(gbase) + (voff)[_i]), (LAS unsigned*)(lds + (bufoff) + ldsw + _i * 8192), 16, 0, 0); } while (0)
; #define PG8_LDA(dst, b, h) do { _Pragma("unroll") for (int m = 0; m < 4; ++m) _Pragma("unroll") for (int k = 0; k < 2; ++k) dst[m][k] = *(const LAS bf16x8*)(lds + PG8_SA(b, h) + aoff + m * 2048 + k * 1024); } while (0)
; #define PG8_LDB(dst, b, h) do { _Pragma("unroll") for (int n = 0; n < 2; ++n) _Pragma("unroll") for (int k = 0; k < 2; ++k) dst[n][k] = *(const LAS bf16x8*)(lds + PG8_SB(b, h) + boff + n * 2048 + k * 1024); } while (0)
; #define PG8_MMA(ai, bj, At, Bt) do { __builtin_amdgcn_s_setprio(1); _Pragma("unroll") for (int m = 0; m < 4; ++m) _Pragma("unroll") for (int n = 0; n < 2; ++n) _Pragma("unroll") for (int k = 0; k < 2; ++k) \
;         acc[ai][bj][m][n] = __builtin_amdgcn_mfma_f32_16x16x32_bf16(Bt[n][k], At[m][k], acc[ai][bj][m][n], 0, 0, 0); __builtin_amdgcn_s_setprio(0); } while (0)
; #define PG8_WAIT_V(n) asm volatile("s_waitcnt vmcnt(" #n ")" ::: "memory")
; #define PG8_WAIT_L(n) asm volatile("s_waitcnt lgkmcnt(" #n ")" ::: "memory")
; #define PG8_BAR __builtin_amdgcn_s_barrier()
; #define PG8_SCHED __builtin_amdgcn_sched_barrier(0)
; template <class Epi, bool ALIGN_EPI, int K, int LDA, int LDB>
; __device__ __forceinline__ void gemm_phase(LAS unsigned char* lds, const int wid, const Gemm g, const StaticOrder& S, const Epi& E) {
;     ...
;             PG8_LDB(B0, 1, 0); PG8_LDB(B1, 1, 1); PG8_SCHED; PG8_LDA(At, 1, 0); PG8_STAGE(PG8_SA(0, 1), a2 + hA, voffA);
;             PG8_WAIT_V(8); PG8_WAIT_L(0); PG8_BAR; PG8_MMA(0, 0, At, B0); PG8_MMA(0, 1, At, B1); PG8_BAR; PG8_SCHED;
;             PG8_LDA(At, 1, 1); PG8_STAGE(PG8_SB(1, 0), b3, voffB); PG8_STAGE(PG8_SB(1, 1), b3 + hB, voffB); PG8_STAGE(PG8_SA(1, 0), a3, voffA);
;             PG8_WAIT_V(8); PG8_WAIT_L(0); PG8_BAR; PG8_MMA(1, 0, At, B0); PG8_MMA(1, 1, At, B1); PG8_BAR; PG8_SCHED;
	s_add_i32 s52, 0, 0x18000
	s_add_i32 s53, 0, 0x1c000
	v_add_u32_e32 v140, s52, v162
	v_add_u32_e32 v178, s53, v162
	ds_read_b128 v[128:131], v140
	ds_read_b128 v[132:135], v140 offset:1024
	ds_read_b128 v[136:139], v140 offset:2048
	ds_read_b128 v[140:143], v140 offset:3072
	ds_read_b128 v[166:169], v178
	ds_read_b128 v[170:173], v178 offset:1024
	ds_read_b128 v[174:177], v178 offset:2048
	ds_read_b128 v[178:181], v178 offset:3072
	s_add_u32 s40, s40, 0x40000
	s_addc_u32 s41, s41, 0
	s_mov_b32 m0, s43
	ds_read_b128 v[182:185], v165 offset:32768
	ds_read_b128 v[186:189], v165 offset:33792
	ds_read_b128 v[190:193], v165 offset:34816
	ds_read_b128 v[194:197], v165 offset:35840
	ds_read_b128 v[198:201], v165 offset:36864
	ds_read_b128 v[202:205], v165 offset:37888
	ds_read_b128 v[206:209], v165 offset:38912
	ds_read_b128 v[210:213], v165 offset:39936
	global_load_lds_dwordx4 v144, s[40:41]
	s_mov_b32 m0, s48
	s_nop 0
	global_load_lds_dwordx4 v148, s[40:41]
	s_waitcnt vmcnt(8)
	s_waitcnt lgkmcnt(0)
	s_barrier
	s_setprio 1
	s_waitcnt lgkmcnt(0)
	v_mfma_f32_16x16x32_bf16 v[124:127], v[128:131], v[182:185], v[124:127]
	v_mfma_f32_16x16x32_bf16 v[120:123], v[136:139], v[182:185], v[120:123]
	v_mfma_f32_16x16x32_bf16 v[108:111], v[128:131], v[190:193], v[108:111]
	v_mfma_f32_16x16x32_bf16 v[104:107], v[136:139], v[190:193], v[104:107]
	v_mfma_f32_16x16x32_bf16 v[92:95], v[128:131], v[198:201], v[92:95]
	v_mfma_f32_16x16x32_bf16 v[88:91], v[136:139], v[198:201], v[88:91]
	v_mfma_f32_16x16x32_bf16 v[76:79], v[128:131], v[206:209], v[76:79]
	v_mfma_f32_16x16x32_bf16 v[72:75], v[136:139], v[206:209], v[72:75]
	v_mfma_f32_16x16x32_bf16 v[124:127], v[132:135], v[186:189], v[124:127]
	v_mfma_f32_16x16x32_bf16 v[120:123], v[140:143], v[186:189], v[120:123]
	v_mfma_f32_16x16x32_bf16 v[108:111], v[132:135], v[194:197], v[108:111]
	v_mfma_f32_16x16x32_bf16 v[104:107], v[140:143], v[194:197], v[104:107]
	v_mfma_f32_16x16x32_bf16 v[92:95], v[132:135], v[202:205], v[92:95]
	v_mfma_f32_16x16x32_bf16 v[88:91], v[140:143], v[202:205], v[88:91]
	v_mfma_f32_16x16x32_bf16 v[76:79], v[132:135], v[210:213], v[76:79]
	v_mfma_f32_16x16x32_bf16 v[72:75], v[140:143], v[210:213], v[72:75]
	v_mfma_f32_16x16x32_bf16 v[116:119], v[166:169], v[182:185], v[116:119]
	v_mfma_f32_16x16x32_bf16 v[112:115], v[174:177], v[182:185], v[112:115]
	v_mfma_f32_16x16x32_bf16 v[100:103], v[166:169], v[190:193], v[100:103]
	v_mfma_f32_16x16x32_bf16 v[96:99], v[174:177], v[190:193], v[96:99]
	v_mfma_f32_16x16x32_bf16 v[84:87], v[166:169], v[198:201], v[84:87]
	v_mfma_f32_16x16x32_bf16 v[80:83], v[174:177], v[198:201], v[80:83]
	v_mfma_f32_16x16x32_bf16 v[68:71], v[166:169], v[206:209], v[68:71]
	v_mfma_f32_16x16x32_bf16 v[64:67], v[174:177], v[206:209], v[64:67]
	v_mfma_f32_16x16x32_bf16 v[116:119], v[170:173], v[186:189], v[116:119]
	v_mfma_f32_16x16x32_bf16 v[112:115], v[178:181], v[186:189], v[112:115]
	v_mfma_f32_16x16x32_bf16 v[100:103], v[170:173], v[194:197], v[100:103]
	v_mfma_f32_16x16x32_bf16 v[96:99], v[178:181], v[194:197], v[96:99]
	v_mfma_f32_16x16x32_bf16 v[84:87], v[170:173], v[202:205], v[84:87]
	v_mfma_f32_16x16x32_bf16 v[80:83], v[178:181], v[202:205], v[80:83]
	v_mfma_f32_16x16x32_bf16 v[68:71], v[170:173], v[210:213], v[68:71]
	v_mfma_f32_16x16x32_bf16 v[64:67], v[178:181], v[210:213], v[64:67]
	s_setprio 0
	s_barrier
	s_add_i32 s40, s52, s33
	s_mov_b32 m0, s40
	ds_read_b128 v[182:185], v165 offset:49152
	ds_read_b128 v[186:189], v165 offset:50176
	ds_read_b128 v[190:193], v165 offset:51200
	ds_read_b128 v[194:197], v165 offset:52224
	ds_read_b128 v[198:201], v165 offset:53248
	ds_read_b128 v[202:205], v165 offset:54272
	ds_read_b128 v[206:209], v165 offset:55296
	ds_read_b128 v[210:213], v165 offset:56320
	global_load_lds_dwordx4 v146, s[98:99]
	s_add_i32 m0, s40, 0x2000
	s_add_u32 s38, s38, 0x40080
	s_addc_u32 s39, s39, 0
	s_add_i32 s40, s53, s33
	global_load_lds_dwordx4 v150, s[98:99]
	s_mov_b32 m0, s40
	s_nop 0
	global_load_lds_dwordx4 v146, s[38:39]
	s_add_i32 m0, s40, 0x2000
	s_nop 0
	global_load_lds_dwordx4 v150, s[38:39]
	s_mov_b32 m0, s55
	s_nop 0
	global_load_lds_dwordx4 v144, s[100:101]
	s_mov_b32 m0, s56
	s_nop 0
	global_load_lds_dwordx4 v148, s[100:101]
	s_waitcnt vmcnt(8)
	s_waitcnt lgkmcnt(0)
	s_barrier
	s_setprio 1
	s_waitcnt lgkmcnt(0)
	v_mfma_f32_16x16x32_bf16 v[60:63], v[128:131], v[182:185], v[60:63]
	v_mfma_f32_16x16x32_bf16 v[56:59], v[136:139], v[182:185], v[56:59]
	v_mfma_f32_16x16x32_bf16 v[44:47], v[128:131], v[190:193], v[44:47]
	v_mfma_f32_16x16x32_bf16 v[40:43], v[136:139], v[190:193], v[40:43]
	v_mfma_f32_16x16x32_bf16 v[28:31], v[128:131], v[198:201], v[28:31]
	v_mfma_f32_16x16x32_bf16 v[24:27], v[136:139], v[198:201], v[24:27]
	v_mfma_f32_16x16x32_bf16 v[12:15], v[128:131], v[206:209], v[12:15]
	v_mfma_f32_16x16x32_bf16 v[8:11], v[136:139], v[206:209], v[8:11]
	v_mfma_f32_16x16x32_bf16 v[60:63], v[132:135], v[186:189], v[60:63]
	v_mfma_f32_16x16x32_bf16 v[56:59], v[140:143], v[186:189], v[56:59]
	v_mfma_f32_16x16x32_bf16 v[44:47], v[132:135], v[194:197], v[44:47]
	v_mfma_f32_16x16x32_bf16 v[40:43], v[140:143], v[194:197], v[40:43]
	v_mfma_f32_16x16x32_bf16 v[28:31], v[132:135], v[202:205], v[28:31]
	v_mfma_f32_16x16x32_bf16 v[24:27], v[140:143], v[202:205], v[24:27]
	v_mfma_f32_16x16x32_bf16 v[12:15], v[132:135], v[210:213], v[12:15]
	v_mfma_f32_16x16x32_bf16 v[8:11], v[140:143], v[210:213], v[8:11]
	v_mfma_f32_16x16x32_bf16 v[52:55], v[166:169], v[182:185], v[52:55]
	v_mfma_f32_16x16x32_bf16 v[48:51], v[174:177], v[182:185], v[48:51]
	v_mfma_f32_16x16x32_bf16 v[36:39], v[166:169], v[190:193], v[36:39]
	v_mfma_f32_16x16x32_bf16 v[32:35], v[174:177], v[190:193], v[32:35]
	v_mfma_f32_16x16x32_bf16 v[20:23], v[166:169], v[198:201], v[20:23]
	v_mfma_f32_16x16x32_bf16 v[16:19], v[174:177], v[198:201], v[16:19]
	v_mfma_f32_16x16x32_bf16 v[4:7], v[166:169], v[206:209], v[4:7]
	v_mfma_f32_16x16x32_bf16 v[0:3], v[174:177], v[206:209], v[0:3]
	v_mfma_f32_16x16x32_bf16 v[52:55], v[170:173], v[186:189], v[52:55]
	v_mfma_f32_16x16x32_bf16 v[48:51], v[178:181], v[186:189], v[48:51]
	v_mfma_f32_16x16x32_bf16 v[36:39], v[170:173], v[194:197], v[36:39]
	v_mfma_f32_16x16x32_bf16 v[32:35], v[178:181], v[194:197], v[32:35]
	v_mfma_f32_16x16x32_bf16 v[20:23], v[170:173], v[202:205], v[20:23]
	v_mfma_f32_16x16x32_bf16 v[16:19], v[178:181], v[202:205], v[16:19]
	v_mfma_f32_16x16x32_bf16 v[4:7], v[170:173], v[210:213], v[4:7]
	v_mfma_f32_16x16x32_bf16 v[0:3], v[178:181], v[210:213], v[0:3]
	s_setprio 0
	s_barrier
	s_add_i32 s67, s67, 2
	s_add_u32 s36, s36, 0x100
	s_addc_u32 s37, s37, 0
	s_add_u32 s65, s65, 0x100
	s_addc_u32 s66, s66, 0

; #define PG8_STAGE(bufoff, gbase, voff) do { _Pragma("unroll") for (int _i = 0; _i < 2; ++_i) \
;         __builtin_amdgcn_global_load_lds((const unsigned*)((const char*)(gbase) + (voff)[_i]), (LAS unsigned*)(lds + (bufoff) + ldsw + _i * 8192), 16, 0, 0); } while (0)
; #define PG8_LDA(dst, b, h) do { _Pragma("unroll") for (int m = 0; m < 4; ++m) _Pragma("unroll") for (int k = 0; k < 2; ++k) dst[m][k] = *(const LAS bf16x8*)(lds + PG8_SA(b, h) + aoff + m * 2048 + k * 1024); } while (0)
; #define PG8_WAIT_V(n) asm volatile("s_waitcnt vmcnt(" #n ")" ::: "memory")
; #define PG8_BAR __builtin_amdgcn_s_barrier()
;     __device__ bool next(int i, Unit& u) const {
;         const long L = (long)i * G + c; if (L >= nwg) return false;
;         int wgid = (int)L; { const int q = nwg / NXCD, r = nwg % NXCD, xcd = wgid % NXCD, off = wgid / NXCD; wgid = (xcd < r ? xcd * (q + 1) : r * (q + 1) + (xcd - r) * q) + off; }
;         const int nig = WGM * nN, gid = wgid / nig, fm = gid * WGM, gsz = (nM - fm) < WGM ? (nM - fm) : WGM;
;         u.pm = fm + ((wgid % nig) % gsz); u.pn = (wgid % nig) / gsz; return true;
; template <class Epi, bool ALIGN_EPI, int K, int LDA, int LDB>
; __device__ __forceinline__ void gemm_phase(LAS unsigned char* lds, const int wid, const Gemm g, const StaticOrder& S, const Epi& E) {
;     ...
;         const bool has_next = S.next(ui + 1, nxt);
;         const char* nA = has_next ? (const char*)g.A + (size_t)nxt.pm * tA : cA; const char* nB = has_next ? (const char*)g.Bt + (size_t)nxt.pn * tB : cB;
;         for (int t = 0; t < nt; t += 2) {
;             const bool last = (t == nt - 2);
;             const char* a1 = cA + (size_t)(t + 1) * kstep;
;             const char* a2 = last ? nA : cA + (size_t)(t + 2) * kstep; const char* b2 = last ? nB : cB + (size_t)(t + 2) * kstep;
;             const char* a3 = a2 + kstep; const char* b3 = b2 + kstep;
;             PG8_LDB(B0, 0, 0); PG8_LDB(B1, 0, 1); PG8_SCHED; PG8_LDA(At, 0, 0); PG8_STAGE(PG8_SA(1, 1), a1 + hA, voffA);
;             PG8_WAIT_V(8); PG8_WAIT_L(0); PG8_BAR; PG8_MMA(0, 0, At, B0); PG8_MMA(0, 1, At, B1); PG8_BAR; PG8_SCHED;
;             PG8_LDA(At, 0, 1); PG8_STAGE(PG8_SB(0, 0), b2, voffB); PG8_STAGE(PG8_SB(0, 1), b2 + hB, voffB); PG8_STAGE(PG8_SA(0, 0), a2, voffA);
;             PG8_WAIT_V(8); PG8_WAIT_L(0); PG8_BAR; PG8_MMA(1, 0, At, B0); PG8_MMA(1, 1, At, B1); PG8_BAR; PG8_SCHED;
.LBB0_1049:
	ds_read_b128 v[148:151], v145
	ds_read_b128 v[152:155], v145 offset:1024
	ds_read_b128 v[156:159], v145 offset:2048
	ds_read_b128 v[160:163], v145 offset:3072
	ds_read_b128 v[164:167], v146
	ds_read_b128 v[168:171], v146 offset:1024
	ds_read_b128 v[172:175], v146 offset:2048
	ds_read_b128 v[176:179], v146 offset:3072
	ds_read_b128 v[180:183], v147
	ds_read_b128 v[184:187], v147 offset:1024
	ds_read_b128 v[188:191], v147 offset:2048
	ds_read_b128 v[192:195], v147 offset:3072
	ds_read_b128 v[196:199], v147 offset:4096
	ds_read_b128 v[200:203], v147 offset:5120
	ds_read_b128 v[204:207], v147 offset:6144
	ds_read_b128 v[208:211], v147 offset:7168
	s_add_i32 s34, s34, 1
	s_mul_i32 s4, s34, s37
	s_mul_hi_u32 s5, s34, s90
	s_add_i32 s5, s5, s4
	s_mul_i32 s4, s34, s90
	s_add_u32 s16, s4, s2
	s_addc_u32 s17, s5, s28
	v_cmp_gt_i64_e32 vcc, s[16:17], v[142:143]
	v_cmp_lt_i64_e64 s[4:5], s[16:17], v[140:141]
	s_cbranch_vccnz .LBB0_1051
	s_ashr_i32 s12, s16, 31
	s_lshr_b32 s12, s12, 29
	s_add_i32 s12, s16, s12
	s_ashr_i32 s13, s12, 3
	s_and_b32 s12, s12, -8
	s_sub_i32 s12, s16, s12
	s_cmp_lt_i32 s12, 0
	s_cselect_b32 s14, s29, 0x2c0
	s_mul_i32 s12, s12, s14
	s_add_i32 s12, s12, s13
	s_mul_hi_i32 s13, s12, 0x2e8ba2e9
	s_lshr_b32 s14, s13, 31
	s_ashr_i32 s13, s13, 5
	s_add_i32 s13, s13, s14
	s_lshl_b32 s14, s13, 3
	s_mulk_i32 s13, 0xb0
	s_sub_i32 s13, s12, s13
	s_lshr_b32 s12, s13, 3
	s_and_b32 s13, s13, 7
	s_add_i32 s14, s14, s13
.LBB0_1051:
	s_ashr_i32 s15, s14, 31
	s_lshl_b64 s[16:17], s[14:15], 19
	v_readlane_b32 s13, v254, 0
	s_add_u32 s16, s13, s16
	v_readlane_b32 s13, v254, 1
	s_addc_u32 s17, s13, s17
	s_and_b64 s[18:19], s[4:5], exec
	s_cselect_b32 s15, s17, s23
	s_cselect_b32 s48, s16, s22
	s_ashr_i32 s13, s12, 31
	s_lshl_b64 s[18:19], s[12:13], 19
	s_add_u32 s18, s0, s18
	s_addc_u32 s19, s1, s19
	s_and_b64 s[26:27], s[4:5], exec
	s_cselect_b32 s13, s19, s25
	s_cselect_b32 s49, s18, s24
	s_add_u32 s22, s22, 0x40080
	s_addc_u32 s23, s23, 0
	s_add_u32 s51, s24, 0x100
	s_addc_u32 s54, s25, 0
	s_mov_b32 s55, -2
	s_add_u32 s24, s22, 0xfffc0080
	s_addc_u32 s25, s23, -1
	s_cmp_eq_u32 s55, 12
	s_cselect_b32 s27, s15, s25
	s_cselect_b32 s26, s48, s24
	s_cselect_b32 s25, s13, s54
	s_cselect_b32 s24, s49, s51
	s_add_i32 m0, s21, 0xc000
	global_load_lds_dwordx4 v136, s[22:23]
	s_add_i32 m0, s21, 0xe000
	s_nop 0
	global_load_lds_dwordx4 v138, s[22:23]
	s_waitcnt vmcnt(8)
	s_waitcnt lgkmcnt(0)
	s_barrier
	s_setprio 1
	s_waitcnt lgkmcnt(0)
	v_mfma_f32_16x16x32_bf16 v[124:127], v[148:151], v[180:183], 0
	v_mfma_f32_16x16x32_bf16 v[120:123], v[156:159], v[180:183], 0
	v_mfma_f32_16x16x32_bf16 v[108:111], v[148:151], v[188:191], 0
	v_mfma_f32_16x16x32_bf16 v[104:107], v[156:159], v[188:191], 0
	v_mfma_f32_16x16x32_bf16 v[92:95], v[148:151], v[196:199], 0
	v_mfma_f32_16x16x32_bf16 v[88:91], v[156:159], v[196:199], 0
	v_mfma_f32_16x16x32_bf16 v[76:79], v[148:151], v[204:207], 0
	v_mfma_f32_16x16x32_bf16 v[72:75], v[156:159], v[204:207], 0
	v_mfma_f32_16x16x32_bf16 v[124:127], v[152:155], v[184:187], v[124:127]
	v_mfma_f32_16x16x32_bf16 v[120:123], v[160:163], v[184:187], v[120:123]
	v_mfma_f32_16x16x32_bf16 v[108:111], v[152:155], v[192:195], v[108:111]
	v_mfma_f32_16x16x32_bf16 v[104:107], v[160:163], v[192:195], v[104:107]
	v_mfma_f32_16x16x32_bf16 v[92:95], v[152:155], v[200:203], v[92:95]
	v_mfma_f32_16x16x32_bf16 v[88:91], v[160:163], v[200:203], v[88:91]
	v_mfma_f32_16x16x32_bf16 v[76:79], v[152:155], v[208:211], v[76:79]
	v_mfma_f32_16x16x32_bf16 v[72:75], v[160:163], v[208:211], v[72:75]
	v_mfma_f32_16x16x32_bf16 v[116:119], v[164:167], v[180:183], 0
	v_mfma_f32_16x16x32_bf16 v[112:115], v[172:175], v[180:183], 0
	v_mfma_f32_16x16x32_bf16 v[100:103], v[164:167], v[188:191], 0
	v_mfma_f32_16x16x32_bf16 v[96:99], v[172:175], v[188:191], 0
	v_mfma_f32_16x16x32_bf16 v[84:87], v[164:167], v[196:199], 0
	v_mfma_f32_16x16x32_bf16 v[80:83], v[172:175], v[196:199], 0
	v_mfma_f32_16x16x32_bf16 v[68:71], v[164:167], v[204:207], 0
	v_mfma_f32_16x16x32_bf16 v[64:67], v[172:175], v[204:207], 0
	v_mfma_f32_16x16x32_bf16 v[116:119], v[168:171], v[184:187], v[116:119]
	v_mfma_f32_16x16x32_bf16 v[112:115], v[176:179], v[184:187], v[112:115]
	v_mfma_f32_16x16x32_bf16 v[100:103], v[168:171], v[192:195], v[100:103]
	v_mfma_f32_16x16x32_bf16 v[96:99], v[176:179], v[192:195], v[96:99]
	v_mfma_f32_16x16x32_bf16 v[84:87], v[168:171], v[200:203], v[84:87]
	v_mfma_f32_16x16x32_bf16 v[80:83], v[176:179], v[200:203], v[80:83]
	v_mfma_f32_16x16x32_bf16 v[68:71], v[168:171], v[208:211], v[68:71]
	v_mfma_f32_16x16x32_bf16 v[64:67], v[176:179], v[208:211], v[64:67]
	s_setprio 0
	s_barrier
	s_add_u32 s98, s24, s10
	s_addc_u32 s99, s25, s11
	s_add_u32 s100, s26, s10
	s_addc_u32 s101, s27, s11
	s_add_i32 s52, s40, s3
	s_mov_b32 m0, s52
	ds_read_b128 v[180:183], v147 offset:16384
	ds_read_b128 v[184:187], v147 offset:17408
	ds_read_b128 v[188:191], v147 offset:18432
	ds_read_b128 v[192:195], v147 offset:19456
	ds_read_b128 v[196:199], v147 offset:20480
	ds_read_b128 v[200:203], v147 offset:21504
	ds_read_b128 v[204:207], v147 offset:22528
	ds_read_b128 v[208:211], v147 offset:23552
	global_load_lds_dwordx4 v132, s[24:25]
	s_add_i32 m0, s52, 0x2000
	s_add_u32 s56, s24, 0x40000
	s_addc_u32 s57, s25, 0
	s_add_i32 s52, s41, s3
	global_load_lds_dwordx4 v128, s[24:25]
	s_mov_b32 m0, s52
	s_nop 0
	global_load_lds_dwordx4 v132, s[56:57]
	s_add_i32 m0, s52, 0x2000
	s_nop 0
	global_load_lds_dwordx4 v128, s[56:57]
	s_mov_b32 m0, s21
	s_nop 0
	global_load_lds_dwordx4 v134, s[26:27]
	s_mov_b32 m0, s30
	s_nop 0
	global_load_lds_dwordx4 v130, s[26:27]
	s_waitcnt vmcnt(8)
	s_waitcnt lgkmcnt(0)
	s_barrier
; #define PG8_STAGE(bufoff, gbase, voff) do { _Pragma("unroll") for (int _i = 0; _i < 2; ++_i) \
;         __builtin_amdgcn_global_load_lds((const unsigned*)((const char*)(gbase) + (voff)[_i]), (LAS unsigned*)(lds + (bufoff) + ldsw + _i * 8192), 16, 0, 0); } while (0)
; #define PG8_LDA(dst, b, h) do { _Pragma("unroll") for (int m = 0; m < 4; ++m) _Pragma("unroll") for (int k = 0; k < 2; ++k) dst[m][k] = *(const LAS bf16x8*)(lds + PG8_SA(b, h) + aoff + m * 2048 + k * 1024); } while (0)
; #define PG8_LDB(dst, b, h) do { _Pragma("unroll") for (int n = 0; n < 2; ++n) _Pragma("unroll") for (int k = 0; k < 2; ++k) dst[n][k] = *(const LAS bf16x8*)(lds + PG8_SB(b, h) + boff + n * 2048 + k * 1024); } while (0)
; #define PG8_MMA(ai, bj, At, Bt) do { __builtin_amdgcn_s_setprio(1); _Pragma("unroll") for (int m = 0; m < 4; ++m) _Pragma("unroll") for (int n = 0; n < 2; ++n) _Pragma("unroll") for (int k = 0; k < 2; ++k) \
;         acc[ai][bj][m][n] = __builtin_amdgcn_mfma_f32_16x16x32_bf16(Bt[n][k], At[m][k], acc[ai][bj][m][n], 0, 0, 0); __builtin_amdgcn_s_setprio(0); } while (0)
; #define PG8_WAIT_V(n) asm volatile("s_waitcnt vmcnt(" #n ")" ::: "memory")
; #define PG8_WAIT_L(n) asm volatile("s_waitcnt lgkmcnt(" #n ")" ::: "memory")
; #define PG8_BAR __builtin_amdgcn_s_barrier()
; #define PG8_SCHED __builtin_amdgcn_sched_barrier(0)
; template <class Epi, bool ALIGN_EPI, int K, int LDA, int LDB>
; __device__ __forceinline__ void gemm_phase(LAS unsigned char* lds, const int wid, const Gemm g, const StaticOrder& S, const Epi& E) {
;     ...
;             PG8_WAIT_V(8); PG8_WAIT_L(0); PG8_BAR; PG8_MMA(1, 0, At, B0); PG8_MMA(1, 1, At, B1); PG8_BAR; PG8_SCHED;
;             PG8_LDB(B0, 1, 0); PG8_LDB(B1, 1, 1); PG8_SCHED; PG8_LDA(At, 1, 0); PG8_STAGE(PG8_SA(0, 1), a2 + hA, voffA);
;             PG8_WAIT_V(8); PG8_WAIT_L(0); PG8_BAR; PG8_MMA(0, 0, At, B0); PG8_MMA(0, 1, At, B1); PG8_BAR; PG8_SCHED;
	s_setprio 1
	s_waitcnt lgkmcnt(0)
	v_mfma_f32_16x16x32_bf16 v[60:63], v[148:151], v[180:183], 0
	v_mfma_f32_16x16x32_bf16 v[56:59], v[156:159], v[180:183], 0
	v_mfma_f32_16x16x32_bf16 v[44:47], v[148:151], v[188:191], 0
	v_mfma_f32_16x16x32_bf16 v[40:43], v[156:159], v[188:191], 0
	v_mfma_f32_16x16x32_bf16 v[28:31], v[148:151], v[196:199], 0
	v_mfma_f32_16x16x32_bf16 v[24:27], v[156:159], v[196:199], 0
	v_mfma_f32_16x16x32_bf16 v[12:15], v[148:151], v[204:207], 0
	v_mfma_f32_16x16x32_bf16 v[8:11], v[156:159], v[204:207], 0
	v_mfma_f32_16x16x32_bf16 v[60:63], v[152:155], v[184:187], v[60:63]
	v_mfma_f32_16x16x32_bf16 v[56:59], v[160:163], v[184:187], v[56:59]
	v_mfma_f32_16x16x32_bf16 v[44:47], v[152:155], v[192:195], v[44:47]
	v_mfma_f32_16x16x32_bf16 v[40:43], v[160:163], v[192:195], v[40:43]
	v_mfma_f32_16x16x32_bf16 v[28:31], v[152:155], v[200:203], v[28:31]
	v_mfma_f32_16x16x32_bf16 v[24:27], v[160:163], v[200:203], v[24:27]
	v_mfma_f32_16x16x32_bf16 v[12:15], v[152:155], v[208:211], v[12:15]
	v_mfma_f32_16x16x32_bf16 v[8:11], v[160:163], v[208:211], v[8:11]
	v_mfma_f32_16x16x32_bf16 v[52:55], v[164:167], v[180:183], 0
	v_mfma_f32_16x16x32_bf16 v[48:51], v[172:175], v[180:183], 0
	v_mfma_f32_16x16x32_bf16 v[36:39], v[164:167], v[188:191], 0
	v_mfma_f32_16x16x32_bf16 v[32:35], v[172:175], v[188:191], 0
	v_mfma_f32_16x16x32_bf16 v[20:23], v[164:167], v[196:199], 0
	v_mfma_f32_16x16x32_bf16 v[16:19], v[172:175], v[196:199], 0
	v_mfma_f32_16x16x32_bf16 v[4:7], v[164:167], v[204:207], 0
	v_mfma_f32_16x16x32_bf16 v[0:3], v[172:175], v[204:207], 0
	v_mfma_f32_16x16x32_bf16 v[52:55], v[168:171], v[184:187], v[52:55]
	v_mfma_f32_16x16x32_bf16 v[48:51], v[176:179], v[184:187], v[48:51]
	v_mfma_f32_16x16x32_bf16 v[36:39], v[168:171], v[192:195], v[36:39]
	v_mfma_f32_16x16x32_bf16 v[32:35], v[176:179], v[192:195], v[32:35]
	v_mfma_f32_16x16x32_bf16 v[20:23], v[168:171], v[200:203], v[20:23]
	v_mfma_f32_16x16x32_bf16 v[16:19], v[176:179], v[200:203], v[16:19]
	v_mfma_f32_16x16x32_bf16 v[4:7], v[168:171], v[208:211], v[4:7]
	v_mfma_f32_16x16x32_bf16 v[0:3], v[176:179], v[208:211], v[0:3]
	s_setprio 0
	s_barrier
	s_add_i32 s52, 0, 0x18000
	s_add_i32 s53, 0, 0x1c000
	v_add_u32_e32 v160, s52, v144
	v_add_u32_e32 v176, s53, v144
	ds_read_b128 v[148:151], v160
	ds_read_b128 v[152:155], v160 offset:1024
	ds_read_b128 v[156:159], v160 offset:2048
	ds_read_b128 v[160:163], v160 offset:3072
	ds_read_b128 v[164:167], v176
	ds_read_b128 v[168:171], v176 offset:1024
	ds_read_b128 v[172:175], v176 offset:2048
	ds_read_b128 v[176:179], v176 offset:3072
	s_add_u32 s26, s26, 0x40000
	s_addc_u32 s27, s27, 0
	s_mov_b32 m0, s31
	ds_read_b128 v[180:183], v147 offset:32768
	ds_read_b128 v[184:187], v147 offset:33792
	ds_read_b128 v[188:191], v147 offset:34816
	ds_read_b128 v[192:195], v147 offset:35840
	ds_read_b128 v[196:199], v147 offset:36864
	ds_read_b128 v[200:203], v147 offset:37888
	ds_read_b128 v[204:207], v147 offset:38912
	ds_read_b128 v[208:211], v147 offset:39936
	global_load_lds_dwordx4 v134, s[26:27]
	s_mov_b32 m0, s33
	s_nop 0
	global_load_lds_dwordx4 v130, s[26:27]
	s_waitcnt vmcnt(8)
	s_waitcnt lgkmcnt(0)
	s_barrier
	s_setprio 1
	s_waitcnt lgkmcnt(0)
	v_mfma_f32_16x16x32_bf16 v[124:127], v[148:151], v[180:183], v[124:127]
	v_mfma_f32_16x16x32_bf16 v[120:123], v[156:159], v[180:183], v[120:123]
	v_mfma_f32_16x16x32_bf16 v[108:111], v[148:151], v[188:191], v[108:111]
	v_mfma_f32_16x16x32_bf16 v[104:107], v[156:159], v[188:191], v[104:107]
	v_mfma_f32_16x16x32_bf16 v[92:95], v[148:151], v[196:199], v[92:95]
	v_mfma_f32_16x16x32_bf16 v[88:91], v[156:159], v[196:199], v[88:91]
	v_mfma_f32_16x16x32_bf16 v[76:79], v[148:151], v[204:207], v[76:79]
	v_mfma_f32_16x16x32_bf16 v[72:75], v[156:159], v[204:207], v[72:75]
	v_mfma_f32_16x16x32_bf16 v[124:127], v[152:155], v[184:187], v[124:127]
	v_mfma_f32_16x16x32_bf16 v[120:123], v[160:163], v[184:187], v[120:123]
	v_mfma_f32_16x16x32_bf16 v[108:111], v[152:155], v[192:195], v[108:111]
	v_mfma_f32_16x16x32_bf16 v[104:107], v[160:163], v[192:195], v[104:107]
	v_mfma_f32_16x16x32_bf16 v[92:95], v[152:155], v[200:203], v[92:95]
	v_mfma_f32_16x16x32_bf16 v[88:91], v[160:163], v[200:203], v[88:91]
	v_mfma_f32_16x16x32_bf16 v[76:79], v[152:155], v[208:211], v[76:79]
	v_mfma_f32_16x16x32_bf16 v[72:75], v[160:163], v[208:211], v[72:75]
	v_mfma_f32_16x16x32_bf16 v[116:119], v[164:167], v[180:183], v[116:119]
	v_mfma_f32_16x16x32_bf16 v[112:115], v[172:175], v[180:183], v[112:115]
	v_mfma_f32_16x16x32_bf16 v[100:103], v[164:167], v[188:191], v[100:103]
	v_mfma_f32_16x16x32_bf16 v[96:99], v[172:175], v[188:191], v[96:99]
	v_mfma_f32_16x16x32_bf16 v[84:87], v[164:167], v[196:199], v[84:87]
	v_mfma_f32_16x16x32_bf16 v[80:83], v[172:175], v[196:199], v[80:83]
	v_mfma_f32_16x16x32_bf16 v[68:71], v[164:167], v[204:207], v[68:71]
	v_mfma_f32_16x16x32_bf16 v[64:67], v[172:175], v[204:207], v[64:67]
	v_mfma_f32_16x16x32_bf16 v[116:119], v[168:171], v[184:187], v[116:119]
	v_mfma_f32_16x16x32_bf16 v[112:115], v[176:179], v[184:187], v[112:115]
	v_mfma_f32_16x16x32_bf16 v[100:103], v[168:171], v[192:195], v[100:103]
	v_mfma_f32_16x16x32_bf16 v[96:99], v[176:179], v[192:195], v[96:99]
	v_mfma_f32_16x16x32_bf16 v[84:87], v[168:171], v[200:203], v[84:87]
	v_mfma_f32_16x16x32_bf16 v[80:83], v[176:179], v[200:203], v[80:83]
	v_mfma_f32_16x16x32_bf16 v[68:71], v[168:171], v[208:211], v[68:71]
	v_mfma_f32_16x16x32_bf16 v[64:67], v[176:179], v[208:211], v[64:67]
	s_setprio 0
	s_barrier
; #define PG8_STAGE(bufoff, gbase, voff) do { _Pragma("unroll") for (int _i = 0; _i < 2; ++_i) \
;         __builtin_amdgcn_global_load_lds((const unsigned*)((const char*)(gbase) + (voff)[_i]), (LAS unsigned*)(lds + (bufoff) + ldsw + _i * 8192), 16, 0, 0); } while (0)
; #define PG8_LDA(dst, b, h) do { _Pragma("unroll") for (int m = 0; m < 4; ++m) _Pragma("unroll") for (int k = 0; k < 2; ++k) dst[m][k] = *(const LAS bf16x8*)(lds + PG8_SA(b, h) + aoff + m * 2048 + k * 1024); } while (0)
; #define PG8_MMA(ai, bj, At, Bt) do { __builtin_amdgcn_s_setprio(1); _Pragma("unroll") for (int m = 0; m < 4; ++m) _Pragma("unroll") for (int n = 0; n < 2; ++n) _Pragma("unroll") for (int k = 0; k < 2; ++k) \
;         acc[ai][bj][m][n] = __builtin_amdgcn_mfma_f32_16x16x32_bf16(Bt[n][k], At[m][k], acc[ai][bj][m][n], 0, 0, 0); __builtin_amdgcn_s_setprio(0); } while (0)
; #define PG8_WAIT_V(n) asm volatile("s_waitcnt vmcnt(" #n ")" ::: "memory")
; #define PG8_WAIT_L(n) asm volatile("s_waitcnt lgkmcnt(" #n ")" ::: "memory")
; #define PG8_BAR __builtin_amdgcn_s_barrier()
; #define PG8_SCHED __builtin_amdgcn_sched_barrier(0)
; template <class Epi, bool ALIGN_EPI, int K, int LDA, int LDB>
; __device__ __forceinline__ void gemm_phase(LAS unsigned char* lds, const int wid, const Gemm g, const StaticOrder& S, const Epi& E) {
;     ...
;             PG8_LDA(At, 1, 1); PG8_STAGE(PG8_SB(1, 0), b3, voffB); PG8_STAGE(PG8_SB(1, 1), b3 + hB, voffB); PG8_STAGE(PG8_SA(1, 0), a3, voffA);
;             PG8_WAIT_V(8); PG8_WAIT_L(0); PG8_BAR; PG8_MMA(1, 0, At, B0); PG8_MMA(1, 1, At, B1); PG8_BAR; PG8_SCHED;
;         }
	s_add_i32 s26, s52, s3
	s_mov_b32 m0, s26
	ds_read_b128 v[180:183], v147 offset:49152
	ds_read_b128 v[184:187], v147 offset:50176
	ds_read_b128 v[188:191], v147 offset:51200
	ds_read_b128 v[192:195], v147 offset:52224
	ds_read_b128 v[196:199], v147 offset:53248
	ds_read_b128 v[200:203], v147 offset:54272
	ds_read_b128 v[204:207], v147 offset:55296
	ds_read_b128 v[208:211], v147 offset:56320
	global_load_lds_dwordx4 v132, s[98:99]
	s_add_i32 m0, s26, 0x2000
	s_add_u32 s24, s24, 0x40080
	s_addc_u32 s25, s25, 0
	s_add_i32 s26, s53, s3
	global_load_lds_dwordx4 v128, s[98:99]
	s_mov_b32 m0, s26
	s_nop 0
	global_load_lds_dwordx4 v132, s[24:25]
	s_add_i32 m0, s26, 0x2000
	s_nop 0
	global_load_lds_dwordx4 v128, s[24:25]
	s_mov_b32 m0, s38
	s_nop 0
	global_load_lds_dwordx4 v134, s[100:101]
	s_mov_b32 m0, s39
	s_nop 0
	global_load_lds_dwordx4 v130, s[100:101]
	s_waitcnt vmcnt(8)
	s_waitcnt lgkmcnt(0)
	s_barrier
	s_setprio 1
	s_waitcnt lgkmcnt(0)
	v_mfma_f32_16x16x32_bf16 v[60:63], v[148:151], v[180:183], v[60:63]
	v_mfma_f32_16x16x32_bf16 v[56:59], v[156:159], v[180:183], v[56:59]
	v_mfma_f32_16x16x32_bf16 v[44:47], v[148:151], v[188:191], v[44:47]
	v_mfma_f32_16x16x32_bf16 v[40:43], v[156:159], v[188:191], v[40:43]
	v_mfma_f32_16x16x32_bf16 v[28:31], v[148:151], v[196:199], v[28:31]
	v_mfma_f32_16x16x32_bf16 v[24:27], v[156:159], v[196:199], v[24:27]
	v_mfma_f32_16x16x32_bf16 v[12:15], v[148:151], v[204:207], v[12:15]
	v_mfma_f32_16x16x32_bf16 v[8:11], v[156:159], v[204:207], v[8:11]
	v_mfma_f32_16x16x32_bf16 v[60:63], v[152:155], v[184:187], v[60:63]
	v_mfma_f32_16x16x32_bf16 v[56:59], v[160:163], v[184:187], v[56:59]
	v_mfma_f32_16x16x32_bf16 v[44:47], v[152:155], v[192:195], v[44:47]
	v_mfma_f32_16x16x32_bf16 v[40:43], v[160:163], v[192:195], v[40:43]
	v_mfma_f32_16x16x32_bf16 v[28:31], v[152:155], v[200:203], v[28:31]
	v_mfma_f32_16x16x32_bf16 v[24:27], v[160:163], v[200:203], v[24:27]
	v_mfma_f32_16x16x32_bf16 v[12:15], v[152:155], v[208:211], v[12:15]
	v_mfma_f32_16x16x32_bf16 v[8:11], v[160:163], v[208:211], v[8:11]
	v_mfma_f32_16x16x32_bf16 v[52:55], v[164:167], v[180:183], v[52:55]
	v_mfma_f32_16x16x32_bf16 v[48:51], v[172:175], v[180:183], v[48:51]
	v_mfma_f32_16x16x32_bf16 v[36:39], v[164:167], v[188:191], v[36:39]
	v_mfma_f32_16x16x32_bf16 v[32:35], v[172:175], v[188:191], v[32:35]
	v_mfma_f32_16x16x32_bf16 v[20:23], v[164:167], v[196:199], v[20:23]
	v_mfma_f32_16x16x32_bf16 v[16:19], v[172:175], v[196:199], v[16:19]
	v_mfma_f32_16x16x32_bf16 v[4:7], v[164:167], v[204:207], v[4:7]
	v_mfma_f32_16x16x32_bf16 v[0:3], v[172:175], v[204:207], v[0:3]
	v_mfma_f32_16x16x32_bf16 v[52:55], v[168:171], v[184:187], v[52:55]
	v_mfma_f32_16x16x32_bf16 v[48:51], v[176:179], v[184:187], v[48:51]
	v_mfma_f32_16x16x32_bf16 v[36:39], v[168:171], v[192:195], v[36:39]
	v_mfma_f32_16x16x32_bf16 v[32:35], v[176:179], v[192:195], v[32:35]
	v_mfma_f32_16x16x32_bf16 v[20:23], v[168:171], v[200:203], v[20:23]
	v_mfma_f32_16x16x32_bf16 v[16:19], v[176:179], v[200:203], v[16:19]
	v_mfma_f32_16x16x32_bf16 v[4:7], v[168:171], v[208:211], v[4:7]
	v_mfma_f32_16x16x32_bf16 v[0:3], v[176:179], v[208:211], v[0:3]
	s_setprio 0
	s_barrier
	s_add_i32 s55, s55, 2
	s_add_u32 s22, s22, 0x100
	s_addc_u32 s23, s23, 0
	s_add_u32 s51, s51, 0x100
	s_addc_u32 s54, s54, 0

; #define PG8_STAGE(bufoff, gbase, voff) do { _Pragma("unroll") for (int _i = 0; _i < 2; ++_i) \
;         __builtin_amdgcn_global_load_lds((const unsigned*)((const char*)(gbase) + (voff)[_i]), (LAS unsigned*)(lds + (bufoff) + ldsw + _i * 8192), 16, 0, 0); } while (0)
; #define PG8_LDA(dst, b, h) do { _Pragma("unroll") for (int m = 0; m < 4; ++m) _Pragma("unroll") for (int k = 0; k < 2; ++k) dst[m][k] = *(const LAS bf16x8*)(lds + PG8_SA(b, h) + aoff + m * 2048 + k * 1024); } while (0)
; #define PG8_LDB(dst, b, h) do { _Pragma("unroll") for (int n = 0; n < 2; ++n) _Pragma("unroll") for (int k = 0; k < 2; ++k) dst[n][k] = *(const LAS bf16x8*)(lds + PG8_SB(b, h) + boff + n * 2048 + k * 1024); } while (0)
; #define PG8_SCHED __builtin_amdgcn_sched_barrier(0)
;     __device__ bool next(int i, Unit& u) const {
;         const long L = (long)i * G + c; if (L >= nwg) return false;
;         int wgid = (int)L; { const int q = nwg / NXCD, r = nwg % NXCD, xcd = wgid % NXCD, off = wgid / NXCD; wgid = (xcd < r ? xcd * (q + 1) : r * (q + 1) + (xcd - r) * q) + off; }
;         const int nig = WGM * nN, gid = wgid / nig, fm = gid * WGM, gsz = (nM - fm) < WGM ? (nM - fm) : WGM;
;         u.pm = fm + ((wgid % nig) % gsz); u.pn = (wgid % nig) / gsz; return true;
; template <class Epi, bool ALIGN_EPI, int K, int LDA, int LDB>
; __device__ __forceinline__ void gemm_phase(LAS unsigned char* lds, const int wid, const Gemm g, const StaticOrder& S, const Epi& E) {
;     ...
;             PG8_LDB(B0, 0, 0); PG8_LDB(B1, 0, 1); PG8_SCHED; PG8_LDA(At, 0, 0); PG8_STAGE(PG8_SA(1, 1), a1 + hA, voffA);
.LBB0_1126:
	ds_read_b128 v[128:131], v175
	ds_read_b128 v[132:135], v175 offset:1024
	ds_read_b128 v[136:139], v175 offset:2048
	ds_read_b128 v[140:143], v175 offset:3072
	ds_read_b128 v[144:147], v176
	ds_read_b128 v[164:167], v176 offset:1024
	ds_read_b128 v[168:171], v176 offset:2048
	ds_read_b128 v[178:181], v176 offset:3072
	ds_read_b128 v[182:185], v177
	ds_read_b128 v[186:189], v177 offset:1024
	ds_read_b128 v[190:193], v177 offset:2048
	ds_read_b128 v[194:197], v177 offset:3072
	ds_read_b128 v[198:201], v177 offset:4096
	ds_read_b128 v[202:205], v177 offset:5120
	ds_read_b128 v[206:209], v177 offset:6144
	ds_read_b128 v[210:213], v177 offset:7168
	s_add_i32 s61, s61, 1
	s_mul_i32 s4, s61, s51
	s_mul_hi_u32 s5, s61, s90
	s_add_i32 s5, s5, s4
	s_mul_i32 s4, s61, s90
	s_add_u32 s4, s4, s2
	s_addc_u32 s5, s5, s0
	v_cmp_gt_i64_e32 vcc, s[4:5], v[162:163]
	v_cmp_lt_i64_e64 s[6:7], s[4:5], v[160:161]
	s_cbranch_vccnz .LBB0_1132
	s_ashr_i32 s5, s4, 31
	s_lshr_b32 s5, s5, 29
	s_add_i32 s24, s4, s5
	s_and_b32 s5, s24, -8
	s_sub_i32 s25, s4, s5
	s_cmp_gt_i32 s25, -1
	s_mov_b64 s[4:5], -1
	s_cbranch_scc0 .LBB0_1129
	s_lshl_b32 s30, s25, 7
	s_mov_b64 s[4:5], 0

; #define PG8_STAGE(bufoff, gbase, voff) do { _Pragma("unroll") for (int _i = 0; _i < 2; ++_i) \
;         __builtin_amdgcn_global_load_lds((const unsigned*)((const char*)(gbase) + (voff)[_i]), (LAS unsigned*)(lds + (bufoff) + ldsw + _i * 8192), 16, 0, 0); } while (0)
; #define PG8_LDA(dst, b, h) do { _Pragma("unroll") for (int m = 0; m < 4; ++m) _Pragma("unroll") for (int k = 0; k < 2; ++k) dst[m][k] = *(const LAS bf16x8*)(lds + PG8_SA(b, h) + aoff + m * 2048 + k * 1024); } while (0)
; #define PG8_LDB(dst, b, h) do { _Pragma("unroll") for (int n = 0; n < 2; ++n) _Pragma("unroll") for (int k = 0; k < 2; ++k) dst[n][k] = *(const LAS bf16x8*)(lds + PG8_SB(b, h) + boff + n * 2048 + k * 1024); } while (0)
; #define PG8_MMA(ai, bj, At, Bt) do { __builtin_amdgcn_s_setprio(1); _Pragma("unroll") for (int m = 0; m < 4; ++m) _Pragma("unroll") for (int n = 0; n < 2; ++n) _Pragma("unroll") for (int k = 0; k < 2; ++k) \
;         acc[ai][bj][m][n] = __builtin_amdgcn_mfma_f32_16x16x32_bf16(Bt[n][k], At[m][k], acc[ai][bj][m][n], 0, 0, 0); __builtin_amdgcn_s_setprio(0); } while (0)
; #define PG8_WAIT_V(n) asm volatile("s_waitcnt vmcnt(" #n ")" ::: "memory")
; template <class Epi, bool ALIGN_EPI, int K, int LDA, int LDB>
; __device__ __forceinline__ void gemm_phase(LAS unsigned char* lds, const int wid, const Gemm g, const StaticOrder& S, const Epi& E) {
;     ...
;         const char* nA = has_next ? (const char*)g.A + (size_t)nxt.pm * tA : cA; const char* nB = has_next ? (const char*)g.Bt + (size_t)nxt.pn * tB : cB;
;         for (int t = 0; t < nt; t += 2) {
;             const bool last = (t == nt - 2);
;             const char* a1 = cA + (size_t)(t + 1) * kstep;
;             const char* a2 = last ? nA : cA + (size_t)(t + 2) * kstep; const char* b2 = last ? nB : cB + (size_t)(t + 2) * kstep;
;             const char* a3 = a2 + kstep; const char* b3 = b2 + kstep;
;             PG8_LDB(B0, 0, 0); PG8_LDB(B1, 0, 1); PG8_SCHED; PG8_LDA(At, 0, 0); PG8_STAGE(PG8_SA(1, 1), a1 + hA, voffA);
;             PG8_WAIT_V(8); PG8_WAIT_L(0); PG8_BAR; PG8_MMA(0, 0, At, B0); PG8_MMA(0, 1, At, B1); PG8_BAR; PG8_SCHED;
;             PG8_LDA(At, 0, 1); PG8_STAGE(PG8_SB(0, 0), b2, voffB); PG8_STAGE(PG8_SB(0, 1), b2 + hB, voffB); PG8_STAGE(PG8_SA(0, 0), a2, voffA);
;             PG8_WAIT_V(8); PG8_WAIT_L(0); PG8_BAR; PG8_MMA(1, 0, At, B0); PG8_MMA(1, 1, At, B1); PG8_BAR; PG8_SCHED;
.LBB0_1136:
	s_add_u32 s65, s28, 0x100
	s_addc_u32 s66, s29, 0
	s_mov_b32 s67, -2
	s_add_u32 s28, s26, 0x100
	s_addc_u32 s29, s27, 0
	s_cmp_eq_u32 s67, 40
	s_cselect_b32 s35, s7, s29
	s_cselect_b32 s34, s6, s28
	s_cselect_b32 s31, s25, s66
	s_cselect_b32 s30, s24, s65
	s_add_i32 m0, s36, 0xc000
	global_load_lds_dwordx4 v156, s[26:27]
	s_add_i32 m0, s36, 0xe000
	s_nop 0
	global_load_lds_dwordx4 v158, s[26:27]
	s_waitcnt vmcnt(8)
	s_waitcnt lgkmcnt(0)
	s_barrier
	s_setprio 1
	s_waitcnt lgkmcnt(0)
	v_mfma_f32_16x16x32_bf16 v[124:127], v[128:131], v[182:185], 0
	v_mfma_f32_16x16x32_bf16 v[116:119], v[136:139], v[182:185], 0
	v_mfma_f32_16x16x32_bf16 v[120:123], v[128:131], v[190:193], 0
	v_mfma_f32_16x16x32_bf16 v[112:115], v[136:139], v[190:193], 0
	v_mfma_f32_16x16x32_bf16 v[92:95], v[128:131], v[198:201], 0
	v_mfma_f32_16x16x32_bf16 v[88:91], v[136:139], v[198:201], 0
	v_mfma_f32_16x16x32_bf16 v[76:79], v[128:131], v[206:209], 0
	v_mfma_f32_16x16x32_bf16 v[72:75], v[136:139], v[206:209], 0
	v_mfma_f32_16x16x32_bf16 v[124:127], v[132:135], v[186:189], v[124:127]
	v_mfma_f32_16x16x32_bf16 v[116:119], v[140:143], v[186:189], v[116:119]
	v_mfma_f32_16x16x32_bf16 v[120:123], v[132:135], v[194:197], v[120:123]
	v_mfma_f32_16x16x32_bf16 v[112:115], v[140:143], v[194:197], v[112:115]
	v_mfma_f32_16x16x32_bf16 v[92:95], v[132:135], v[202:205], v[92:95]
	v_mfma_f32_16x16x32_bf16 v[88:91], v[140:143], v[202:205], v[88:91]
	v_mfma_f32_16x16x32_bf16 v[76:79], v[132:135], v[210:213], v[76:79]
	v_mfma_f32_16x16x32_bf16 v[72:75], v[140:143], v[210:213], v[72:75]
	v_mfma_f32_16x16x32_bf16 v[108:111], v[144:147], v[182:185], 0
	v_mfma_f32_16x16x32_bf16 v[104:107], v[168:171], v[182:185], 0
	v_mfma_f32_16x16x32_bf16 v[100:103], v[144:147], v[190:193], 0
	v_mfma_f32_16x16x32_bf16 v[96:99], v[168:171], v[190:193], 0
	v_mfma_f32_16x16x32_bf16 v[84:87], v[144:147], v[198:201], 0
	v_mfma_f32_16x16x32_bf16 v[80:83], v[168:171], v[198:201], 0
	v_mfma_f32_16x16x32_bf16 v[68:71], v[144:147], v[206:209], 0
	v_mfma_f32_16x16x32_bf16 v[64:67], v[168:171], v[206:209], 0
	v_mfma_f32_16x16x32_bf16 v[108:111], v[164:167], v[186:189], v[108:111]
	v_mfma_f32_16x16x32_bf16 v[104:107], v[178:181], v[186:189], v[104:107]
	v_mfma_f32_16x16x32_bf16 v[100:103], v[164:167], v[194:197], v[100:103]
	v_mfma_f32_16x16x32_bf16 v[96:99], v[178:181], v[194:197], v[96:99]
	v_mfma_f32_16x16x32_bf16 v[84:87], v[164:167], v[202:205], v[84:87]
	v_mfma_f32_16x16x32_bf16 v[80:83], v[178:181], v[202:205], v[80:83]
	v_mfma_f32_16x16x32_bf16 v[68:71], v[164:167], v[210:213], v[68:71]
	v_mfma_f32_16x16x32_bf16 v[64:67], v[178:181], v[210:213], v[64:67]
	s_setprio 0
	s_barrier
	s_add_u32 s98, s30, s12
	s_addc_u32 s99, s31, s13
	s_add_u32 s100, s34, s12
	s_addc_u32 s101, s35, s13
	s_add_i32 s26, s54, s33
	s_mov_b32 m0, s26
	ds_read_b128 v[182:185], v177 offset:16384
	ds_read_b128 v[186:189], v177 offset:17408
	ds_read_b128 v[190:193], v177 offset:18432
	ds_read_b128 v[194:197], v177 offset:19456
	ds_read_b128 v[198:201], v177 offset:20480
	ds_read_b128 v[202:205], v177 offset:21504
	ds_read_b128 v[206:209], v177 offset:22528
	ds_read_b128 v[210:213], v177 offset:23552
	global_load_lds_dwordx4 v150, s[30:31]
	s_add_i32 m0, s26, 0x2000
	s_add_u32 s26, s30, 0xb0000
	s_addc_u32 s27, s31, 0
	s_add_i32 s52, s55, s33
	global_load_lds_dwordx4 v154, s[30:31]
	s_mov_b32 m0, s52
	s_nop 0
	global_load_lds_dwordx4 v150, s[26:27]
	s_add_i32 m0, s52, 0x2000
	s_nop 0
	global_load_lds_dwordx4 v154, s[26:27]
	s_mov_b32 m0, s36
	s_nop 0
	global_load_lds_dwordx4 v148, s[34:35]
	s_mov_b32 m0, s37
	s_nop 0
	global_load_lds_dwordx4 v152, s[34:35]
	s_waitcnt vmcnt(8)
	s_waitcnt lgkmcnt(0)
	s_barrier
	s_setprio 1
	s_waitcnt lgkmcnt(0)
	v_mfma_f32_16x16x32_bf16 v[60:63], v[128:131], v[182:185], 0
	v_mfma_f32_16x16x32_bf16 v[56:59], v[136:139], v[182:185], 0
	v_mfma_f32_16x16x32_bf16 v[44:47], v[128:131], v[190:193], 0
	v_mfma_f32_16x16x32_bf16 v[40:43], v[136:139], v[190:193], 0
	v_mfma_f32_16x16x32_bf16 v[36:39], v[128:131], v[198:201], 0
	v_mfma_f32_16x16x32_bf16 v[32:35], v[136:139], v[198:201], 0
	v_mfma_f32_16x16x32_bf16 v[20:23], v[128:131], v[206:209], 0
	v_mfma_f32_16x16x32_bf16 v[16:19], v[136:139], v[206:209], 0
	v_mfma_f32_16x16x32_bf16 v[60:63], v[132:135], v[186:189], v[60:63]
	v_mfma_f32_16x16x32_bf16 v[56:59], v[140:143], v[186:189], v[56:59]
	v_mfma_f32_16x16x32_bf16 v[44:47], v[132:135], v[194:197], v[44:47]
	v_mfma_f32_16x16x32_bf16 v[40:43], v[140:143], v[194:197], v[40:43]
	v_mfma_f32_16x16x32_bf16 v[36:39], v[132:135], v[202:205], v[36:39]
	v_mfma_f32_16x16x32_bf16 v[32:35], v[140:143], v[202:205], v[32:35]
	v_mfma_f32_16x16x32_bf16 v[20:23], v[132:135], v[210:213], v[20:23]
	v_mfma_f32_16x16x32_bf16 v[16:19], v[140:143], v[210:213], v[16:19]
	v_mfma_f32_16x16x32_bf16 v[52:55], v[144:147], v[182:185], 0
	v_mfma_f32_16x16x32_bf16 v[48:51], v[168:171], v[182:185], 0
	v_mfma_f32_16x16x32_bf16 v[28:31], v[144:147], v[190:193], 0
	v_mfma_f32_16x16x32_bf16 v[24:27], v[168:171], v[190:193], 0
	v_mfma_f32_16x16x32_bf16 v[12:15], v[144:147], v[198:201], 0
	v_mfma_f32_16x16x32_bf16 v[8:11], v[168:171], v[198:201], 0
	v_mfma_f32_16x16x32_bf16 v[4:7], v[144:147], v[206:209], 0
	v_mfma_f32_16x16x32_bf16 v[0:3], v[168:171], v[206:209], 0
	v_mfma_f32_16x16x32_bf16 v[52:55], v[164:167], v[186:189], v[52:55]
	v_mfma_f32_16x16x32_bf16 v[48:51], v[178:181], v[186:189], v[48:51]
	v_mfma_f32_16x16x32_bf16 v[28:31], v[164:167], v[194:197], v[28:31]
	v_mfma_f32_16x16x32_bf16 v[24:27], v[178:181], v[194:197], v[24:27]
	v_mfma_f32_16x16x32_bf16 v[12:15], v[164:167], v[202:205], v[12:15]
	v_mfma_f32_16x16x32_bf16 v[8:11], v[178:181], v[202:205], v[8:11]
	v_mfma_f32_16x16x32_bf16 v[4:7], v[164:167], v[210:213], v[4:7]
	v_mfma_f32_16x16x32_bf16 v[0:3], v[178:181], v[210:213], v[0:3]
	s_setprio 0
	s_barrier
; #define PG8_STAGE(bufoff, gbase, voff) do { _Pragma("unroll") for (int _i = 0; _i < 2; ++_i) \
;         __builtin_amdgcn_global_load_lds((const unsigned*)((const char*)(gbase) + (voff)[_i]), (LAS unsigned*)(lds + (bufoff) + ldsw + _i * 8192), 16, 0, 0); } while (0)
; #define PG8_LDA(dst, b, h) do { _Pragma("unroll") for (int m = 0; m < 4; ++m) _Pragma("unroll") for (int k = 0; k < 2; ++k) dst[m][k] = *(const LAS bf16x8*)(lds + PG8_SA(b, h) + aoff + m * 2048 + k * 1024); } while (0)
; #define PG8_LDB(dst, b, h) do { _Pragma("unroll") for (int n = 0; n < 2; ++n) _Pragma("unroll") for (int k = 0; k < 2; ++k) dst[n][k] = *(const LAS bf16x8*)(lds + PG8_SB(b, h) + boff + n * 2048 + k * 1024); } while (0)
; #define PG8_MMA(ai, bj, At, Bt) do { __builtin_amdgcn_s_setprio(1); _Pragma("unroll") for (int m = 0; m < 4; ++m) _Pragma("unroll") for (int n = 0; n < 2; ++n) _Pragma("unroll") for (int k = 0; k < 2; ++k) \
;         acc[ai][bj][m][n] = __builtin_amdgcn_mfma_f32_16x16x32_bf16(Bt[n][k], At[m][k], acc[ai][bj][m][n], 0, 0, 0); __builtin_amdgcn_s_setprio(0); } while (0)
; #define PG8_WAIT_V(n) asm volatile("s_waitcnt vmcnt(" #n ")" ::: "memory")
; #define PG8_WAIT_L(n) asm volatile("s_waitcnt lgkmcnt(" #n ")" ::: "memory")
; #define PG8_BAR __builtin_amdgcn_s_barrier()
; #define PG8_SCHED __builtin_amdgcn_sched_barrier(0)
; template <class Epi, bool ALIGN_EPI, int K, int LDA, int LDB>
; __device__ __forceinline__ void gemm_phase(LAS unsigned char* lds, const int wid, const Gemm g, const StaticOrder& S, const Epi& E) {
;     ...
;             PG8_LDB(B0, 1, 0); PG8_LDB(B1, 1, 1); PG8_SCHED; PG8_LDA(At, 1, 0); PG8_STAGE(PG8_SA(0, 1), a2 + hA, voffA);
;             PG8_WAIT_V(8); PG8_WAIT_L(0); PG8_BAR; PG8_MMA(0, 0, At, B0); PG8_MMA(0, 1, At, B1); PG8_BAR; PG8_SCHED;
;             PG8_LDA(At, 1, 1); PG8_STAGE(PG8_SB(1, 0), b3, voffB); PG8_STAGE(PG8_SB(1, 1), b3 + hB, voffB); PG8_STAGE(PG8_SA(1, 0), a3, voffA);
;             PG8_WAIT_V(8); PG8_WAIT_L(0); PG8_BAR; PG8_MMA(1, 0, At, B0); PG8_MMA(1, 1, At, B1); PG8_BAR; PG8_SCHED;
	s_add_i32 s52, 0, 0x18000
	s_add_i32 s53, 0, 0x1c000
	v_add_u32_e32 v140, s52, v174
	v_add_u32_e32 v178, s53, v174
	ds_read_b128 v[128:131], v140
	ds_read_b128 v[132:135], v140 offset:1024
	ds_read_b128 v[136:139], v140 offset:2048
	ds_read_b128 v[140:143], v140 offset:3072
	ds_read_b128 v[144:147], v178
	ds_read_b128 v[164:167], v178 offset:1024
	ds_read_b128 v[168:171], v178 offset:2048
	ds_read_b128 v[178:181], v178 offset:3072
	s_add_u32 s26, s34, 0xb0000
	s_addc_u32 s27, s35, 0
	s_mov_b32 m0, s38
	ds_read_b128 v[182:185], v177 offset:32768
	ds_read_b128 v[186:189], v177 offset:33792
	ds_read_b128 v[190:193], v177 offset:34816
	ds_read_b128 v[194:197], v177 offset:35840
	ds_read_b128 v[198:201], v177 offset:36864
	ds_read_b128 v[202:205], v177 offset:37888
	ds_read_b128 v[206:209], v177 offset:38912
	ds_read_b128 v[210:213], v177 offset:39936
	global_load_lds_dwordx4 v148, s[26:27]
	s_mov_b32 m0, s39
	s_nop 0
	global_load_lds_dwordx4 v152, s[26:27]
	s_waitcnt vmcnt(8)
	s_waitcnt lgkmcnt(0)
	s_barrier
	s_setprio 1
	s_waitcnt lgkmcnt(0)
	v_mfma_f32_16x16x32_bf16 v[124:127], v[128:131], v[182:185], v[124:127]
	v_mfma_f32_16x16x32_bf16 v[116:119], v[136:139], v[182:185], v[116:119]
	v_mfma_f32_16x16x32_bf16 v[120:123], v[128:131], v[190:193], v[120:123]
	v_mfma_f32_16x16x32_bf16 v[112:115], v[136:139], v[190:193], v[112:115]
	v_mfma_f32_16x16x32_bf16 v[92:95], v[128:131], v[198:201], v[92:95]
	v_mfma_f32_16x16x32_bf16 v[88:91], v[136:139], v[198:201], v[88:91]
	v_mfma_f32_16x16x32_bf16 v[76:79], v[128:131], v[206:209], v[76:79]
	v_mfma_f32_16x16x32_bf16 v[72:75], v[136:139], v[206:209], v[72:75]
	v_mfma_f32_16x16x32_bf16 v[124:127], v[132:135], v[186:189], v[124:127]
	v_mfma_f32_16x16x32_bf16 v[116:119], v[140:143], v[186:189], v[116:119]
	v_mfma_f32_16x16x32_bf16 v[120:123], v[132:135], v[194:197], v[120:123]
	v_mfma_f32_16x16x32_bf16 v[112:115], v[140:143], v[194:197], v[112:115]
	v_mfma_f32_16x16x32_bf16 v[92:95], v[132:135], v[202:205], v[92:95]
	v_mfma_f32_16x16x32_bf16 v[88:91], v[140:143], v[202:205], v[88:91]
	v_mfma_f32_16x16x32_bf16 v[76:79], v[132:135], v[210:213], v[76:79]
	v_mfma_f32_16x16x32_bf16 v[72:75], v[140:143], v[210:213], v[72:75]
	v_mfma_f32_16x16x32_bf16 v[108:111], v[144:147], v[182:185], v[108:111]
	v_mfma_f32_16x16x32_bf16 v[104:107], v[168:171], v[182:185], v[104:107]
	v_mfma_f32_16x16x32_bf16 v[100:103], v[144:147], v[190:193], v[100:103]
	v_mfma_f32_16x16x32_bf16 v[96:99], v[168:171], v[190:193], v[96:99]
	v_mfma_f32_16x16x32_bf16 v[84:87], v[144:147], v[198:201], v[84:87]
	v_mfma_f32_16x16x32_bf16 v[80:83], v[168:171], v[198:201], v[80:83]
	v_mfma_f32_16x16x32_bf16 v[68:71], v[144:147], v[206:209], v[68:71]
	v_mfma_f32_16x16x32_bf16 v[64:67], v[168:171], v[206:209], v[64:67]
	v_mfma_f32_16x16x32_bf16 v[108:111], v[164:167], v[186:189], v[108:111]
	v_mfma_f32_16x16x32_bf16 v[104:107], v[178:181], v[186:189], v[104:107]
	v_mfma_f32_16x16x32_bf16 v[100:103], v[164:167], v[194:197], v[100:103]
	v_mfma_f32_16x16x32_bf16 v[96:99], v[178:181], v[194:197], v[96:99]
	v_mfma_f32_16x16x32_bf16 v[84:87], v[164:167], v[202:205], v[84:87]
	v_mfma_f32_16x16x32_bf16 v[80:83], v[178:181], v[202:205], v[80:83]
	v_mfma_f32_16x16x32_bf16 v[68:71], v[164:167], v[210:213], v[68:71]
	v_mfma_f32_16x16x32_bf16 v[64:67], v[178:181], v[210:213], v[64:67]
	s_setprio 0
	s_barrier
	s_add_i32 s26, s52, s33
	s_mov_b32 m0, s26
	ds_read_b128 v[182:185], v177 offset:49152
	ds_read_b128 v[186:189], v177 offset:50176
	ds_read_b128 v[190:193], v177 offset:51200
	ds_read_b128 v[194:197], v177 offset:52224
	ds_read_b128 v[198:201], v177 offset:53248
	ds_read_b128 v[202:205], v177 offset:54272
	ds_read_b128 v[206:209], v177 offset:55296
	ds_read_b128 v[210:213], v177 offset:56320
	global_load_lds_dwordx4 v150, s[98:99]
	s_add_i32 m0, s26, 0x2000
	s_add_u32 s26, s30, 0xb0080
	s_addc_u32 s27, s31, 0
	s_add_i32 s30, s53, s33
	global_load_lds_dwordx4 v154, s[98:99]
	s_mov_b32 m0, s30
	s_nop 0
	global_load_lds_dwordx4 v150, s[26:27]
	s_add_i32 m0, s30, 0x2000
	s_nop 0
	global_load_lds_dwordx4 v154, s[26:27]
	s_mov_b32 m0, s48
	s_nop 0
	global_load_lds_dwordx4 v148, s[100:101]
	s_mov_b32 m0, s49
	s_nop 0
	global_load_lds_dwordx4 v152, s[100:101]
	s_waitcnt vmcnt(8)
	s_waitcnt lgkmcnt(0)
	s_barrier
	s_setprio 1
	s_waitcnt lgkmcnt(0)
	v_mfma_f32_16x16x32_bf16 v[60:63], v[128:131], v[182:185], v[60:63]
	v_mfma_f32_16x16x32_bf16 v[56:59], v[136:139], v[182:185], v[56:59]
	v_mfma_f32_16x16x32_bf16 v[44:47], v[128:131], v[190:193], v[44:47]
	v_mfma_f32_16x16x32_bf16 v[40:43], v[136:139], v[190:193], v[40:43]
	v_mfma_f32_16x16x32_bf16 v[36:39], v[128:131], v[198:201], v[36:39]
	v_mfma_f32_16x16x32_bf16 v[32:35], v[136:139], v[198:201], v[32:35]
	v_mfma_f32_16x16x32_bf16 v[20:23], v[128:131], v[206:209], v[20:23]
	v_mfma_f32_16x16x32_bf16 v[16:19], v[136:139], v[206:209], v[16:19]
	v_mfma_f32_16x16x32_bf16 v[60:63], v[132:135], v[186:189], v[60:63]
	v_mfma_f32_16x16x32_bf16 v[56:59], v[140:143], v[186:189], v[56:59]
	v_mfma_f32_16x16x32_bf16 v[44:47], v[132:135], v[194:197], v[44:47]
	v_mfma_f32_16x16x32_bf16 v[40:43], v[140:143], v[194:197], v[40:43]
	v_mfma_f32_16x16x32_bf16 v[36:39], v[132:135], v[202:205], v[36:39]
	v_mfma_f32_16x16x32_bf16 v[32:35], v[140:143], v[202:205], v[32:35]
	v_mfma_f32_16x16x32_bf16 v[20:23], v[132:135], v[210:213], v[20:23]
	v_mfma_f32_16x16x32_bf16 v[16:19], v[140:143], v[210:213], v[16:19]
	v_mfma_f32_16x16x32_bf16 v[52:55], v[144:147], v[182:185], v[52:55]
	v_mfma_f32_16x16x32_bf16 v[48:51], v[168:171], v[182:185], v[48:51]
	v_mfma_f32_16x16x32_bf16 v[28:31], v[144:147], v[190:193], v[28:31]
	v_mfma_f32_16x16x32_bf16 v[24:27], v[168:171], v[190:193], v[24:27]
	v_mfma_f32_16x16x32_bf16 v[12:15], v[144:147], v[198:201], v[12:15]
	v_mfma_f32_16x16x32_bf16 v[8:11], v[168:171], v[198:201], v[8:11]
	v_mfma_f32_16x16x32_bf16 v[4:7], v[144:147], v[206:209], v[4:7]
	v_mfma_f32_16x16x32_bf16 v[0:3], v[168:171], v[206:209], v[0:3]
	v_mfma_f32_16x16x32_bf16 v[52:55], v[164:167], v[186:189], v[52:55]
	v_mfma_f32_16x16x32_bf16 v[48:51], v[178:181], v[186:189], v[48:51]
	v_mfma_f32_16x16x32_bf16 v[28:31], v[164:167], v[194:197], v[28:31]
	v_mfma_f32_16x16x32_bf16 v[24:27], v[178:181], v[194:197], v[24:27]
	v_mfma_f32_16x16x32_bf16 v[12:15], v[164:167], v[202:205], v[12:15]
	v_mfma_f32_16x16x32_bf16 v[8:11], v[178:181], v[202:205], v[8:11]
	v_mfma_f32_16x16x32_bf16 v[4:7], v[164:167], v[210:213], v[4:7]
	v_mfma_f32_16x16x32_bf16 v[0:3], v[178:181], v[210:213], v[0:3]
	s_setprio 0
	s_barrier
	s_add_i32 s67, s67, 2
	s_add_u32 s65, s65, 0x100
	s_addc_u32 s66, s66, 0
	s_mov_b64 s[26:27], s[28:29]

; #define PG8_STAGE(bufoff, gbase, voff) do { _Pragma("unroll") for (int _i = 0; _i < 2; ++_i) \
;         __builtin_amdgcn_global_load_lds((const unsigned*)((const char*)(gbase) + (voff)[_i]), (LAS unsigned*)(lds + (bufoff) + ldsw + _i * 8192), 16, 0, 0); } while (0)
; #define PG8_LDA(dst, b, h) do { _Pragma("unroll") for (int m = 0; m < 4; ++m) _Pragma("unroll") for (int k = 0; k < 2; ++k) dst[m][k] = *(const LAS bf16x8*)(lds + PG8_SA(b, h) + aoff + m * 2048 + k * 1024); } while (0)
; #define PG8_LDB(dst, b, h) do { _Pragma("unroll") for (int n = 0; n < 2; ++n) _Pragma("unroll") for (int k = 0; k < 2; ++k) dst[n][k] = *(const LAS bf16x8*)(lds + PG8_SB(b, h) + boff + n * 2048 + k * 1024); } while (0)
; #define PG8_SCHED __builtin_amdgcn_sched_barrier(0)
;     __device__ bool next(int i, Unit& u) const {
;         const long L = (long)i * G + c; if (L >= nwg) return false;
;         int wgid = (int)L; { const int q = nwg / NXCD, r = nwg % NXCD, xcd = wgid % NXCD, off = wgid / NXCD; wgid = (xcd < r ? xcd * (q + 1) : r * (q + 1) + (xcd - r) * q) + off; }
;         const int nig = WGM * nN, gid = wgid / nig, fm = gid * WGM, gsz = (nM - fm) < WGM ? (nM - fm) : WGM;
;         u.pm = fm + ((wgid % nig) % gsz); u.pn = (wgid % nig) / gsz; return true;
; template <class Epi, bool ALIGN_EPI, int K, int LDA, int LDB>
; __device__ __forceinline__ void gemm_phase(LAS unsigned char* lds, const int wid, const Gemm g, const StaticOrder& S, const Epi& E) {
;     ...
;             PG8_LDB(B0, 0, 0); PG8_LDB(B1, 0, 1); PG8_SCHED; PG8_LDA(At, 0, 0); PG8_STAGE(PG8_SA(1, 1), a1 + hA, voffA);
.LBB0_1272:
	ds_read_b128 v[144:147], v151
	ds_read_b128 v[154:157], v151 offset:1024
	ds_read_b128 v[158:161], v151 offset:2048
	ds_read_b128 v[162:165], v151 offset:3072
	ds_read_b128 v[166:169], v152
	ds_read_b128 v[170:173], v152 offset:1024
	ds_read_b128 v[174:177], v152 offset:2048
	ds_read_b128 v[178:181], v152 offset:3072
	ds_read_b128 v[182:185], v153
	ds_read_b128 v[186:189], v153 offset:1024
	ds_read_b128 v[190:193], v153 offset:2048
	ds_read_b128 v[194:197], v153 offset:3072
	ds_read_b128 v[198:201], v153 offset:4096
	ds_read_b128 v[202:205], v153 offset:5120
	ds_read_b128 v[206:209], v153 offset:6144
	ds_read_b128 v[210:213], v153 offset:7168
	s_add_i32 s43, s43, 1
	s_mul_i32 s4, s43, s51
	s_mul_hi_u32 s5, s43, s90
	s_add_i32 s5, s5, s4
	s_mul_i32 s4, s43, s90
	s_add_u32 s26, s4, s2
	s_addc_u32 s27, s5, s54
	v_cmp_gt_i64_e32 vcc, s[26:27], v[142:143]
	v_cmp_lt_i64_e64 s[4:5], s[26:27], v[140:141]
	s_cbranch_vccnz .LBB0_1278
	s_ashr_i32 s7, s26, 31
	s_lshr_b32 s7, s7, 29
	s_add_i32 s7, s26, s7
	s_and_b32 s22, s7, -8
	s_sub_i32 s24, s26, s22
	s_cmp_gt_i32 s24, -1
	s_mov_b64 s[22:23], -1
	s_cbranch_scc0 .LBB0_1275
	s_lshl_b32 s25, s24, 9
	s_mov_b64 s[22:23], 0

; #define PG8_STAGE(bufoff, gbase, voff) do { _Pragma("unroll") for (int _i = 0; _i < 2; ++_i) \
;         __builtin_amdgcn_global_load_lds((const unsigned*)((const char*)(gbase) + (voff)[_i]), (LAS unsigned*)(lds + (bufoff) + ldsw + _i * 8192), 16, 0, 0); } while (0)
; #define PG8_LDA(dst, b, h) do { _Pragma("unroll") for (int m = 0; m < 4; ++m) _Pragma("unroll") for (int k = 0; k < 2; ++k) dst[m][k] = *(const LAS bf16x8*)(lds + PG8_SA(b, h) + aoff + m * 2048 + k * 1024); } while (0)
; #define PG8_LDB(dst, b, h) do { _Pragma("unroll") for (int n = 0; n < 2; ++n) _Pragma("unroll") for (int k = 0; k < 2; ++k) dst[n][k] = *(const LAS bf16x8*)(lds + PG8_SB(b, h) + boff + n * 2048 + k * 1024); } while (0)
; #define PG8_MMA(ai, bj, At, Bt) do { __builtin_amdgcn_s_setprio(1); _Pragma("unroll") for (int m = 0; m < 4; ++m) _Pragma("unroll") for (int n = 0; n < 2; ++n) _Pragma("unroll") for (int k = 0; k < 2; ++k) \
;         acc[ai][bj][m][n] = __builtin_amdgcn_mfma_f32_16x16x32_bf16(Bt[n][k], At[m][k], acc[ai][bj][m][n], 0, 0, 0); __builtin_amdgcn_s_setprio(0); } while (0)
; template <class Epi, bool ALIGN_EPI, int K, int LDA, int LDB>
; __device__ __forceinline__ void gemm_phase(LAS unsigned char* lds, const int wid, const Gemm g, const StaticOrder& S, const Epi& E) {
;     ...
;         const bool has_next = S.next(ui + 1, nxt);
;         const char* nA = has_next ? (const char*)g.A + (size_t)nxt.pm * tA : cA; const char* nB = has_next ? (const char*)g.Bt + (size_t)nxt.pn * tB : cB;
;         for (int t = 0; t < nt; t += 2) {
;             const bool last = (t == nt - 2);
;             const char* a1 = cA + (size_t)(t + 1) * kstep;
;             const char* a2 = last ? nA : cA + (size_t)(t + 2) * kstep; const char* b2 = last ? nB : cB + (size_t)(t + 2) * kstep;
;             const char* a3 = a2 + kstep; const char* b3 = b2 + kstep;
;             PG8_LDB(B0, 0, 0); PG8_LDB(B1, 0, 1); PG8_SCHED; PG8_LDA(At, 0, 0); PG8_STAGE(PG8_SA(1, 1), a1 + hA, voffA);
;             PG8_WAIT_V(8); PG8_WAIT_L(0); PG8_BAR; PG8_MMA(0, 0, At, B0); PG8_MMA(0, 1, At, B1); PG8_BAR; PG8_SCHED;
;             PG8_LDA(At, 0, 1); PG8_STAGE(PG8_SB(0, 0), b2, voffB); PG8_STAGE(PG8_SB(0, 1), b2 + hB, voffB); PG8_STAGE(PG8_SA(0, 0), a2, voffA);
;             PG8_WAIT_V(8); PG8_WAIT_L(0); PG8_BAR; PG8_MMA(1, 0, At, B0); PG8_MMA(1, 1, At, B1); PG8_BAR; PG8_SCHED;
.LBB0_1278:
	s_ashr_i32 s25, s24, 31
	s_lshl_b64 s[26:27], s[24:25], 19
	v_readlane_b32 s7, v254, 0
	s_add_u32 s26, s7, s26
	v_readlane_b32 s7, v254, 1
	s_addc_u32 s27, s7, s27
	s_and_b64 s[28:29], s[4:5], exec
	s_cselect_b32 s7, s27, s35
	s_cselect_b32 s25, s26, s34
	s_ashr_i32 s23, s22, 31
	s_lshl_b64 s[28:29], s[22:23], 19
	s_add_u32 s28, s0, s28
	s_addc_u32 s29, s1, s29
	s_and_b64 s[38:39], s[4:5], exec
	s_cselect_b32 s23, s29, s37
	s_cselect_b32 s42, s28, s36
	s_add_u32 s34, s34, 0x40080
	s_addc_u32 s35, s35, 0
	s_add_u32 s59, s36, 0x100
	s_addc_u32 s60, s37, 0
	s_mov_b32 s61, -2
	s_add_u32 s36, s34, 0xfffc0080
	s_addc_u32 s37, s35, -1
	s_cmp_eq_u32 s61, 12
	s_cselect_b32 s39, s7, s37
	s_cselect_b32 s38, s25, s36
	s_cselect_b32 s37, s23, s60
	s_cselect_b32 s36, s42, s59
	s_add_i32 m0, s31, 0xc000
	global_load_lds_dwordx4 v136, s[34:35]
	s_add_i32 m0, s31, 0xe000
	s_nop 0
	global_load_lds_dwordx4 v138, s[34:35]
	s_waitcnt vmcnt(8)
	s_waitcnt lgkmcnt(0)
	s_barrier
	s_setprio 1
	s_waitcnt lgkmcnt(0)
	v_mfma_f32_16x16x32_bf16 v[124:127], v[144:147], v[182:185], 0
	v_mfma_f32_16x16x32_bf16 v[120:123], v[158:161], v[182:185], 0
	v_mfma_f32_16x16x32_bf16 v[108:111], v[144:147], v[190:193], 0
	v_mfma_f32_16x16x32_bf16 v[104:107], v[158:161], v[190:193], 0
	v_mfma_f32_16x16x32_bf16 v[92:95], v[144:147], v[198:201], 0
	v_mfma_f32_16x16x32_bf16 v[88:91], v[158:161], v[198:201], 0
	v_mfma_f32_16x16x32_bf16 v[76:79], v[144:147], v[206:209], 0
	v_mfma_f32_16x16x32_bf16 v[72:75], v[158:161], v[206:209], 0
	v_mfma_f32_16x16x32_bf16 v[124:127], v[154:157], v[186:189], v[124:127]
	v_mfma_f32_16x16x32_bf16 v[120:123], v[162:165], v[186:189], v[120:123]
	v_mfma_f32_16x16x32_bf16 v[108:111], v[154:157], v[194:197], v[108:111]
	v_mfma_f32_16x16x32_bf16 v[104:107], v[162:165], v[194:197], v[104:107]
	v_mfma_f32_16x16x32_bf16 v[92:95], v[154:157], v[202:205], v[92:95]
	v_mfma_f32_16x16x32_bf16 v[88:91], v[162:165], v[202:205], v[88:91]
	v_mfma_f32_16x16x32_bf16 v[76:79], v[154:157], v[210:213], v[76:79]
	v_mfma_f32_16x16x32_bf16 v[72:75], v[162:165], v[210:213], v[72:75]
	v_mfma_f32_16x16x32_bf16 v[116:119], v[166:169], v[182:185], 0
	v_mfma_f32_16x16x32_bf16 v[112:115], v[174:177], v[182:185], 0
	v_mfma_f32_16x16x32_bf16 v[100:103], v[166:169], v[190:193], 0
	v_mfma_f32_16x16x32_bf16 v[96:99], v[174:177], v[190:193], 0
	v_mfma_f32_16x16x32_bf16 v[84:87], v[166:169], v[198:201], 0
	v_mfma_f32_16x16x32_bf16 v[80:83], v[174:177], v[198:201], 0
	v_mfma_f32_16x16x32_bf16 v[68:71], v[166:169], v[206:209], 0
	v_mfma_f32_16x16x32_bf16 v[64:67], v[174:177], v[206:209], 0
	v_mfma_f32_16x16x32_bf16 v[116:119], v[170:173], v[186:189], v[116:119]
	v_mfma_f32_16x16x32_bf16 v[112:115], v[178:181], v[186:189], v[112:115]
	v_mfma_f32_16x16x32_bf16 v[100:103], v[170:173], v[194:197], v[100:103]
	v_mfma_f32_16x16x32_bf16 v[96:99], v[178:181], v[194:197], v[96:99]
	v_mfma_f32_16x16x32_bf16 v[84:87], v[170:173], v[202:205], v[84:87]
	v_mfma_f32_16x16x32_bf16 v[80:83], v[178:181], v[202:205], v[80:83]
	v_mfma_f32_16x16x32_bf16 v[68:71], v[170:173], v[210:213], v[68:71]
	v_mfma_f32_16x16x32_bf16 v[64:67], v[178:181], v[210:213], v[64:67]
	s_setprio 0
	s_barrier
	s_add_u32 s98, s36, s12
	s_addc_u32 s99, s37, s13
	s_add_u32 s100, s38, s12
	s_addc_u32 s101, s39, s13
	s_add_i32 s52, s57, s3
	s_mov_b32 m0, s52
	ds_read_b128 v[182:185], v153 offset:16384
	ds_read_b128 v[186:189], v153 offset:17408
	ds_read_b128 v[190:193], v153 offset:18432
	ds_read_b128 v[194:197], v153 offset:19456
	ds_read_b128 v[198:201], v153 offset:20480
	ds_read_b128 v[202:205], v153 offset:21504
	ds_read_b128 v[206:209], v153 offset:22528
	ds_read_b128 v[210:213], v153 offset:23552
	global_load_lds_dwordx4 v130, s[36:37]
	s_add_i32 m0, s52, 0x2000
	s_add_u32 s62, s36, 0x40000
	s_addc_u32 s63, s37, 0
	s_add_i32 s52, s58, s3
	global_load_lds_dwordx4 v134, s[36:37]
	s_mov_b32 m0, s52
	s_nop 0
	global_load_lds_dwordx4 v130, s[62:63]
	s_add_i32 m0, s52, 0x2000
	s_nop 0
	global_load_lds_dwordx4 v134, s[62:63]
	s_mov_b32 m0, s31
	s_nop 0
	global_load_lds_dwordx4 v128, s[38:39]
	s_mov_b32 m0, s33
	s_nop 0
	global_load_lds_dwordx4 v132, s[38:39]
	s_waitcnt vmcnt(8)
	s_waitcnt lgkmcnt(0)
	s_barrier
	s_setprio 1
	s_waitcnt lgkmcnt(0)
	v_mfma_f32_16x16x32_bf16 v[60:63], v[144:147], v[182:185], 0
	v_mfma_f32_16x16x32_bf16 v[56:59], v[158:161], v[182:185], 0
	v_mfma_f32_16x16x32_bf16 v[44:47], v[144:147], v[190:193], 0
	v_mfma_f32_16x16x32_bf16 v[40:43], v[158:161], v[190:193], 0
	v_mfma_f32_16x16x32_bf16 v[28:31], v[144:147], v[198:201], 0
	v_mfma_f32_16x16x32_bf16 v[24:27], v[158:161], v[198:201], 0
	v_mfma_f32_16x16x32_bf16 v[12:15], v[144:147], v[206:209], 0
	v_mfma_f32_16x16x32_bf16 v[8:11], v[158:161], v[206:209], 0
	v_mfma_f32_16x16x32_bf16 v[60:63], v[154:157], v[186:189], v[60:63]
	v_mfma_f32_16x16x32_bf16 v[56:59], v[162:165], v[186:189], v[56:59]
	v_mfma_f32_16x16x32_bf16 v[44:47], v[154:157], v[194:197], v[44:47]
	v_mfma_f32_16x16x32_bf16 v[40:43], v[162:165], v[194:197], v[40:43]
	v_mfma_f32_16x16x32_bf16 v[28:31], v[154:157], v[202:205], v[28:31]
	v_mfma_f32_16x16x32_bf16 v[24:27], v[162:165], v[202:205], v[24:27]
	v_mfma_f32_16x16x32_bf16 v[12:15], v[154:157], v[210:213], v[12:15]
	v_mfma_f32_16x16x32_bf16 v[8:11], v[162:165], v[210:213], v[8:11]
	v_mfma_f32_16x16x32_bf16 v[52:55], v[166:169], v[182:185], 0
	v_mfma_f32_16x16x32_bf16 v[48:51], v[174:177], v[182:185], 0
	v_mfma_f32_16x16x32_bf16 v[36:39], v[166:169], v[190:193], 0
	v_mfma_f32_16x16x32_bf16 v[32:35], v[174:177], v[190:193], 0
	v_mfma_f32_16x16x32_bf16 v[20:23], v[166:169], v[198:201], 0
	v_mfma_f32_16x16x32_bf16 v[16:19], v[174:177], v[198:201], 0
	v_mfma_f32_16x16x32_bf16 v[4:7], v[166:169], v[206:209], 0
	v_mfma_f32_16x16x32_bf16 v[0:3], v[174:177], v[206:209], 0
	v_mfma_f32_16x16x32_bf16 v[52:55], v[170:173], v[186:189], v[52:55]
	v_mfma_f32_16x16x32_bf16 v[48:51], v[178:181], v[186:189], v[48:51]
	v_mfma_f32_16x16x32_bf16 v[36:39], v[170:173], v[194:197], v[36:39]
	v_mfma_f32_16x16x32_bf16 v[32:35], v[178:181], v[194:197], v[32:35]
	v_mfma_f32_16x16x32_bf16 v[20:23], v[170:173], v[202:205], v[20:23]
	v_mfma_f32_16x16x32_bf16 v[16:19], v[178:181], v[202:205], v[16:19]
	v_mfma_f32_16x16x32_bf16 v[4:7], v[170:173], v[210:213], v[4:7]
	v_mfma_f32_16x16x32_bf16 v[0:3], v[178:181], v[210:213], v[0:3]
	s_setprio 0
	s_barrier
; #define PG8_STAGE(bufoff, gbase, voff) do { _Pragma("unroll") for (int _i = 0; _i < 2; ++_i) \
;         __builtin_amdgcn_global_load_lds((const unsigned*)((const char*)(gbase) + (voff)[_i]), (LAS unsigned*)(lds + (bufoff) + ldsw + _i * 8192), 16, 0, 0); } while (0)
; #define PG8_LDA(dst, b, h) do { _Pragma("unroll") for (int m = 0; m < 4; ++m) _Pragma("unroll") for (int k = 0; k < 2; ++k) dst[m][k] = *(const LAS bf16x8*)(lds + PG8_SA(b, h) + aoff + m * 2048 + k * 1024); } while (0)
; #define PG8_LDB(dst, b, h) do { _Pragma("unroll") for (int n = 0; n < 2; ++n) _Pragma("unroll") for (int k = 0; k < 2; ++k) dst[n][k] = *(const LAS bf16x8*)(lds + PG8_SB(b, h) + boff + n * 2048 + k * 1024); } while (0)
; #define PG8_MMA(ai, bj, At, Bt) do { __builtin_amdgcn_s_setprio(1); _Pragma("unroll") for (int m = 0; m < 4; ++m) _Pragma("unroll") for (int n = 0; n < 2; ++n) _Pragma("unroll") for (int k = 0; k < 2; ++k) \
;         acc[ai][bj][m][n] = __builtin_amdgcn_mfma_f32_16x16x32_bf16(Bt[n][k], At[m][k], acc[ai][bj][m][n], 0, 0, 0); __builtin_amdgcn_s_setprio(0); } while (0)
; #define PG8_WAIT_V(n) asm volatile("s_waitcnt vmcnt(" #n ")" ::: "memory")
; #define PG8_WAIT_L(n) asm volatile("s_waitcnt lgkmcnt(" #n ")" ::: "memory")
; #define PG8_BAR __builtin_amdgcn_s_barrier()
; #define PG8_SCHED __builtin_amdgcn_sched_barrier(0)
; template <class Epi, bool ALIGN_EPI, int K, int LDA, int LDB>
; __device__ __forceinline__ void gemm_phase(LAS unsigned char* lds, const int wid, const Gemm g, const StaticOrder& S, const Epi& E) {
;     ...
;             PG8_LDB(B0, 1, 0); PG8_LDB(B1, 1, 1); PG8_SCHED; PG8_LDA(At, 1, 0); PG8_STAGE(PG8_SA(0, 1), a2 + hA, voffA);
;             PG8_WAIT_V(8); PG8_WAIT_L(0); PG8_BAR; PG8_MMA(0, 0, At, B0); PG8_MMA(0, 1, At, B1); PG8_BAR; PG8_SCHED;
;             PG8_LDA(At, 1, 1); PG8_STAGE(PG8_SB(1, 0), b3, voffB); PG8_STAGE(PG8_SB(1, 1), b3 + hB, voffB); PG8_STAGE(PG8_SA(1, 0), a3, voffA);
;             PG8_WAIT_V(8); PG8_WAIT_L(0); PG8_BAR; PG8_MMA(1, 0, At, B0); PG8_MMA(1, 1, At, B1); PG8_BAR; PG8_SCHED;
	s_add_i32 s52, 0, 0x18000
	s_add_i32 s53, 0, 0x1c000
	v_add_u32_e32 v162, s52, v150
	v_add_u32_e32 v178, s53, v150
	ds_read_b128 v[144:147], v162
	ds_read_b128 v[154:157], v162 offset:1024
	ds_read_b128 v[158:161], v162 offset:2048
	ds_read_b128 v[162:165], v162 offset:3072
	ds_read_b128 v[166:169], v178
	ds_read_b128 v[170:173], v178 offset:1024
	ds_read_b128 v[174:177], v178 offset:2048
	ds_read_b128 v[178:181], v178 offset:3072
	s_add_u32 s38, s38, 0x40000
	s_addc_u32 s39, s39, 0
	s_mov_b32 m0, s40
	ds_read_b128 v[182:185], v153 offset:32768
	ds_read_b128 v[186:189], v153 offset:33792
	ds_read_b128 v[190:193], v153 offset:34816
	ds_read_b128 v[194:197], v153 offset:35840
	ds_read_b128 v[198:201], v153 offset:36864
	ds_read_b128 v[202:205], v153 offset:37888
	ds_read_b128 v[206:209], v153 offset:38912
	ds_read_b128 v[210:213], v153 offset:39936
	global_load_lds_dwordx4 v128, s[38:39]
	s_mov_b32 m0, s41
	s_nop 0
	global_load_lds_dwordx4 v132, s[38:39]
	s_waitcnt vmcnt(8)
	s_waitcnt lgkmcnt(0)
	s_barrier
	s_setprio 1
	s_waitcnt lgkmcnt(0)
	v_mfma_f32_16x16x32_bf16 v[124:127], v[144:147], v[182:185], v[124:127]
	v_mfma_f32_16x16x32_bf16 v[120:123], v[158:161], v[182:185], v[120:123]
	v_mfma_f32_16x16x32_bf16 v[108:111], v[144:147], v[190:193], v[108:111]
	v_mfma_f32_16x16x32_bf16 v[104:107], v[158:161], v[190:193], v[104:107]
	v_mfma_f32_16x16x32_bf16 v[92:95], v[144:147], v[198:201], v[92:95]
	v_mfma_f32_16x16x32_bf16 v[88:91], v[158:161], v[198:201], v[88:91]
	v_mfma_f32_16x16x32_bf16 v[76:79], v[144:147], v[206:209], v[76:79]
	v_mfma_f32_16x16x32_bf16 v[72:75], v[158:161], v[206:209], v[72:75]
	v_mfma_f32_16x16x32_bf16 v[124:127], v[154:157], v[186:189], v[124:127]
	v_mfma_f32_16x16x32_bf16 v[120:123], v[162:165], v[186:189], v[120:123]
	v_mfma_f32_16x16x32_bf16 v[108:111], v[154:157], v[194:197], v[108:111]
	v_mfma_f32_16x16x32_bf16 v[104:107], v[162:165], v[194:197], v[104:107]
	v_mfma_f32_16x16x32_bf16 v[92:95], v[154:157], v[202:205], v[92:95]
	v_mfma_f32_16x16x32_bf16 v[88:91], v[162:165], v[202:205], v[88:91]
	v_mfma_f32_16x16x32_bf16 v[76:79], v[154:157], v[210:213], v[76:79]
	v_mfma_f32_16x16x32_bf16 v[72:75], v[162:165], v[210:213], v[72:75]
	v_mfma_f32_16x16x32_bf16 v[116:119], v[166:169], v[182:185], v[116:119]
	v_mfma_f32_16x16x32_bf16 v[112:115], v[174:177], v[182:185], v[112:115]
	v_mfma_f32_16x16x32_bf16 v[100:103], v[166:169], v[190:193], v[100:103]
	v_mfma_f32_16x16x32_bf16 v[96:99], v[174:177], v[190:193], v[96:99]
	v_mfma_f32_16x16x32_bf16 v[84:87], v[166:169], v[198:201], v[84:87]
	v_mfma_f32_16x16x32_bf16 v[80:83], v[174:177], v[198:201], v[80:83]
	v_mfma_f32_16x16x32_bf16 v[68:71], v[166:169], v[206:209], v[68:71]
	v_mfma_f32_16x16x32_bf16 v[64:67], v[174:177], v[206:209], v[64:67]
	v_mfma_f32_16x16x32_bf16 v[116:119], v[170:173], v[186:189], v[116:119]
	v_mfma_f32_16x16x32_bf16 v[112:115], v[178:181], v[186:189], v[112:115]
	v_mfma_f32_16x16x32_bf16 v[100:103], v[170:173], v[194:197], v[100:103]
	v_mfma_f32_16x16x32_bf16 v[96:99], v[178:181], v[194:197], v[96:99]
	v_mfma_f32_16x16x32_bf16 v[84:87], v[170:173], v[202:205], v[84:87]
	v_mfma_f32_16x16x32_bf16 v[80:83], v[178:181], v[202:205], v[80:83]
	v_mfma_f32_16x16x32_bf16 v[68:71], v[170:173], v[210:213], v[68:71]
	v_mfma_f32_16x16x32_bf16 v[64:67], v[178:181], v[210:213], v[64:67]
	s_setprio 0
	s_barrier
	s_add_i32 s38, s52, s3
	s_mov_b32 m0, s38
	ds_read_b128 v[182:185], v153 offset:49152
	ds_read_b128 v[186:189], v153 offset:50176
	ds_read_b128 v[190:193], v153 offset:51200
	ds_read_b128 v[194:197], v153 offset:52224
	ds_read_b128 v[198:201], v153 offset:53248
	ds_read_b128 v[202:205], v153 offset:54272
	ds_read_b128 v[206:209], v153 offset:55296
	ds_read_b128 v[210:213], v153 offset:56320
	global_load_lds_dwordx4 v130, s[98:99]
	s_add_i32 m0, s38, 0x2000
	s_add_u32 s36, s36, 0x40080
	s_addc_u32 s37, s37, 0
	s_add_i32 s38, s53, s3
	global_load_lds_dwordx4 v134, s[98:99]
	s_mov_b32 m0, s38
	s_nop 0
	global_load_lds_dwordx4 v130, s[36:37]
	s_add_i32 m0, s38, 0x2000
	s_nop 0
	global_load_lds_dwordx4 v134, s[36:37]
	s_mov_b32 m0, s55
	s_nop 0
	global_load_lds_dwordx4 v128, s[100:101]
	s_mov_b32 m0, s56
	s_nop 0
	global_load_lds_dwordx4 v132, s[100:101]
	s_waitcnt vmcnt(8)
	s_waitcnt lgkmcnt(0)
	s_barrier
	s_setprio 1
	s_waitcnt lgkmcnt(0)
	v_mfma_f32_16x16x32_bf16 v[60:63], v[144:147], v[182:185], v[60:63]
	v_mfma_f32_16x16x32_bf16 v[56:59], v[158:161], v[182:185], v[56:59]
	v_mfma_f32_16x16x32_bf16 v[44:47], v[144:147], v[190:193], v[44:47]
	v_mfma_f32_16x16x32_bf16 v[40:43], v[158:161], v[190:193], v[40:43]
	v_mfma_f32_16x16x32_bf16 v[28:31], v[144:147], v[198:201], v[28:31]
	v_mfma_f32_16x16x32_bf16 v[24:27], v[158:161], v[198:201], v[24:27]
	v_mfma_f32_16x16x32_bf16 v[12:15], v[144:147], v[206:209], v[12:15]
	v_mfma_f32_16x16x32_bf16 v[8:11], v[158:161], v[206:209], v[8:11]
	v_mfma_f32_16x16x32_bf16 v[60:63], v[154:157], v[186:189], v[60:63]
	v_mfma_f32_16x16x32_bf16 v[56:59], v[162:165], v[186:189], v[56:59]
	v_mfma_f32_16x16x32_bf16 v[44:47], v[154:157], v[194:197], v[44:47]
	v_mfma_f32_16x16x32_bf16 v[40:43], v[162:165], v[194:197], v[40:43]
	v_mfma_f32_16x16x32_bf16 v[28:31], v[154:157], v[202:205], v[28:31]
	v_mfma_f32_16x16x32_bf16 v[24:27], v[162:165], v[202:205], v[24:27]
	v_mfma_f32_16x16x32_bf16 v[12:15], v[154:157], v[210:213], v[12:15]
	v_mfma_f32_16x16x32_bf16 v[8:11], v[162:165], v[210:213], v[8:11]
	v_mfma_f32_16x16x32_bf16 v[52:55], v[166:169], v[182:185], v[52:55]
	v_mfma_f32_16x16x32_bf16 v[48:51], v[174:177], v[182:185], v[48:51]
	v_mfma_f32_16x16x32_bf16 v[36:39], v[166:169], v[190:193], v[36:39]
	v_mfma_f32_16x16x32_bf16 v[32:35], v[174:177], v[190:193], v[32:35]
	v_mfma_f32_16x16x32_bf16 v[20:23], v[166:169], v[198:201], v[20:23]
	v_mfma_f32_16x16x32_bf16 v[16:19], v[174:177], v[198:201], v[16:19]
	v_mfma_f32_16x16x32_bf16 v[4:7], v[166:169], v[206:209], v[4:7]
	v_mfma_f32_16x16x32_bf16 v[0:3], v[174:177], v[206:209], v[0:3]
	v_mfma_f32_16x16x32_bf16 v[52:55], v[170:173], v[186:189], v[52:55]
	v_mfma_f32_16x16x32_bf16 v[48:51], v[178:181], v[186:189], v[48:51]
	v_mfma_f32_16x16x32_bf16 v[36:39], v[170:173], v[194:197], v[36:39]
	v_mfma_f32_16x16x32_bf16 v[32:35], v[178:181], v[194:197], v[32:35]
	v_mfma_f32_16x16x32_bf16 v[20:23], v[170:173], v[202:205], v[20:23]
	v_mfma_f32_16x16x32_bf16 v[16:19], v[178:181], v[202:205], v[16:19]
	v_mfma_f32_16x16x32_bf16 v[4:7], v[170:173], v[210:213], v[4:7]
	v_mfma_f32_16x16x32_bf16 v[0:3], v[178:181], v[210:213], v[0:3]
	s_setprio 0
	s_barrier
	s_add_i32 s61, s61, 2
	s_add_u32 s34, s34, 0x100
	s_addc_u32 s35, s35, 0
	s_add_u32 s59, s59, 0x100
	s_addc_u32 s60, s60, 0

; #define PG8_STAGE(bufoff, gbase, voff) do { _Pragma("unroll") for (int _i = 0; _i < 2; ++_i) \
;         __builtin_amdgcn_global_load_lds((const unsigned*)((const char*)(gbase) + (voff)[_i]), (LAS unsigned*)(lds + (bufoff) + ldsw + _i * 8192), 16, 0, 0); } while (0)
; #define PG8_LDA(dst, b, h) do { _Pragma("unroll") for (int m = 0; m < 4; ++m) _Pragma("unroll") for (int k = 0; k < 2; ++k) dst[m][k] = *(const LAS bf16x8*)(lds + PG8_SA(b, h) + aoff + m * 2048 + k * 1024); } while (0)
; #define PG8_LDB(dst, b, h) do { _Pragma("unroll") for (int n = 0; n < 2; ++n) _Pragma("unroll") for (int k = 0; k < 2; ++k) dst[n][k] = *(const LAS bf16x8*)(lds + PG8_SB(b, h) + boff + n * 2048 + k * 1024); } while (0)
; #define PG8_SCHED __builtin_amdgcn_sched_barrier(0)
;     __device__ bool next(int i, Unit& u) const {
;         const long L = (long)i * G + c; if (L >= nwg) return false;
;         int wgid = (int)L; { const int q = nwg / NXCD, r = nwg % NXCD, xcd = wgid % NXCD, off = wgid / NXCD; wgid = (xcd < r ? xcd * (q + 1) : r * (q + 1) + (xcd - r) * q) + off; }
;         const int nig = WGM * nN, gid = wgid / nig, fm = gid * WGM, gsz = (nM - fm) < WGM ? (nM - fm) : WGM;
;         u.pm = fm + ((wgid % nig) % gsz); u.pn = (wgid % nig) / gsz; return true;
; template <class Epi, bool ALIGN_EPI, int K, int LDA, int LDB>
; __device__ __forceinline__ void gemm_phase(LAS unsigned char* lds, const int wid, const Gemm g, const StaticOrder& S, const Epi& E) {
;     ...
;             PG8_LDB(B0, 0, 0); PG8_LDB(B1, 0, 1); PG8_SCHED; PG8_LDA(At, 0, 0); PG8_STAGE(PG8_SA(1, 1), a1 + hA, voffA);
.LBB0_1470:
	ds_read_b128 v[128:131], v175
	ds_read_b128 v[132:135], v175 offset:1024
	ds_read_b128 v[136:139], v175 offset:2048
	ds_read_b128 v[140:143], v175 offset:3072
	ds_read_b128 v[144:147], v176
	ds_read_b128 v[164:167], v176 offset:1024
	ds_read_b128 v[168:171], v176 offset:2048
	ds_read_b128 v[178:181], v176 offset:3072
	ds_read_b128 v[182:185], v177
	ds_read_b128 v[186:189], v177 offset:1024
	ds_read_b128 v[190:193], v177 offset:2048
	ds_read_b128 v[194:197], v177 offset:3072
	ds_read_b128 v[198:201], v177 offset:4096
	ds_read_b128 v[202:205], v177 offset:5120
	ds_read_b128 v[206:209], v177 offset:6144
	ds_read_b128 v[210:213], v177 offset:7168
	s_add_i32 s65, s65, 1
	s_mul_i32 s4, s65, s57
	s_mul_hi_u32 s5, s65, s90
	s_add_i32 s5, s5, s4
	s_mul_i32 s4, s65, s90
	s_add_u32 s26, s4, s2
	s_addc_u32 s27, s5, s0
	v_cmp_gt_i64_e32 vcc, s[26:27], v[162:163]
	v_cmp_lt_i64_e64 s[4:5], s[26:27], v[160:161]
	s_cbranch_vccnz .LBB0_1476
	s_ashr_i32 s22, s26, 31
	s_lshr_b32 s22, s22, 29
	s_add_i32 s24, s26, s22
	s_and_b32 s22, s24, -8
	s_sub_i32 s25, s26, s22
	s_cmp_gt_i32 s25, -1
	s_mov_b64 s[22:23], -1
	s_cbranch_scc0 .LBB0_1473
	s_lshl_b32 s26, s25, 7
	s_mov_b64 s[22:23], 0

; #define PG8_STAGE(bufoff, gbase, voff) do { _Pragma("unroll") for (int _i = 0; _i < 2; ++_i) \
;         __builtin_amdgcn_global_load_lds((const unsigned*)((const char*)(gbase) + (voff)[_i]), (LAS unsigned*)(lds + (bufoff) + ldsw + _i * 8192), 16, 0, 0); } while (0)
; #define PG8_LDA(dst, b, h) do { _Pragma("unroll") for (int m = 0; m < 4; ++m) _Pragma("unroll") for (int k = 0; k < 2; ++k) dst[m][k] = *(const LAS bf16x8*)(lds + PG8_SA(b, h) + aoff + m * 2048 + k * 1024); } while (0)
; #define PG8_LDB(dst, b, h) do { _Pragma("unroll") for (int n = 0; n < 2; ++n) _Pragma("unroll") for (int k = 0; k < 2; ++k) dst[n][k] = *(const LAS bf16x8*)(lds + PG8_SB(b, h) + boff + n * 2048 + k * 1024); } while (0)
; #define PG8_MMA(ai, bj, At, Bt) do { __builtin_amdgcn_s_setprio(1); _Pragma("unroll") for (int m = 0; m < 4; ++m) _Pragma("unroll") for (int n = 0; n < 2; ++n) _Pragma("unroll") for (int k = 0; k < 2; ++k) \
;         acc[ai][bj][m][n] = __builtin_amdgcn_mfma_f32_16x16x32_bf16(Bt[n][k], At[m][k], acc[ai][bj][m][n], 0, 0, 0); __builtin_amdgcn_s_setprio(0); } while (0)
; template <class Epi, bool ALIGN_EPI, int K, int LDA, int LDB>
; __device__ __forceinline__ void gemm_phase(LAS unsigned char* lds, const int wid, const Gemm g, const StaticOrder& S, const Epi& E) {
;     ...
;         const bool has_next = S.next(ui + 1, nxt);
;         const char* nA = has_next ? (const char*)g.A + (size_t)nxt.pm * tA : cA; const char* nB = has_next ? (const char*)g.Bt + (size_t)nxt.pn * tB : cB;
;         for (int t = 0; t < nt; t += 2) {
;             const bool last = (t == nt - 2);
;             const char* a1 = cA + (size_t)(t + 1) * kstep;
;             const char* a2 = last ? nA : cA + (size_t)(t + 2) * kstep; const char* b2 = last ? nB : cB + (size_t)(t + 2) * kstep;
;             const char* a3 = a2 + kstep; const char* b3 = b2 + kstep;
;             PG8_LDB(B0, 0, 0); PG8_LDB(B1, 0, 1); PG8_SCHED; PG8_LDA(At, 0, 0); PG8_STAGE(PG8_SA(1, 1), a1 + hA, voffA);
;             PG8_WAIT_V(8); PG8_WAIT_L(0); PG8_BAR; PG8_MMA(0, 0, At, B0); PG8_MMA(0, 1, At, B1); PG8_BAR; PG8_SCHED;
;             PG8_LDA(At, 0, 1); PG8_STAGE(PG8_SB(0, 0), b2, voffB); PG8_STAGE(PG8_SB(0, 1), b2 + hB, voffB); PG8_STAGE(PG8_SA(0, 0), a2, voffA);
;             PG8_WAIT_V(8); PG8_WAIT_L(0); PG8_BAR; PG8_MMA(1, 0, At, B0); PG8_MMA(1, 1, At, B1); PG8_BAR; PG8_SCHED;
.LBB0_1476:
	s_ashr_i32 s25, s24, 31
	s_lshl_b64 s[26:27], s[24:25], 19
	v_readlane_b32 s23, v254, 0
	s_add_u32 s26, s23, s26
	v_readlane_b32 s23, v254, 1
	s_addc_u32 s27, s23, s27
	s_and_b64 s[28:29], s[4:5], exec
	s_cselect_b32 s25, s27, s35
	s_cselect_b32 s42, s26, s34
	s_ashr_i32 s23, s22, 31
	s_lshl_b64 s[28:29], s[22:23], 19
	s_add_u32 s28, s1, s28
	s_addc_u32 s29, s3, s29
	s_and_b64 s[38:39], s[4:5], exec
	s_cselect_b32 s23, s29, s37
	s_cselect_b32 s66, s28, s36
	s_add_u32 s34, s34, 0x40080
	s_addc_u32 s35, s35, 0
	s_add_u32 s67, s36, 0x100
	s_addc_u32 s68, s37, 0
	s_mov_b32 s69, -2
	s_add_u32 s36, s34, 0xfffc0080
	s_addc_u32 s37, s35, -1
	s_cmp_eq_u32 s69, 12
	s_cselect_b32 s39, s25, s37
	s_cselect_b32 s38, s42, s36
	s_cselect_b32 s37, s23, s68
	s_cselect_b32 s36, s66, s67
	s_add_i32 m0, s40, 0xc000
	global_load_lds_dwordx4 v156, s[34:35]
	s_add_i32 m0, s40, 0xe000
	s_nop 0
	global_load_lds_dwordx4 v158, s[34:35]
	s_waitcnt vmcnt(8)
	s_waitcnt lgkmcnt(0)
	s_barrier
	s_setprio 1
	s_waitcnt lgkmcnt(0)
	v_mfma_f32_16x16x32_bf16 v[124:127], v[128:131], v[182:185], 0
	v_mfma_f32_16x16x32_bf16 v[116:119], v[136:139], v[182:185], 0
	v_mfma_f32_16x16x32_bf16 v[120:123], v[128:131], v[190:193], 0
	v_mfma_f32_16x16x32_bf16 v[112:115], v[136:139], v[190:193], 0
	v_mfma_f32_16x16x32_bf16 v[92:95], v[128:131], v[198:201], 0
	v_mfma_f32_16x16x32_bf16 v[88:91], v[136:139], v[198:201], 0
	v_mfma_f32_16x16x32_bf16 v[76:79], v[128:131], v[206:209], 0
	v_mfma_f32_16x16x32_bf16 v[72:75], v[136:139], v[206:209], 0
	v_mfma_f32_16x16x32_bf16 v[124:127], v[132:135], v[186:189], v[124:127]
	v_mfma_f32_16x16x32_bf16 v[116:119], v[140:143], v[186:189], v[116:119]
	v_mfma_f32_16x16x32_bf16 v[120:123], v[132:135], v[194:197], v[120:123]
	v_mfma_f32_16x16x32_bf16 v[112:115], v[140:143], v[194:197], v[112:115]
	v_mfma_f32_16x16x32_bf16 v[92:95], v[132:135], v[202:205], v[92:95]
	v_mfma_f32_16x16x32_bf16 v[88:91], v[140:143], v[202:205], v[88:91]
	v_mfma_f32_16x16x32_bf16 v[76:79], v[132:135], v[210:213], v[76:79]
	v_mfma_f32_16x16x32_bf16 v[72:75], v[140:143], v[210:213], v[72:75]
	v_mfma_f32_16x16x32_bf16 v[108:111], v[144:147], v[182:185], 0
	v_mfma_f32_16x16x32_bf16 v[104:107], v[168:171], v[182:185], 0
	v_mfma_f32_16x16x32_bf16 v[100:103], v[144:147], v[190:193], 0
	v_mfma_f32_16x16x32_bf16 v[96:99], v[168:171], v[190:193], 0
	v_mfma_f32_16x16x32_bf16 v[84:87], v[144:147], v[198:201], 0
	v_mfma_f32_16x16x32_bf16 v[80:83], v[168:171], v[198:201], 0
	v_mfma_f32_16x16x32_bf16 v[68:71], v[144:147], v[206:209], 0
	v_mfma_f32_16x16x32_bf16 v[64:67], v[168:171], v[206:209], 0
	v_mfma_f32_16x16x32_bf16 v[108:111], v[164:167], v[186:189], v[108:111]
	v_mfma_f32_16x16x32_bf16 v[104:107], v[178:181], v[186:189], v[104:107]
	v_mfma_f32_16x16x32_bf16 v[100:103], v[164:167], v[194:197], v[100:103]
	v_mfma_f32_16x16x32_bf16 v[96:99], v[178:181], v[194:197], v[96:99]
	v_mfma_f32_16x16x32_bf16 v[84:87], v[164:167], v[202:205], v[84:87]
	v_mfma_f32_16x16x32_bf16 v[80:83], v[178:181], v[202:205], v[80:83]
	v_mfma_f32_16x16x32_bf16 v[68:71], v[164:167], v[210:213], v[68:71]
	v_mfma_f32_16x16x32_bf16 v[64:67], v[178:181], v[210:213], v[64:67]
	s_setprio 0
	s_barrier
	s_add_u32 s98, s36, s12
	s_addc_u32 s99, s37, s13
	s_add_u32 s100, s38, s12
	s_addc_u32 s101, s39, s13
	s_add_i32 s52, s58, s33
	s_mov_b32 m0, s52
	ds_read_b128 v[182:185], v177 offset:16384
	ds_read_b128 v[186:189], v177 offset:17408
	ds_read_b128 v[190:193], v177 offset:18432
	ds_read_b128 v[194:197], v177 offset:19456
	ds_read_b128 v[198:201], v177 offset:20480
	ds_read_b128 v[202:205], v177 offset:21504
	ds_read_b128 v[206:209], v177 offset:22528
	ds_read_b128 v[210:213], v177 offset:23552
	global_load_lds_dwordx4 v150, s[36:37]
	s_add_i32 m0, s52, 0x2000
	s_add_u32 s70, s36, 0x40000
	s_addc_u32 s71, s37, 0
	s_add_i32 s52, s59, s33
	global_load_lds_dwordx4 v154, s[36:37]
	s_mov_b32 m0, s52
	s_nop 0
	global_load_lds_dwordx4 v150, s[70:71]
	s_add_i32 m0, s52, 0x2000
	s_nop 0
	global_load_lds_dwordx4 v154, s[70:71]
	s_mov_b32 m0, s40
	s_nop 0
	global_load_lds_dwordx4 v148, s[38:39]
	s_mov_b32 m0, s41
	s_nop 0
	global_load_lds_dwordx4 v152, s[38:39]
	s_waitcnt vmcnt(8)
	s_waitcnt lgkmcnt(0)
	s_barrier
	s_setprio 1
	s_waitcnt lgkmcnt(0)
	v_mfma_f32_16x16x32_bf16 v[60:63], v[128:131], v[182:185], 0
	v_mfma_f32_16x16x32_bf16 v[56:59], v[136:139], v[182:185], 0
	v_mfma_f32_16x16x32_bf16 v[44:47], v[128:131], v[190:193], 0
	v_mfma_f32_16x16x32_bf16 v[40:43], v[136:139], v[190:193], 0
	v_mfma_f32_16x16x32_bf16 v[36:39], v[128:131], v[198:201], 0
	v_mfma_f32_16x16x32_bf16 v[32:35], v[136:139], v[198:201], 0
	v_mfma_f32_16x16x32_bf16 v[20:23], v[128:131], v[206:209], 0
	v_mfma_f32_16x16x32_bf16 v[16:19], v[136:139], v[206:209], 0
	v_mfma_f32_16x16x32_bf16 v[60:63], v[132:135], v[186:189], v[60:63]
	v_mfma_f32_16x16x32_bf16 v[56:59], v[140:143], v[186:189], v[56:59]
	v_mfma_f32_16x16x32_bf16 v[44:47], v[132:135], v[194:197], v[44:47]
	v_mfma_f32_16x16x32_bf16 v[40:43], v[140:143], v[194:197], v[40:43]
	v_mfma_f32_16x16x32_bf16 v[36:39], v[132:135], v[202:205], v[36:39]
	v_mfma_f32_16x16x32_bf16 v[32:35], v[140:143], v[202:205], v[32:35]
	v_mfma_f32_16x16x32_bf16 v[20:23], v[132:135], v[210:213], v[20:23]
	v_mfma_f32_16x16x32_bf16 v[16:19], v[140:143], v[210:213], v[16:19]
	v_mfma_f32_16x16x32_bf16 v[52:55], v[144:147], v[182:185], 0
	v_mfma_f32_16x16x32_bf16 v[48:51], v[168:171], v[182:185], 0
	v_mfma_f32_16x16x32_bf16 v[28:31], v[144:147], v[190:193], 0
	v_mfma_f32_16x16x32_bf16 v[24:27], v[168:171], v[190:193], 0
	v_mfma_f32_16x16x32_bf16 v[12:15], v[144:147], v[198:201], 0
	v_mfma_f32_16x16x32_bf16 v[8:11], v[168:171], v[198:201], 0
	v_mfma_f32_16x16x32_bf16 v[4:7], v[144:147], v[206:209], 0
	v_mfma_f32_16x16x32_bf16 v[0:3], v[168:171], v[206:209], 0
	v_mfma_f32_16x16x32_bf16 v[52:55], v[164:167], v[186:189], v[52:55]
	v_mfma_f32_16x16x32_bf16 v[48:51], v[178:181], v[186:189], v[48:51]
	v_mfma_f32_16x16x32_bf16 v[28:31], v[164:167], v[194:197], v[28:31]
	v_mfma_f32_16x16x32_bf16 v[24:27], v[178:181], v[194:197], v[24:27]
	v_mfma_f32_16x16x32_bf16 v[12:15], v[164:167], v[202:205], v[12:15]
	v_mfma_f32_16x16x32_bf16 v[8:11], v[178:181], v[202:205], v[8:11]
	v_mfma_f32_16x16x32_bf16 v[4:7], v[164:167], v[210:213], v[4:7]
	v_mfma_f32_16x16x32_bf16 v[0:3], v[178:181], v[210:213], v[0:3]
	s_setprio 0
	s_barrier
; #define PG8_STAGE(bufoff, gbase, voff) do { _Pragma("unroll") for (int _i = 0; _i < 2; ++_i) \
;         __builtin_amdgcn_global_load_lds((const unsigned*)((const char*)(gbase) + (voff)[_i]), (LAS unsigned*)(lds + (bufoff) + ldsw + _i * 8192), 16, 0, 0); } while (0)
; #define PG8_LDA(dst, b, h) do { _Pragma("unroll") for (int m = 0; m < 4; ++m) _Pragma("unroll") for (int k = 0; k < 2; ++k) dst[m][k] = *(const LAS bf16x8*)(lds + PG8_SA(b, h) + aoff + m * 2048 + k * 1024); } while (0)
; #define PG8_LDB(dst, b, h) do { _Pragma("unroll") for (int n = 0; n < 2; ++n) _Pragma("unroll") for (int k = 0; k < 2; ++k) dst[n][k] = *(const LAS bf16x8*)(lds + PG8_SB(b, h) + boff + n * 2048 + k * 1024); } while (0)
; #define PG8_MMA(ai, bj, At, Bt) do { __builtin_amdgcn_s_setprio(1); _Pragma("unroll") for (int m = 0; m < 4; ++m) _Pragma("unroll") for (int n = 0; n < 2; ++n) _Pragma("unroll") for (int k = 0; k < 2; ++k) \
;         acc[ai][bj][m][n] = __builtin_amdgcn_mfma_f32_16x16x32_bf16(Bt[n][k], At[m][k], acc[ai][bj][m][n], 0, 0, 0); __builtin_amdgcn_s_setprio(0); } while (0)
; #define PG8_WAIT_V(n) asm volatile("s_waitcnt vmcnt(" #n ")" ::: "memory")
; #define PG8_WAIT_L(n) asm volatile("s_waitcnt lgkmcnt(" #n ")" ::: "memory")
; #define PG8_BAR __builtin_amdgcn_s_barrier()
; #define PG8_SCHED __builtin_amdgcn_sched_barrier(0)
; template <class Epi, bool ALIGN_EPI, int K, int LDA, int LDB>
; __device__ __forceinline__ void gemm_phase(LAS unsigned char* lds, const int wid, const Gemm g, const StaticOrder& S, const Epi& E) {
;     ...
;             PG8_LDB(B0, 1, 0); PG8_LDB(B1, 1, 1); PG8_SCHED; PG8_LDA(At, 1, 0); PG8_STAGE(PG8_SA(0, 1), a2 + hA, voffA);
;             PG8_WAIT_V(8); PG8_WAIT_L(0); PG8_BAR; PG8_MMA(0, 0, At, B0); PG8_MMA(0, 1, At, B1); PG8_BAR; PG8_SCHED;
;             PG8_LDA(At, 1, 1); PG8_STAGE(PG8_SB(1, 0), b3, voffB); PG8_STAGE(PG8_SB(1, 1), b3 + hB, voffB); PG8_STAGE(PG8_SA(1, 0), a3, voffA);
;             PG8_WAIT_V(8); PG8_WAIT_L(0); PG8_BAR; PG8_MMA(1, 0, At, B0); PG8_MMA(1, 1, At, B1); PG8_BAR; PG8_SCHED;
	s_add_i32 s52, 0, 0x18000
	s_add_i32 s53, 0, 0x1c000
	v_add_u32_e32 v140, s52, v174
	v_add_u32_e32 v178, s53, v174
	ds_read_b128 v[128:131], v140
	ds_read_b128 v[132:135], v140 offset:1024
	ds_read_b128 v[136:139], v140 offset:2048
	ds_read_b128 v[140:143], v140 offset:3072
	ds_read_b128 v[144:147], v178
	ds_read_b128 v[164:167], v178 offset:1024
	ds_read_b128 v[168:171], v178 offset:2048
	ds_read_b128 v[178:181], v178 offset:3072
	s_add_u32 s38, s38, 0x40000
	s_addc_u32 s39, s39, 0
	s_mov_b32 m0, s43
	ds_read_b128 v[182:185], v177 offset:32768
	ds_read_b128 v[186:189], v177 offset:33792
	ds_read_b128 v[190:193], v177 offset:34816
	ds_read_b128 v[194:197], v177 offset:35840
	ds_read_b128 v[198:201], v177 offset:36864
	ds_read_b128 v[202:205], v177 offset:37888
	ds_read_b128 v[206:209], v177 offset:38912
	ds_read_b128 v[210:213], v177 offset:39936
	global_load_lds_dwordx4 v148, s[38:39]
	s_mov_b32 m0, s48
	s_nop 0
	global_load_lds_dwordx4 v152, s[38:39]
	s_waitcnt vmcnt(8)
	s_waitcnt lgkmcnt(0)
	s_barrier
	s_setprio 1
	s_waitcnt lgkmcnt(0)
	v_mfma_f32_16x16x32_bf16 v[124:127], v[128:131], v[182:185], v[124:127]
	v_mfma_f32_16x16x32_bf16 v[116:119], v[136:139], v[182:185], v[116:119]
	v_mfma_f32_16x16x32_bf16 v[120:123], v[128:131], v[190:193], v[120:123]
	v_mfma_f32_16x16x32_bf16 v[112:115], v[136:139], v[190:193], v[112:115]
	v_mfma_f32_16x16x32_bf16 v[92:95], v[128:131], v[198:201], v[92:95]
	v_mfma_f32_16x16x32_bf16 v[88:91], v[136:139], v[198:201], v[88:91]
	v_mfma_f32_16x16x32_bf16 v[76:79], v[128:131], v[206:209], v[76:79]
	v_mfma_f32_16x16x32_bf16 v[72:75], v[136:139], v[206:209], v[72:75]
	v_mfma_f32_16x16x32_bf16 v[124:127], v[132:135], v[186:189], v[124:127]
	v_mfma_f32_16x16x32_bf16 v[116:119], v[140:143], v[186:189], v[116:119]
	v_mfma_f32_16x16x32_bf16 v[120:123], v[132:135], v[194:197], v[120:123]
	v_mfma_f32_16x16x32_bf16 v[112:115], v[140:143], v[194:197], v[112:115]
	v_mfma_f32_16x16x32_bf16 v[92:95], v[132:135], v[202:205], v[92:95]
	v_mfma_f32_16x16x32_bf16 v[88:91], v[140:143], v[202:205], v[88:91]
	v_mfma_f32_16x16x32_bf16 v[76:79], v[132:135], v[210:213], v[76:79]
	v_mfma_f32_16x16x32_bf16 v[72:75], v[140:143], v[210:213], v[72:75]
	v_mfma_f32_16x16x32_bf16 v[108:111], v[144:147], v[182:185], v[108:111]
	v_mfma_f32_16x16x32_bf16 v[104:107], v[168:171], v[182:185], v[104:107]
	v_mfma_f32_16x16x32_bf16 v[100:103], v[144:147], v[190:193], v[100:103]
	v_mfma_f32_16x16x32_bf16 v[96:99], v[168:171], v[190:193], v[96:99]
	v_mfma_f32_16x16x32_bf16 v[84:87], v[144:147], v[198:201], v[84:87]
	v_mfma_f32_16x16x32_bf16 v[80:83], v[168:171], v[198:201], v[80:83]
	v_mfma_f32_16x16x32_bf16 v[68:71], v[144:147], v[206:209], v[68:71]
	v_mfma_f32_16x16x32_bf16 v[64:67], v[168:171], v[206:209], v[64:67]
	v_mfma_f32_16x16x32_bf16 v[108:111], v[164:167], v[186:189], v[108:111]
	v_mfma_f32_16x16x32_bf16 v[104:107], v[178:181], v[186:189], v[104:107]
	v_mfma_f32_16x16x32_bf16 v[100:103], v[164:167], v[194:197], v[100:103]
	v_mfma_f32_16x16x32_bf16 v[96:99], v[178:181], v[194:197], v[96:99]
	v_mfma_f32_16x16x32_bf16 v[84:87], v[164:167], v[202:205], v[84:87]
	v_mfma_f32_16x16x32_bf16 v[80:83], v[178:181], v[202:205], v[80:83]
	v_mfma_f32_16x16x32_bf16 v[68:71], v[164:167], v[210:213], v[68:71]
	v_mfma_f32_16x16x32_bf16 v[64:67], v[178:181], v[210:213], v[64:67]
	s_setprio 0
	s_barrier
	s_add_i32 s38, s52, s33
	s_mov_b32 m0, s38
	ds_read_b128 v[182:185], v177 offset:49152
	ds_read_b128 v[186:189], v177 offset:50176
	ds_read_b128 v[190:193], v177 offset:51200
	ds_read_b128 v[194:197], v177 offset:52224
	ds_read_b128 v[198:201], v177 offset:53248
	ds_read_b128 v[202:205], v177 offset:54272
	ds_read_b128 v[206:209], v177 offset:55296
	ds_read_b128 v[210:213], v177 offset:56320
	global_load_lds_dwordx4 v150, s[98:99]
	s_add_i32 m0, s38, 0x2000
	s_add_u32 s36, s36, 0x40080
	s_addc_u32 s37, s37, 0
	s_add_i32 s38, s53, s33
	global_load_lds_dwordx4 v154, s[98:99]
	s_mov_b32 m0, s38
	s_nop 0
	global_load_lds_dwordx4 v150, s[36:37]
	s_add_i32 m0, s38, 0x2000
	s_nop 0
	global_load_lds_dwordx4 v154, s[36:37]
	s_mov_b32 m0, s55
	s_nop 0
	global_load_lds_dwordx4 v148, s[100:101]
	s_mov_b32 m0, s56
	s_nop 0
	global_load_lds_dwordx4 v152, s[100:101]
	s_waitcnt vmcnt(8)
	s_waitcnt lgkmcnt(0)
	s_barrier
	s_setprio 1
	s_waitcnt lgkmcnt(0)
	v_mfma_f32_16x16x32_bf16 v[60:63], v[128:131], v[182:185], v[60:63]
	v_mfma_f32_16x16x32_bf16 v[56:59], v[136:139], v[182:185], v[56:59]
	v_mfma_f32_16x16x32_bf16 v[44:47], v[128:131], v[190:193], v[44:47]
	v_mfma_f32_16x16x32_bf16 v[40:43], v[136:139], v[190:193], v[40:43]
	v_mfma_f32_16x16x32_bf16 v[36:39], v[128:131], v[198:201], v[36:39]
	v_mfma_f32_16x16x32_bf16 v[32:35], v[136:139], v[198:201], v[32:35]
	v_mfma_f32_16x16x32_bf16 v[20:23], v[128:131], v[206:209], v[20:23]
	v_mfma_f32_16x16x32_bf16 v[16:19], v[136:139], v[206:209], v[16:19]
	v_mfma_f32_16x16x32_bf16 v[60:63], v[132:135], v[186:189], v[60:63]
	v_mfma_f32_16x16x32_bf16 v[56:59], v[140:143], v[186:189], v[56:59]
	v_mfma_f32_16x16x32_bf16 v[44:47], v[132:135], v[194:197], v[44:47]
	v_mfma_f32_16x16x32_bf16 v[40:43], v[140:143], v[194:197], v[40:43]
	v_mfma_f32_16x16x32_bf16 v[36:39], v[132:135], v[202:205], v[36:39]
	v_mfma_f32_16x16x32_bf16 v[32:35], v[140:143], v[202:205], v[32:35]
	v_mfma_f32_16x16x32_bf16 v[20:23], v[132:135], v[210:213], v[20:23]
	v_mfma_f32_16x16x32_bf16 v[16:19], v[140:143], v[210:213], v[16:19]
	v_mfma_f32_16x16x32_bf16 v[52:55], v[144:147], v[182:185], v[52:55]
	v_mfma_f32_16x16x32_bf16 v[48:51], v[168:171], v[182:185], v[48:51]
	v_mfma_f32_16x16x32_bf16 v[28:31], v[144:147], v[190:193], v[28:31]
	v_mfma_f32_16x16x32_bf16 v[24:27], v[168:171], v[190:193], v[24:27]
	v_mfma_f32_16x16x32_bf16 v[12:15], v[144:147], v[198:201], v[12:15]
	v_mfma_f32_16x16x32_bf16 v[8:11], v[168:171], v[198:201], v[8:11]
	v_mfma_f32_16x16x32_bf16 v[4:7], v[144:147], v[206:209], v[4:7]
	v_mfma_f32_16x16x32_bf16 v[0:3], v[168:171], v[206:209], v[0:3]
	v_mfma_f32_16x16x32_bf16 v[52:55], v[164:167], v[186:189], v[52:55]
	v_mfma_f32_16x16x32_bf16 v[48:51], v[178:181], v[186:189], v[48:51]
	v_mfma_f32_16x16x32_bf16 v[28:31], v[164:167], v[194:197], v[28:31]
	v_mfma_f32_16x16x32_bf16 v[24:27], v[178:181], v[194:197], v[24:27]
	v_mfma_f32_16x16x32_bf16 v[12:15], v[164:167], v[202:205], v[12:15]
	v_mfma_f32_16x16x32_bf16 v[8:11], v[178:181], v[202:205], v[8:11]
	v_mfma_f32_16x16x32_bf16 v[4:7], v[164:167], v[210:213], v[4:7]
	v_mfma_f32_16x16x32_bf16 v[0:3], v[178:181], v[210:213], v[0:3]
	s_setprio 0
	s_barrier
	s_add_i32 s69, s69, 2
	s_add_u32 s34, s34, 0x100
	s_addc_u32 s35, s35, 0
	s_add_u32 s67, s67, 0x100
	s_addc_u32 s68, s68, 0

; #define PG8_STAGE(bufoff, gbase, voff) do { _Pragma("unroll") for (int _i = 0; _i < 2; ++_i) \
;         __builtin_amdgcn_global_load_lds((const unsigned*)((const char*)(gbase) + (voff)[_i]), (LAS unsigned*)(lds + (bufoff) + ldsw + _i * 8192), 16, 0, 0); } while (0)
; #define PG8_LDA(dst, b, h) do { _Pragma("unroll") for (int m = 0; m < 4; ++m) _Pragma("unroll") for (int k = 0; k < 2; ++k) dst[m][k] = *(const LAS bf16x8*)(lds + PG8_SA(b, h) + aoff + m * 2048 + k * 1024); } while (0)
; #define PG8_LDB(dst, b, h) do { _Pragma("unroll") for (int n = 0; n < 2; ++n) _Pragma("unroll") for (int k = 0; k < 2; ++k) dst[n][k] = *(const LAS bf16x8*)(lds + PG8_SB(b, h) + boff + n * 2048 + k * 1024); } while (0)
; #define PG8_SCHED __builtin_amdgcn_sched_barrier(0)
;     __device__ bool next(int i, Unit& u) const {
;         const long L = (long)i * G + c; if (L >= nwg) return false;
;         int wgid = (int)L; { const int q = nwg / NXCD, r = nwg % NXCD, xcd = wgid % NXCD, off = wgid / NXCD; wgid = (xcd < r ? xcd * (q + 1) : r * (q + 1) + (xcd - r) * q) + off; }
;         const int nig = WGM * nN, gid = wgid / nig, fm = gid * WGM, gsz = (nM - fm) < WGM ? (nM - fm) : WGM;
;         u.pm = fm + ((wgid % nig) % gsz); u.pn = (wgid % nig) / gsz; return true;
; template <class Epi, bool ALIGN_EPI, int K, int LDA, int LDB>
; __device__ __forceinline__ void gemm_phase(LAS unsigned char* lds, const int wid, const Gemm g, const StaticOrder& S, const Epi& E) {
;     ...
;             PG8_LDB(B0, 0, 0); PG8_LDB(B1, 0, 1); PG8_SCHED; PG8_LDA(At, 0, 0); PG8_STAGE(PG8_SA(1, 1), a1 + hA, voffA);
.LBB0_1686:
	ds_read_b128 v[120:123], v167
	ds_read_b128 v[124:127], v167 offset:1024
	ds_read_b128 v[128:131], v167 offset:2048
	ds_read_b128 v[132:135], v167 offset:3072
	ds_read_b128 v[160:163], v168
	ds_read_b128 v[170:173], v168 offset:1024
	ds_read_b128 v[174:177], v168 offset:2048
	ds_read_b128 v[178:181], v168 offset:3072
	ds_read_b128 v[182:185], v169
	ds_read_b128 v[186:189], v169 offset:1024
	ds_read_b128 v[190:193], v169 offset:2048
	ds_read_b128 v[194:197], v169 offset:3072
	ds_read_b128 v[198:201], v169 offset:4096
	ds_read_b128 v[202:205], v169 offset:5120
	ds_read_b128 v[206:209], v169 offset:6144
	ds_read_b128 v[210:213], v169 offset:7168
	s_add_i32 s57, s57, 1
	s_mul_i32 s4, s57, s51
	s_mul_hi_u32 s5, s57, s90
	s_add_i32 s5, s5, s4
	s_mul_i32 s4, s57, s90
	s_add_u32 s4, s4, s2
	s_addc_u32 s5, s5, s0
	v_cmp_gt_i64_e32 vcc, s[4:5], v[158:159]
	v_cmp_lt_i64_e64 s[6:7], s[4:5], v[156:157]
	s_cbranch_vccnz .LBB0_1692
	s_ashr_i32 s5, s4, 31
	s_lshr_b32 s5, s5, 29
	s_add_i32 s24, s4, s5
	s_and_b32 s5, s24, -8
	s_sub_i32 s25, s4, s5
	s_cmp_gt_i32 s25, -1
	s_mov_b64 s[4:5], -1
	s_cbranch_scc0 .LBB0_1689
	s_lshl_b32 s30, s25, 7
	s_mov_b64 s[4:5], 0

; #define PG8_STAGE(bufoff, gbase, voff) do { _Pragma("unroll") for (int _i = 0; _i < 2; ++_i) \
;         __builtin_amdgcn_global_load_lds((const unsigned*)((const char*)(gbase) + (voff)[_i]), (LAS unsigned*)(lds + (bufoff) + ldsw + _i * 8192), 16, 0, 0); } while (0)
; #define PG8_LDA(dst, b, h) do { _Pragma("unroll") for (int m = 0; m < 4; ++m) _Pragma("unroll") for (int k = 0; k < 2; ++k) dst[m][k] = *(const LAS bf16x8*)(lds + PG8_SA(b, h) + aoff + m * 2048 + k * 1024); } while (0)
; #define PG8_LDB(dst, b, h) do { _Pragma("unroll") for (int n = 0; n < 2; ++n) _Pragma("unroll") for (int k = 0; k < 2; ++k) dst[n][k] = *(const LAS bf16x8*)(lds + PG8_SB(b, h) + boff + n * 2048 + k * 1024); } while (0)
; #define PG8_MMA(ai, bj, At, Bt) do { __builtin_amdgcn_s_setprio(1); _Pragma("unroll") for (int m = 0; m < 4; ++m) _Pragma("unroll") for (int n = 0; n < 2; ++n) _Pragma("unroll") for (int k = 0; k < 2; ++k) \
;         acc[ai][bj][m][n] = __builtin_amdgcn_mfma_f32_16x16x32_bf16(Bt[n][k], At[m][k], acc[ai][bj][m][n], 0, 0, 0); __builtin_amdgcn_s_setprio(0); } while (0)
; #define PG8_WAIT_V(n) asm volatile("s_waitcnt vmcnt(" #n ")" ::: "memory")
; template <class Epi, bool ALIGN_EPI, int K, int LDA, int LDB>
; __device__ __forceinline__ void gemm_phase(LAS unsigned char* lds, const int wid, const Gemm g, const StaticOrder& S, const Epi& E) {
;     ...
;         const char* nA = has_next ? (const char*)g.A + (size_t)nxt.pm * tA : cA; const char* nB = has_next ? (const char*)g.Bt + (size_t)nxt.pn * tB : cB;
;         for (int t = 0; t < nt; t += 2) {
;             const bool last = (t == nt - 2);
;             const char* a1 = cA + (size_t)(t + 1) * kstep;
;             const char* a2 = last ? nA : cA + (size_t)(t + 2) * kstep; const char* b2 = last ? nB : cB + (size_t)(t + 2) * kstep;
;             const char* a3 = a2 + kstep; const char* b3 = b2 + kstep;
;             PG8_LDB(B0, 0, 0); PG8_LDB(B1, 0, 1); PG8_SCHED; PG8_LDA(At, 0, 0); PG8_STAGE(PG8_SA(1, 1), a1 + hA, voffA);
;             PG8_WAIT_V(8); PG8_WAIT_L(0); PG8_BAR; PG8_MMA(0, 0, At, B0); PG8_MMA(0, 1, At, B1); PG8_BAR; PG8_SCHED;
;             PG8_LDA(At, 0, 1); PG8_STAGE(PG8_SB(0, 0), b2, voffB); PG8_STAGE(PG8_SB(0, 1), b2 + hB, voffB); PG8_STAGE(PG8_SA(0, 0), a2, voffA);
;             PG8_WAIT_V(8); PG8_WAIT_L(0); PG8_BAR; PG8_MMA(1, 0, At, B0); PG8_MMA(1, 1, At, B1); PG8_BAR; PG8_SCHED;
.LBB0_1696:
	s_add_u32 s61, s28, 0x100
	s_addc_u32 s62, s29, 0
	s_mov_b32 s63, -2
	s_add_u32 s28, s26, 0x100
	s_addc_u32 s29, s27, 0
	s_cmp_eq_u32 s63, 40
	s_cselect_b32 s35, s7, s29
	s_cselect_b32 s34, s6, s28
	s_cselect_b32 s31, s25, s62
	s_cselect_b32 s30, s24, s61
	s_add_i32 m0, s36, 0xc000
	global_load_lds_dwordx4 v152, s[26:27]
	s_add_i32 m0, s36, 0xe000
	s_nop 0
	global_load_lds_dwordx4 v154, s[26:27]
	s_waitcnt vmcnt(8)
	s_waitcnt lgkmcnt(0)
	s_barrier
	s_setprio 1
	s_waitcnt lgkmcnt(0)
	v_mfma_f32_16x16x32_bf16 v[140:143], v[120:123], v[182:185], 0
	v_mfma_f32_16x16x32_bf16 v[136:139], v[128:131], v[182:185], 0
	v_mfma_f32_16x16x32_bf16 v[108:111], v[120:123], v[190:193], 0
	v_mfma_f32_16x16x32_bf16 v[104:107], v[128:131], v[190:193], 0
	v_mfma_f32_16x16x32_bf16 v[92:95], v[120:123], v[198:201], 0
	v_mfma_f32_16x16x32_bf16 v[88:91], v[128:131], v[198:201], 0
	v_mfma_f32_16x16x32_bf16 v[76:79], v[120:123], v[206:209], 0
	v_mfma_f32_16x16x32_bf16 v[72:75], v[128:131], v[206:209], 0
	v_mfma_f32_16x16x32_bf16 v[140:143], v[124:127], v[186:189], v[140:143]
	v_mfma_f32_16x16x32_bf16 v[136:139], v[132:135], v[186:189], v[136:139]
	v_mfma_f32_16x16x32_bf16 v[108:111], v[124:127], v[194:197], v[108:111]
	v_mfma_f32_16x16x32_bf16 v[104:107], v[132:135], v[194:197], v[104:107]
	v_mfma_f32_16x16x32_bf16 v[92:95], v[124:127], v[202:205], v[92:95]
	v_mfma_f32_16x16x32_bf16 v[88:91], v[132:135], v[202:205], v[88:91]
	v_mfma_f32_16x16x32_bf16 v[76:79], v[124:127], v[210:213], v[76:79]
	v_mfma_f32_16x16x32_bf16 v[72:75], v[132:135], v[210:213], v[72:75]
	v_mfma_f32_16x16x32_bf16 v[116:119], v[160:163], v[182:185], 0
	v_mfma_f32_16x16x32_bf16 v[112:115], v[174:177], v[182:185], 0
	v_mfma_f32_16x16x32_bf16 v[100:103], v[160:163], v[190:193], 0
	v_mfma_f32_16x16x32_bf16 v[96:99], v[174:177], v[190:193], 0
	v_mfma_f32_16x16x32_bf16 v[84:87], v[160:163], v[198:201], 0
	v_mfma_f32_16x16x32_bf16 v[80:83], v[174:177], v[198:201], 0
	v_mfma_f32_16x16x32_bf16 v[68:71], v[160:163], v[206:209], 0
	v_mfma_f32_16x16x32_bf16 v[64:67], v[174:177], v[206:209], 0
	v_mfma_f32_16x16x32_bf16 v[116:119], v[170:173], v[186:189], v[116:119]
	v_mfma_f32_16x16x32_bf16 v[112:115], v[178:181], v[186:189], v[112:115]
	v_mfma_f32_16x16x32_bf16 v[100:103], v[170:173], v[194:197], v[100:103]
	v_mfma_f32_16x16x32_bf16 v[96:99], v[178:181], v[194:197], v[96:99]
	v_mfma_f32_16x16x32_bf16 v[84:87], v[170:173], v[202:205], v[84:87]
	v_mfma_f32_16x16x32_bf16 v[80:83], v[178:181], v[202:205], v[80:83]
	v_mfma_f32_16x16x32_bf16 v[68:71], v[170:173], v[210:213], v[68:71]
	v_mfma_f32_16x16x32_bf16 v[64:67], v[178:181], v[210:213], v[64:67]
	s_setprio 0
	s_barrier
	s_add_u32 s98, s30, s12
	s_addc_u32 s99, s31, s13
	s_add_u32 s100, s34, s12
	s_addc_u32 s101, s35, s13
	s_add_i32 s26, s54, s33
	s_mov_b32 m0, s26
	ds_read_b128 v[182:185], v169 offset:16384
	ds_read_b128 v[186:189], v169 offset:17408
	ds_read_b128 v[190:193], v169 offset:18432
	ds_read_b128 v[194:197], v169 offset:19456
	ds_read_b128 v[198:201], v169 offset:20480
	ds_read_b128 v[202:205], v169 offset:21504
	ds_read_b128 v[206:209], v169 offset:22528
	ds_read_b128 v[210:213], v169 offset:23552
	global_load_lds_dwordx4 v146, s[30:31]
	s_add_i32 m0, s26, 0x2000
	s_add_u32 s26, s30, 0xb0000
	s_addc_u32 s27, s31, 0
	s_add_i32 s52, s55, s33
	global_load_lds_dwordx4 v150, s[30:31]
	s_mov_b32 m0, s52
	s_nop 0
	global_load_lds_dwordx4 v146, s[26:27]
	s_add_i32 m0, s52, 0x2000
	s_nop 0
	global_load_lds_dwordx4 v150, s[26:27]
	s_mov_b32 m0, s36
	s_nop 0
	global_load_lds_dwordx4 v144, s[34:35]
	s_mov_b32 m0, s37
	s_nop 0
	global_load_lds_dwordx4 v148, s[34:35]
	s_waitcnt vmcnt(8)
	s_waitcnt lgkmcnt(0)
	s_barrier
	s_setprio 1
	s_waitcnt lgkmcnt(0)
	v_mfma_f32_16x16x32_bf16 v[60:63], v[120:123], v[182:185], 0
	v_mfma_f32_16x16x32_bf16 v[56:59], v[128:131], v[182:185], 0
	v_mfma_f32_16x16x32_bf16 v[44:47], v[120:123], v[190:193], 0
	v_mfma_f32_16x16x32_bf16 v[40:43], v[128:131], v[190:193], 0
	v_mfma_f32_16x16x32_bf16 v[28:31], v[120:123], v[198:201], 0
	v_mfma_f32_16x16x32_bf16 v[24:27], v[128:131], v[198:201], 0
	v_mfma_f32_16x16x32_bf16 v[12:15], v[120:123], v[206:209], 0
	v_mfma_f32_16x16x32_bf16 v[8:11], v[128:131], v[206:209], 0
	v_mfma_f32_16x16x32_bf16 v[60:63], v[124:127], v[186:189], v[60:63]
	v_mfma_f32_16x16x32_bf16 v[56:59], v[132:135], v[186:189], v[56:59]
	v_mfma_f32_16x16x32_bf16 v[44:47], v[124:127], v[194:197], v[44:47]
	v_mfma_f32_16x16x32_bf16 v[40:43], v[132:135], v[194:197], v[40:43]
	v_mfma_f32_16x16x32_bf16 v[28:31], v[124:127], v[202:205], v[28:31]
	v_mfma_f32_16x16x32_bf16 v[24:27], v[132:135], v[202:205], v[24:27]
	v_mfma_f32_16x16x32_bf16 v[12:15], v[124:127], v[210:213], v[12:15]
	v_mfma_f32_16x16x32_bf16 v[8:11], v[132:135], v[210:213], v[8:11]
	v_mfma_f32_16x16x32_bf16 v[52:55], v[160:163], v[182:185], 0
	v_mfma_f32_16x16x32_bf16 v[48:51], v[174:177], v[182:185], 0
	v_mfma_f32_16x16x32_bf16 v[36:39], v[160:163], v[190:193], 0
	v_mfma_f32_16x16x32_bf16 v[32:35], v[174:177], v[190:193], 0
	v_mfma_f32_16x16x32_bf16 v[20:23], v[160:163], v[198:201], 0
	v_mfma_f32_16x16x32_bf16 v[16:19], v[174:177], v[198:201], 0
	v_mfma_f32_16x16x32_bf16 v[4:7], v[160:163], v[206:209], 0
	v_mfma_f32_16x16x32_bf16 v[0:3], v[174:177], v[206:209], 0
	v_mfma_f32_16x16x32_bf16 v[52:55], v[170:173], v[186:189], v[52:55]
	v_mfma_f32_16x16x32_bf16 v[48:51], v[178:181], v[186:189], v[48:51]
	v_mfma_f32_16x16x32_bf16 v[36:39], v[170:173], v[194:197], v[36:39]
	v_mfma_f32_16x16x32_bf16 v[32:35], v[178:181], v[194:197], v[32:35]
	v_mfma_f32_16x16x32_bf16 v[20:23], v[170:173], v[202:205], v[20:23]
	v_mfma_f32_16x16x32_bf16 v[16:19], v[178:181], v[202:205], v[16:19]
	v_mfma_f32_16x16x32_bf16 v[4:7], v[170:173], v[210:213], v[4:7]
	v_mfma_f32_16x16x32_bf16 v[0:3], v[178:181], v[210:213], v[0:3]
	s_setprio 0
	s_barrier
; #define PG8_STAGE(bufoff, gbase, voff) do { _Pragma("unroll") for (int _i = 0; _i < 2; ++_i) \
;         __builtin_amdgcn_global_load_lds((const unsigned*)((const char*)(gbase) + (voff)[_i]), (LAS unsigned*)(lds + (bufoff) + ldsw + _i * 8192), 16, 0, 0); } while (0)
; #define PG8_LDA(dst, b, h) do { _Pragma("unroll") for (int m = 0; m < 4; ++m) _Pragma("unroll") for (int k = 0; k < 2; ++k) dst[m][k] = *(const LAS bf16x8*)(lds + PG8_SA(b, h) + aoff + m * 2048 + k * 1024); } while (0)
; #define PG8_LDB(dst, b, h) do { _Pragma("unroll") for (int n = 0; n < 2; ++n) _Pragma("unroll") for (int k = 0; k < 2; ++k) dst[n][k] = *(const LAS bf16x8*)(lds + PG8_SB(b, h) + boff + n * 2048 + k * 1024); } while (0)
; #define PG8_MMA(ai, bj, At, Bt) do { __builtin_amdgcn_s_setprio(1); _Pragma("unroll") for (int m = 0; m < 4; ++m) _Pragma("unroll") for (int n = 0; n < 2; ++n) _Pragma("unroll") for (int k = 0; k < 2; ++k) \
;         acc[ai][bj][m][n] = __builtin_amdgcn_mfma_f32_16x16x32_bf16(Bt[n][k], At[m][k], acc[ai][bj][m][n], 0, 0, 0); __builtin_amdgcn_s_setprio(0); } while (0)
; #define PG8_WAIT_V(n) asm volatile("s_waitcnt vmcnt(" #n ")" ::: "memory")
; #define PG8_WAIT_L(n) asm volatile("s_waitcnt lgkmcnt(" #n ")" ::: "memory")
; #define PG8_BAR __builtin_amdgcn_s_barrier()
; #define PG8_SCHED __builtin_amdgcn_sched_barrier(0)
; template <class Epi, bool ALIGN_EPI, int K, int LDA, int LDB>
; __device__ __forceinline__ void gemm_phase(LAS unsigned char* lds, const int wid, const Gemm g, const StaticOrder& S, const Epi& E) {
;     ...
;             PG8_LDB(B0, 1, 0); PG8_LDB(B1, 1, 1); PG8_SCHED; PG8_LDA(At, 1, 0); PG8_STAGE(PG8_SA(0, 1), a2 + hA, voffA);
;             PG8_WAIT_V(8); PG8_WAIT_L(0); PG8_BAR; PG8_MMA(0, 0, At, B0); PG8_MMA(0, 1, At, B1); PG8_BAR; PG8_SCHED;
;             PG8_LDA(At, 1, 1); PG8_STAGE(PG8_SB(1, 0), b3, voffB); PG8_STAGE(PG8_SB(1, 1), b3 + hB, voffB); PG8_STAGE(PG8_SA(1, 0), a3, voffA);
;             PG8_WAIT_V(8); PG8_WAIT_L(0); PG8_BAR; PG8_MMA(1, 0, At, B0); PG8_MMA(1, 1, At, B1); PG8_BAR; PG8_SCHED;
	s_add_i32 s52, 0, 0x18000
	s_add_i32 s53, 0, 0x1c000
	v_add_u32_e32 v132, s52, v166
	v_add_u32_e32 v178, s53, v166
	ds_read_b128 v[120:123], v132
	ds_read_b128 v[124:127], v132 offset:1024
	ds_read_b128 v[128:131], v132 offset:2048
	ds_read_b128 v[132:135], v132 offset:3072
	ds_read_b128 v[160:163], v178
	ds_read_b128 v[170:173], v178 offset:1024
	ds_read_b128 v[174:177], v178 offset:2048
	ds_read_b128 v[178:181], v178 offset:3072
	s_add_u32 s26, s34, 0xb0000
	s_addc_u32 s27, s35, 0
	s_mov_b32 m0, s38
	ds_read_b128 v[182:185], v169 offset:32768
	ds_read_b128 v[186:189], v169 offset:33792
	ds_read_b128 v[190:193], v169 offset:34816
	ds_read_b128 v[194:197], v169 offset:35840
	ds_read_b128 v[198:201], v169 offset:36864
	ds_read_b128 v[202:205], v169 offset:37888
	ds_read_b128 v[206:209], v169 offset:38912
	ds_read_b128 v[210:213], v169 offset:39936
	global_load_lds_dwordx4 v144, s[26:27]
	s_mov_b32 m0, s39
	s_nop 0
	global_load_lds_dwordx4 v148, s[26:27]
	s_waitcnt vmcnt(8)
	s_waitcnt lgkmcnt(0)
	s_barrier
	s_setprio 1
	s_waitcnt lgkmcnt(0)
	v_mfma_f32_16x16x32_bf16 v[140:143], v[120:123], v[182:185], v[140:143]
	v_mfma_f32_16x16x32_bf16 v[136:139], v[128:131], v[182:185], v[136:139]
	v_mfma_f32_16x16x32_bf16 v[108:111], v[120:123], v[190:193], v[108:111]
	v_mfma_f32_16x16x32_bf16 v[104:107], v[128:131], v[190:193], v[104:107]
	v_mfma_f32_16x16x32_bf16 v[92:95], v[120:123], v[198:201], v[92:95]
	v_mfma_f32_16x16x32_bf16 v[88:91], v[128:131], v[198:201], v[88:91]
	v_mfma_f32_16x16x32_bf16 v[76:79], v[120:123], v[206:209], v[76:79]
	v_mfma_f32_16x16x32_bf16 v[72:75], v[128:131], v[206:209], v[72:75]
	v_mfma_f32_16x16x32_bf16 v[140:143], v[124:127], v[186:189], v[140:143]
	v_mfma_f32_16x16x32_bf16 v[136:139], v[132:135], v[186:189], v[136:139]
	v_mfma_f32_16x16x32_bf16 v[108:111], v[124:127], v[194:197], v[108:111]
	v_mfma_f32_16x16x32_bf16 v[104:107], v[132:135], v[194:197], v[104:107]
	v_mfma_f32_16x16x32_bf16 v[92:95], v[124:127], v[202:205], v[92:95]
	v_mfma_f32_16x16x32_bf16 v[88:91], v[132:135], v[202:205], v[88:91]
	v_mfma_f32_16x16x32_bf16 v[76:79], v[124:127], v[210:213], v[76:79]
	v_mfma_f32_16x16x32_bf16 v[72:75], v[132:135], v[210:213], v[72:75]
	v_mfma_f32_16x16x32_bf16 v[116:119], v[160:163], v[182:185], v[116:119]
	v_mfma_f32_16x16x32_bf16 v[112:115], v[174:177], v[182:185], v[112:115]
	v_mfma_f32_16x16x32_bf16 v[100:103], v[160:163], v[190:193], v[100:103]
	v_mfma_f32_16x16x32_bf16 v[96:99], v[174:177], v[190:193], v[96:99]
	v_mfma_f32_16x16x32_bf16 v[84:87], v[160:163], v[198:201], v[84:87]
	v_mfma_f32_16x16x32_bf16 v[80:83], v[174:177], v[198:201], v[80:83]
	v_mfma_f32_16x16x32_bf16 v[68:71], v[160:163], v[206:209], v[68:71]
	v_mfma_f32_16x16x32_bf16 v[64:67], v[174:177], v[206:209], v[64:67]
	v_mfma_f32_16x16x32_bf16 v[116:119], v[170:173], v[186:189], v[116:119]
	v_mfma_f32_16x16x32_bf16 v[112:115], v[178:181], v[186:189], v[112:115]
	v_mfma_f32_16x16x32_bf16 v[100:103], v[170:173], v[194:197], v[100:103]
	v_mfma_f32_16x16x32_bf16 v[96:99], v[178:181], v[194:197], v[96:99]
	v_mfma_f32_16x16x32_bf16 v[84:87], v[170:173], v[202:205], v[84:87]
	v_mfma_f32_16x16x32_bf16 v[80:83], v[178:181], v[202:205], v[80:83]
	v_mfma_f32_16x16x32_bf16 v[68:71], v[170:173], v[210:213], v[68:71]
	v_mfma_f32_16x16x32_bf16 v[64:67], v[178:181], v[210:213], v[64:67]
	s_setprio 0
	s_barrier
	s_add_i32 s26, s52, s33
	s_mov_b32 m0, s26
	ds_read_b128 v[182:185], v169 offset:49152
	ds_read_b128 v[186:189], v169 offset:50176
	ds_read_b128 v[190:193], v169 offset:51200
	ds_read_b128 v[194:197], v169 offset:52224
	ds_read_b128 v[198:201], v169 offset:53248
	ds_read_b128 v[202:205], v169 offset:54272
	ds_read_b128 v[206:209], v169 offset:55296
	ds_read_b128 v[210:213], v169 offset:56320
	global_load_lds_dwordx4 v146, s[98:99]
	s_add_i32 m0, s26, 0x2000
	s_add_u32 s26, s30, 0xb0080
	s_addc_u32 s27, s31, 0
	s_add_i32 s30, s53, s33
	global_load_lds_dwordx4 v150, s[98:99]
	s_mov_b32 m0, s30
	s_nop 0
	global_load_lds_dwordx4 v146, s[26:27]
	s_add_i32 m0, s30, 0x2000
	s_nop 0
	global_load_lds_dwordx4 v150, s[26:27]
	s_mov_b32 m0, s48
	s_nop 0
	global_load_lds_dwordx4 v144, s[100:101]
	s_mov_b32 m0, s49
	s_nop 0
	global_load_lds_dwordx4 v148, s[100:101]
	s_waitcnt vmcnt(8)
	s_waitcnt lgkmcnt(0)
	s_barrier
	s_setprio 1
	s_waitcnt lgkmcnt(0)
	v_mfma_f32_16x16x32_bf16 v[60:63], v[120:123], v[182:185], v[60:63]
	v_mfma_f32_16x16x32_bf16 v[56:59], v[128:131], v[182:185], v[56:59]
	v_mfma_f32_16x16x32_bf16 v[44:47], v[120:123], v[190:193], v[44:47]
	v_mfma_f32_16x16x32_bf16 v[40:43], v[128:131], v[190:193], v[40:43]
	v_mfma_f32_16x16x32_bf16 v[28:31], v[120:123], v[198:201], v[28:31]
	v_mfma_f32_16x16x32_bf16 v[24:27], v[128:131], v[198:201], v[24:27]
	v_mfma_f32_16x16x32_bf16 v[12:15], v[120:123], v[206:209], v[12:15]
	v_mfma_f32_16x16x32_bf16 v[8:11], v[128:131], v[206:209], v[8:11]
	v_mfma_f32_16x16x32_bf16 v[60:63], v[124:127], v[186:189], v[60:63]
	v_mfma_f32_16x16x32_bf16 v[56:59], v[132:135], v[186:189], v[56:59]
	v_mfma_f32_16x16x32_bf16 v[44:47], v[124:127], v[194:197], v[44:47]
	v_mfma_f32_16x16x32_bf16 v[40:43], v[132:135], v[194:197], v[40:43]
	v_mfma_f32_16x16x32_bf16 v[28:31], v[124:127], v[202:205], v[28:31]
	v_mfma_f32_16x16x32_bf16 v[24:27], v[132:135], v[202:205], v[24:27]
	v_mfma_f32_16x16x32_bf16 v[12:15], v[124:127], v[210:213], v[12:15]
	v_mfma_f32_16x16x32_bf16 v[8:11], v[132:135], v[210:213], v[8:11]
	v_mfma_f32_16x16x32_bf16 v[52:55], v[160:163], v[182:185], v[52:55]
	v_mfma_f32_16x16x32_bf16 v[48:51], v[174:177], v[182:185], v[48:51]
	v_mfma_f32_16x16x32_bf16 v[36:39], v[160:163], v[190:193], v[36:39]
	v_mfma_f32_16x16x32_bf16 v[32:35], v[174:177], v[190:193], v[32:35]
	v_mfma_f32_16x16x32_bf16 v[20:23], v[160:163], v[198:201], v[20:23]
	v_mfma_f32_16x16x32_bf16 v[16:19], v[174:177], v[198:201], v[16:19]
	v_mfma_f32_16x16x32_bf16 v[4:7], v[160:163], v[206:209], v[4:7]
	v_mfma_f32_16x16x32_bf16 v[0:3], v[174:177], v[206:209], v[0:3]
	v_mfma_f32_16x16x32_bf16 v[52:55], v[170:173], v[186:189], v[52:55]
	v_mfma_f32_16x16x32_bf16 v[48:51], v[178:181], v[186:189], v[48:51]
	v_mfma_f32_16x16x32_bf16 v[36:39], v[170:173], v[194:197], v[36:39]
	v_mfma_f32_16x16x32_bf16 v[32:35], v[178:181], v[194:197], v[32:35]
	v_mfma_f32_16x16x32_bf16 v[20:23], v[170:173], v[202:205], v[20:23]
	v_mfma_f32_16x16x32_bf16 v[16:19], v[178:181], v[202:205], v[16:19]
	v_mfma_f32_16x16x32_bf16 v[4:7], v[170:173], v[210:213], v[4:7]
	v_mfma_f32_16x16x32_bf16 v[0:3], v[178:181], v[210:213], v[0:3]
	s_setprio 0
	s_barrier
	s_add_i32 s63, s63, 2
	s_add_u32 s61, s61, 0x100
	s_addc_u32 s62, s62, 0
	s_mov_b64 s[26:27], s[28:29]
